# plus: removed mid-segment s_setprio 0/1 pair and the redundant post-barrier lgkmcnt(0) in every MMA segment
# speedup vs baseline: 1.0052x; 1.0052x over previous
.LBB0_120:
	ds_read_b128 v[128:131], v178
	ds_read_b128 v[132:135], v178 offset:1024
	ds_read_b128 v[154:157], v178 offset:2048
	ds_read_b128 v[158:161], v178 offset:3072
	ds_read_b128 v[162:165], v179
	ds_read_b128 v[166:169], v179 offset:1024
	ds_read_b128 v[182:185], v179 offset:2048
	ds_read_b128 v[186:189], v179 offset:3072
	s_add_u32 s67, s88, 0xfffc0080
	s_addc_u32 s68, s89, -1
	s_cmp_eq_u32 s66, 12
	s_cselect_b32 s93, s52, s68
	s_cselect_b32 s92, s53, s67
	s_cselect_b32 s91, s56, s59
	s_cselect_b32 s90, s57, s58
	v_lshl_add_u64 v[170:171], s[88:89], 0, v[144:145]
	s_add_i32 m0, s17, 0xc000
	ds_read_b128 v[190:193], v180
	ds_read_b128 v[194:197], v180 offset:1024
	ds_read_b128 v[198:201], v180 offset:2048
	ds_read_b128 v[202:205], v180 offset:3072
	ds_read_b128 v[206:209], v180 offset:4096
	ds_read_b128 v[210:213], v180 offset:5120
	ds_read_b128 v[214:217], v180 offset:6144
	ds_read_b128 v[218:221], v180 offset:7168
	global_load_lds_dwordx4 v[170:171], off
	v_lshl_add_u64 v[170:171], s[88:89], 0, v[148:149]
	s_add_i32 m0, s17, 0xe000
	s_nop 0
	global_load_lds_dwordx4 v[170:171], off
	s_waitcnt vmcnt(8)
	s_waitcnt lgkmcnt(0)
	s_barrier
	s_setprio 1
	v_mfma_f32_16x16x32_bf16 v[124:127], v[128:131], v[190:193], v[124:127]
	v_mfma_f32_16x16x32_bf16 v[116:119], v[154:157], v[190:193], v[116:119]
	v_mfma_f32_16x16x32_bf16 v[108:111], v[128:131], v[198:201], v[108:111]
	v_mfma_f32_16x16x32_bf16 v[100:103], v[154:157], v[198:201], v[100:103]
	v_mfma_f32_16x16x32_bf16 v[92:95], v[128:131], v[206:209], v[92:95]
	v_mfma_f32_16x16x32_bf16 v[84:87], v[154:157], v[206:209], v[84:87]
	v_mfma_f32_16x16x32_bf16 v[76:79], v[128:131], v[214:217], v[76:79]
	v_mfma_f32_16x16x32_bf16 v[68:71], v[154:157], v[214:217], v[68:71]
	v_mfma_f32_16x16x32_bf16 v[124:127], v[132:135], v[194:197], v[124:127]
	v_mfma_f32_16x16x32_bf16 v[116:119], v[158:161], v[194:197], v[116:119]
	v_mfma_f32_16x16x32_bf16 v[108:111], v[132:135], v[202:205], v[108:111]
	v_mfma_f32_16x16x32_bf16 v[100:103], v[158:161], v[202:205], v[100:103]
	v_mfma_f32_16x16x32_bf16 v[92:95], v[132:135], v[210:213], v[92:95]
	v_mfma_f32_16x16x32_bf16 v[84:87], v[158:161], v[210:213], v[84:87]
	v_mfma_f32_16x16x32_bf16 v[76:79], v[132:135], v[218:221], v[76:79]
	v_mfma_f32_16x16x32_bf16 v[68:71], v[158:161], v[218:221], v[68:71]
	v_mfma_f32_16x16x32_bf16 v[120:123], v[162:165], v[190:193], v[120:123]
	v_mfma_f32_16x16x32_bf16 v[112:115], v[182:185], v[190:193], v[112:115]
	v_mfma_f32_16x16x32_bf16 v[104:107], v[162:165], v[198:201], v[104:107]
	v_mfma_f32_16x16x32_bf16 v[96:99], v[182:185], v[198:201], v[96:99]
	v_mfma_f32_16x16x32_bf16 v[88:91], v[162:165], v[206:209], v[88:91]
	v_mfma_f32_16x16x32_bf16 v[80:83], v[182:185], v[206:209], v[80:83]
	v_mfma_f32_16x16x32_bf16 v[72:75], v[162:165], v[214:217], v[72:75]
	v_mfma_f32_16x16x32_bf16 v[64:67], v[182:185], v[214:217], v[64:67]
	v_mfma_f32_16x16x32_bf16 v[120:123], v[166:169], v[194:197], v[120:123]
	v_mfma_f32_16x16x32_bf16 v[112:115], v[186:189], v[194:197], v[112:115]
	v_mfma_f32_16x16x32_bf16 v[104:107], v[166:169], v[202:205], v[104:107]
	v_mfma_f32_16x16x32_bf16 v[96:99], v[186:189], v[202:205], v[96:99]
	s_setprio 3
	s_barrier
	v_mfma_f32_16x16x32_bf16 v[88:91], v[166:169], v[210:213], v[88:91]
	v_mfma_f32_16x16x32_bf16 v[80:83], v[186:189], v[210:213], v[80:83]
	v_mfma_f32_16x16x32_bf16 v[72:75], v[166:169], v[218:221], v[72:75]
	v_mfma_f32_16x16x32_bf16 v[64:67], v[186:189], v[218:221], v[64:67]
	s_setprio 0
	s_add_i32 s67, s25, s16
	v_lshl_add_u64 v[170:171], s[90:91], 0, v[140:141]
	s_mov_b32 m0, s67
	ds_read_b128 v[190:193], v180 offset:16384
	ds_read_b128 v[194:197], v180 offset:17408
	ds_read_b128 v[198:201], v180 offset:18432
	ds_read_b128 v[202:205], v180 offset:19456
	ds_read_b128 v[206:209], v180 offset:20480
	ds_read_b128 v[210:213], v180 offset:21504
	ds_read_b128 v[214:217], v180 offset:22528
	ds_read_b128 v[218:221], v180 offset:23552
	global_load_lds_dwordx4 v[170:171], off
	s_add_i32 m0, s67, 0x2000
	s_add_u32 s68, s90, 0x40000
	v_lshl_add_u64 v[222:223], s[90:91], 0, v[136:137]
	s_addc_u32 s69, s91, 0
	s_add_i32 s67, s26, s16
	global_load_lds_dwordx4 v[222:223], off
	v_lshl_add_u64 v[224:225], s[68:69], 0, v[140:141]
	s_mov_b32 m0, s67
	v_lshl_add_u64 v[226:227], s[92:93], 0, v[138:139]
	global_load_lds_dwordx4 v[224:225], off
	v_lshl_add_u64 v[224:225], s[68:69], 0, v[136:137]
	s_add_i32 m0, s67, 0x2000
	s_nop 0
	global_load_lds_dwordx4 v[224:225], off
	v_lshl_add_u64 v[224:225], s[92:93], 0, v[142:143]
	s_mov_b32 m0, s17
	s_nop 0
	global_load_lds_dwordx4 v[224:225], off
	s_mov_b32 m0, s18
	s_nop 0
	global_load_lds_dwordx4 v[226:227], off
	s_waitcnt vmcnt(8)
	s_waitcnt lgkmcnt(0)
	s_barrier
	s_setprio 1
	v_mfma_f32_16x16x32_bf16 v[60:63], v[128:131], v[190:193], v[60:63]
	v_mfma_f32_16x16x32_bf16 v[52:55], v[154:157], v[190:193], v[52:55]
	v_mfma_f32_16x16x32_bf16 v[44:47], v[128:131], v[198:201], v[44:47]
	v_mfma_f32_16x16x32_bf16 v[36:39], v[154:157], v[198:201], v[36:39]
	v_mfma_f32_16x16x32_bf16 v[28:31], v[128:131], v[206:209], v[28:31]
	v_mfma_f32_16x16x32_bf16 v[20:23], v[154:157], v[206:209], v[20:23]
	v_mfma_f32_16x16x32_bf16 v[12:15], v[128:131], v[214:217], v[12:15]
	v_mfma_f32_16x16x32_bf16 v[4:7], v[154:157], v[214:217], v[4:7]
	v_mfma_f32_16x16x32_bf16 v[60:63], v[132:135], v[194:197], v[60:63]
	v_mfma_f32_16x16x32_bf16 v[52:55], v[158:161], v[194:197], v[52:55]
	v_mfma_f32_16x16x32_bf16 v[44:47], v[132:135], v[202:205], v[44:47]
	v_mfma_f32_16x16x32_bf16 v[36:39], v[158:161], v[202:205], v[36:39]
	v_mfma_f32_16x16x32_bf16 v[28:31], v[132:135], v[210:213], v[28:31]
	v_mfma_f32_16x16x32_bf16 v[20:23], v[158:161], v[210:213], v[20:23]
	v_mfma_f32_16x16x32_bf16 v[12:15], v[132:135], v[218:221], v[12:15]
	v_mfma_f32_16x16x32_bf16 v[4:7], v[158:161], v[218:221], v[4:7]
	v_mfma_f32_16x16x32_bf16 v[56:59], v[162:165], v[190:193], v[56:59]
	v_mfma_f32_16x16x32_bf16 v[48:51], v[182:185], v[190:193], v[48:51]
	v_mfma_f32_16x16x32_bf16 v[40:43], v[162:165], v[198:201], v[40:43]
	v_mfma_f32_16x16x32_bf16 v[32:35], v[182:185], v[198:201], v[32:35]
	v_mfma_f32_16x16x32_bf16 v[24:27], v[162:165], v[206:209], v[24:27]
	v_mfma_f32_16x16x32_bf16 v[16:19], v[182:185], v[206:209], v[16:19]
	v_mfma_f32_16x16x32_bf16 v[8:11], v[162:165], v[214:217], v[8:11]
	v_mfma_f32_16x16x32_bf16 v[0:3], v[182:185], v[214:217], v[0:3]
	v_mfma_f32_16x16x32_bf16 v[56:59], v[166:169], v[194:197], v[56:59]
	v_mfma_f32_16x16x32_bf16 v[48:51], v[186:189], v[194:197], v[48:51]
	v_mfma_f32_16x16x32_bf16 v[40:43], v[166:169], v[202:205], v[40:43]
	v_mfma_f32_16x16x32_bf16 v[32:35], v[186:189], v[202:205], v[32:35]
	s_setprio 3
	s_barrier
	v_mfma_f32_16x16x32_bf16 v[24:27], v[166:169], v[210:213], v[24:27]
	v_mfma_f32_16x16x32_bf16 v[16:19], v[186:189], v[210:213], v[16:19]
	v_mfma_f32_16x16x32_bf16 v[8:11], v[166:169], v[218:221], v[8:11]
	v_mfma_f32_16x16x32_bf16 v[0:3], v[186:189], v[218:221], v[0:3]
	s_setprio 0
	s_add_i32 s67, 0, 0x18000
	s_add_i32 s73, 0, 0x1c000
	v_add_u32_e32 v158, s67, v175
	v_add_u32_e32 v186, s73, v175
	ds_read_b128 v[128:131], v158
	ds_read_b128 v[132:135], v158 offset:1024
	ds_read_b128 v[154:157], v158 offset:2048
	ds_read_b128 v[158:161], v158 offset:3072
	ds_read_b128 v[162:165], v186
	ds_read_b128 v[166:169], v186 offset:1024
	ds_read_b128 v[182:185], v186 offset:2048
	ds_read_b128 v[186:189], v186 offset:3072
	s_add_u32 s68, s92, 0x40000
	s_addc_u32 s69, s93, 0
	s_mov_b32 m0, s19
	v_lshl_add_u64 v[228:229], s[68:69], 0, v[142:143]
	ds_read_b128 v[190:193], v180 offset:32768
	ds_read_b128 v[194:197], v180 offset:33792
	ds_read_b128 v[198:201], v180 offset:34816
	ds_read_b128 v[202:205], v180 offset:35840
	ds_read_b128 v[206:209], v180 offset:36864
	ds_read_b128 v[210:213], v180 offset:37888
	ds_read_b128 v[214:217], v180 offset:38912
	ds_read_b128 v[218:221], v180 offset:39936
	global_load_lds_dwordx4 v[228:229], off
	v_lshl_add_u64 v[228:229], s[68:69], 0, v[138:139]
	s_mov_b32 m0, s20
	s_nop 0
	global_load_lds_dwordx4 v[228:229], off
	s_waitcnt vmcnt(8)
	s_waitcnt lgkmcnt(0)
	s_barrier
	s_setprio 1
	v_mfma_f32_16x16x32_bf16 v[124:127], v[128:131], v[190:193], v[124:127]
	v_mfma_f32_16x16x32_bf16 v[116:119], v[154:157], v[190:193], v[116:119]
	v_mfma_f32_16x16x32_bf16 v[108:111], v[128:131], v[198:201], v[108:111]
	v_mfma_f32_16x16x32_bf16 v[100:103], v[154:157], v[198:201], v[100:103]
	v_mfma_f32_16x16x32_bf16 v[92:95], v[128:131], v[206:209], v[92:95]
	v_mfma_f32_16x16x32_bf16 v[84:87], v[154:157], v[206:209], v[84:87]
	v_mfma_f32_16x16x32_bf16 v[76:79], v[128:131], v[214:217], v[76:79]
	v_mfma_f32_16x16x32_bf16 v[68:71], v[154:157], v[214:217], v[68:71]
	v_mfma_f32_16x16x32_bf16 v[124:127], v[132:135], v[194:197], v[124:127]
	v_mfma_f32_16x16x32_bf16 v[116:119], v[158:161], v[194:197], v[116:119]
	v_mfma_f32_16x16x32_bf16 v[108:111], v[132:135], v[202:205], v[108:111]
	v_mfma_f32_16x16x32_bf16 v[100:103], v[158:161], v[202:205], v[100:103]
	v_mfma_f32_16x16x32_bf16 v[92:95], v[132:135], v[210:213], v[92:95]
	v_mfma_f32_16x16x32_bf16 v[84:87], v[158:161], v[210:213], v[84:87]
	v_mfma_f32_16x16x32_bf16 v[76:79], v[132:135], v[218:221], v[76:79]
	v_mfma_f32_16x16x32_bf16 v[68:71], v[158:161], v[218:221], v[68:71]
	v_mfma_f32_16x16x32_bf16 v[120:123], v[162:165], v[190:193], v[120:123]
	v_mfma_f32_16x16x32_bf16 v[112:115], v[182:185], v[190:193], v[112:115]
	v_mfma_f32_16x16x32_bf16 v[104:107], v[162:165], v[198:201], v[104:107]
	v_mfma_f32_16x16x32_bf16 v[96:99], v[182:185], v[198:201], v[96:99]
	v_mfma_f32_16x16x32_bf16 v[88:91], v[162:165], v[206:209], v[88:91]
	v_mfma_f32_16x16x32_bf16 v[80:83], v[182:185], v[206:209], v[80:83]
	v_mfma_f32_16x16x32_bf16 v[72:75], v[162:165], v[214:217], v[72:75]
	v_mfma_f32_16x16x32_bf16 v[64:67], v[182:185], v[214:217], v[64:67]
	v_mfma_f32_16x16x32_bf16 v[120:123], v[166:169], v[194:197], v[120:123]
	v_mfma_f32_16x16x32_bf16 v[112:115], v[186:189], v[194:197], v[112:115]
	v_mfma_f32_16x16x32_bf16 v[104:107], v[166:169], v[202:205], v[104:107]
	v_mfma_f32_16x16x32_bf16 v[96:99], v[186:189], v[202:205], v[96:99]
	s_setprio 3
	s_barrier
	v_mfma_f32_16x16x32_bf16 v[88:91], v[166:169], v[210:213], v[88:91]
	v_mfma_f32_16x16x32_bf16 v[80:83], v[186:189], v[210:213], v[80:83]
	v_mfma_f32_16x16x32_bf16 v[72:75], v[166:169], v[218:221], v[72:75]
	v_mfma_f32_16x16x32_bf16 v[64:67], v[186:189], v[218:221], v[64:67]
	s_setprio 0
	s_add_i32 s67, s67, s16
	v_lshl_add_u64 v[170:171], v[170:171], 0, s[74:75]
	s_mov_b32 m0, s67
	ds_read_b128 v[190:193], v180 offset:49152
	ds_read_b128 v[194:197], v180 offset:50176
	ds_read_b128 v[198:201], v180 offset:51200
	ds_read_b128 v[202:205], v180 offset:52224
	ds_read_b128 v[206:209], v180 offset:53248
	ds_read_b128 v[210:213], v180 offset:54272
	ds_read_b128 v[214:217], v180 offset:55296
	ds_read_b128 v[218:221], v180 offset:56320
	global_load_lds_dwordx4 v[170:171], off
	s_add_i32 m0, s67, 0x2000
	s_add_u32 s68, s90, 0x40080
	v_lshl_add_u64 v[170:171], v[222:223], 0, s[74:75]
	s_addc_u32 s69, s91, 0
	s_add_i32 s67, s73, s16
	global_load_lds_dwordx4 v[170:171], off
	v_lshl_add_u64 v[170:171], s[68:69], 0, v[140:141]
	s_mov_b32 m0, s67
	s_nop 0
	global_load_lds_dwordx4 v[170:171], off
	v_lshl_add_u64 v[170:171], s[68:69], 0, v[136:137]
	s_add_i32 m0, s67, 0x2000
	s_nop 0
	global_load_lds_dwordx4 v[170:171], off
	v_lshl_add_u64 v[170:171], v[224:225], 0, s[74:75]
	s_mov_b32 m0, s23
	s_nop 0
	global_load_lds_dwordx4 v[170:171], off
	v_lshl_add_u64 v[170:171], v[226:227], 0, s[74:75]
	s_mov_b32 m0, s24
	s_nop 0
	global_load_lds_dwordx4 v[170:171], off
	s_waitcnt vmcnt(8)
	s_waitcnt lgkmcnt(0)
	s_barrier
	s_setprio 1
	v_mfma_f32_16x16x32_bf16 v[60:63], v[128:131], v[190:193], v[60:63]
	v_mfma_f32_16x16x32_bf16 v[52:55], v[154:157], v[190:193], v[52:55]
	v_mfma_f32_16x16x32_bf16 v[44:47], v[128:131], v[198:201], v[44:47]
	v_mfma_f32_16x16x32_bf16 v[36:39], v[154:157], v[198:201], v[36:39]
	v_mfma_f32_16x16x32_bf16 v[28:31], v[128:131], v[206:209], v[28:31]
	v_mfma_f32_16x16x32_bf16 v[20:23], v[154:157], v[206:209], v[20:23]
	v_mfma_f32_16x16x32_bf16 v[12:15], v[128:131], v[214:217], v[12:15]
	v_mfma_f32_16x16x32_bf16 v[4:7], v[154:157], v[214:217], v[4:7]
	v_mfma_f32_16x16x32_bf16 v[60:63], v[132:135], v[194:197], v[60:63]
	v_mfma_f32_16x16x32_bf16 v[52:55], v[158:161], v[194:197], v[52:55]
	v_mfma_f32_16x16x32_bf16 v[44:47], v[132:135], v[202:205], v[44:47]
	v_mfma_f32_16x16x32_bf16 v[36:39], v[158:161], v[202:205], v[36:39]
	v_mfma_f32_16x16x32_bf16 v[28:31], v[132:135], v[210:213], v[28:31]
	v_mfma_f32_16x16x32_bf16 v[20:23], v[158:161], v[210:213], v[20:23]
	v_mfma_f32_16x16x32_bf16 v[12:15], v[132:135], v[218:221], v[12:15]
	v_mfma_f32_16x16x32_bf16 v[4:7], v[158:161], v[218:221], v[4:7]
	v_mfma_f32_16x16x32_bf16 v[56:59], v[162:165], v[190:193], v[56:59]
	v_mfma_f32_16x16x32_bf16 v[48:51], v[182:185], v[190:193], v[48:51]
	v_mfma_f32_16x16x32_bf16 v[40:43], v[162:165], v[198:201], v[40:43]
	v_mfma_f32_16x16x32_bf16 v[32:35], v[182:185], v[198:201], v[32:35]
	v_mfma_f32_16x16x32_bf16 v[24:27], v[162:165], v[206:209], v[24:27]
	v_mfma_f32_16x16x32_bf16 v[16:19], v[182:185], v[206:209], v[16:19]
	v_mfma_f32_16x16x32_bf16 v[8:11], v[162:165], v[214:217], v[8:11]
	v_mfma_f32_16x16x32_bf16 v[0:3], v[182:185], v[214:217], v[0:3]
	v_mfma_f32_16x16x32_bf16 v[56:59], v[166:169], v[194:197], v[56:59]
	v_mfma_f32_16x16x32_bf16 v[48:51], v[186:189], v[194:197], v[48:51]
	v_mfma_f32_16x16x32_bf16 v[40:43], v[166:169], v[202:205], v[40:43]
	v_mfma_f32_16x16x32_bf16 v[32:35], v[186:189], v[202:205], v[32:35]
	s_setprio 3
	s_barrier
	v_mfma_f32_16x16x32_bf16 v[24:27], v[166:169], v[210:213], v[24:27]
	v_mfma_f32_16x16x32_bf16 v[16:19], v[186:189], v[210:213], v[16:19]
	v_mfma_f32_16x16x32_bf16 v[8:11], v[166:169], v[218:221], v[8:11]
	v_mfma_f32_16x16x32_bf16 v[0:3], v[186:189], v[218:221], v[0:3]
	s_setprio 0
	s_add_i32 s66, s66, 2
	s_add_u32 s88, s88, 0x100
	s_addc_u32 s89, s89, 0
	s_add_u32 s58, s58, 0x100
	s_addc_u32 s59, s59, 0
	s_cmp_gt_u32 s66, 13
	s_cbranch_scc0 .LBB0_120
	s_and_b64 vcc, exec, s[76:77]
	s_cbranch_vccz .LBB0_123
	s_barrier

.LBB0_272:
	ds_read_b128 v[120:123], v245
	ds_read_b128 v[124:127], v245 offset:1024
	ds_read_b128 v[128:131], v245 offset:2048
	ds_read_b128 v[132:135], v245 offset:3072
	ds_read_b128 v[144:147], v246
	ds_read_b128 v[148:151], v246 offset:1024
	ds_read_b128 v[152:155], v246 offset:2048
	ds_read_b128 v[156:159], v246 offset:3072
	s_add_u32 s59, s86, 0xfff50080
	s_addc_u32 s66, s87, -1
	s_cmp_eq_u32 s58, 40
	s_cselect_b32 s91, s11, s66
	s_cselect_b32 s90, s10, s59
	s_cselect_b32 s89, s85, s57
	s_cselect_b32 s88, s84, s56
	v_lshl_add_u64 v[204:205], s[86:87], 0, v[200:201]
	s_add_i32 m0, s16, 0xc000
	ds_read_b128 v[160:163], v247
	ds_read_b128 v[164:167], v247 offset:1024
	ds_read_b128 v[168:171], v247 offset:2048
	ds_read_b128 v[172:175], v247 offset:3072
	ds_read_b128 v[176:179], v247 offset:4096
	ds_read_b128 v[180:183], v247 offset:5120
	ds_read_b128 v[184:187], v247 offset:6144
	ds_read_b128 v[188:191], v247 offset:7168
	global_load_lds_dwordx4 v[204:205], off
	v_lshl_add_u64 v[204:205], s[86:87], 0, v[202:203]
	s_add_i32 m0, s16, 0xe000
	s_nop 0
	global_load_lds_dwordx4 v[204:205], off
	s_waitcnt vmcnt(8)
	s_waitcnt lgkmcnt(0)
	s_barrier
	s_setprio 1
	v_mfma_f32_16x16x32_bf16 v[140:143], v[120:123], v[160:163], v[140:143]
	v_mfma_f32_16x16x32_bf16 v[136:139], v[128:131], v[160:163], v[136:139]
	v_mfma_f32_16x16x32_bf16 v[108:111], v[120:123], v[168:171], v[108:111]
	v_mfma_f32_16x16x32_bf16 v[104:107], v[128:131], v[168:171], v[104:107]
	v_mfma_f32_16x16x32_bf16 v[92:95], v[120:123], v[176:179], v[92:95]
	v_mfma_f32_16x16x32_bf16 v[88:91], v[128:131], v[176:179], v[88:91]
	v_mfma_f32_16x16x32_bf16 v[76:79], v[120:123], v[184:187], v[76:79]
	v_mfma_f32_16x16x32_bf16 v[72:75], v[128:131], v[184:187], v[72:75]
	v_mfma_f32_16x16x32_bf16 v[140:143], v[124:127], v[164:167], v[140:143]
	v_mfma_f32_16x16x32_bf16 v[136:139], v[132:135], v[164:167], v[136:139]
	v_mfma_f32_16x16x32_bf16 v[108:111], v[124:127], v[172:175], v[108:111]
	v_mfma_f32_16x16x32_bf16 v[104:107], v[132:135], v[172:175], v[104:107]
	v_mfma_f32_16x16x32_bf16 v[92:95], v[124:127], v[180:183], v[92:95]
	v_mfma_f32_16x16x32_bf16 v[88:91], v[132:135], v[180:183], v[88:91]
	v_mfma_f32_16x16x32_bf16 v[76:79], v[124:127], v[188:191], v[76:79]
	v_mfma_f32_16x16x32_bf16 v[72:75], v[132:135], v[188:191], v[72:75]
	v_mfma_f32_16x16x32_bf16 v[116:119], v[144:147], v[160:163], v[116:119]
	v_mfma_f32_16x16x32_bf16 v[112:115], v[152:155], v[160:163], v[112:115]
	v_mfma_f32_16x16x32_bf16 v[100:103], v[144:147], v[168:171], v[100:103]
	v_mfma_f32_16x16x32_bf16 v[96:99], v[152:155], v[168:171], v[96:99]
	v_mfma_f32_16x16x32_bf16 v[84:87], v[144:147], v[176:179], v[84:87]
	v_mfma_f32_16x16x32_bf16 v[80:83], v[152:155], v[176:179], v[80:83]
	v_mfma_f32_16x16x32_bf16 v[68:71], v[144:147], v[184:187], v[68:71]
	v_mfma_f32_16x16x32_bf16 v[64:67], v[152:155], v[184:187], v[64:67]
	v_mfma_f32_16x16x32_bf16 v[116:119], v[148:151], v[164:167], v[116:119]
	v_mfma_f32_16x16x32_bf16 v[112:115], v[156:159], v[164:167], v[112:115]
	v_mfma_f32_16x16x32_bf16 v[100:103], v[148:151], v[172:175], v[100:103]
	v_mfma_f32_16x16x32_bf16 v[96:99], v[156:159], v[172:175], v[96:99]
	s_setprio 3
	s_barrier
	v_mfma_f32_16x16x32_bf16 v[84:87], v[148:151], v[180:183], v[84:87]
	v_mfma_f32_16x16x32_bf16 v[80:83], v[156:159], v[180:183], v[80:83]
	v_mfma_f32_16x16x32_bf16 v[68:71], v[148:151], v[188:191], v[68:71]
	v_mfma_f32_16x16x32_bf16 v[64:67], v[156:159], v[188:191], v[64:67]
	s_setprio 0
	s_add_i32 s59, s26, s15
	v_lshl_add_u64 v[204:205], s[88:89], 0, v[194:195]
	s_mov_b32 m0, s59
	ds_read_b128 v[160:163], v247 offset:16384
	ds_read_b128 v[164:167], v247 offset:17408
	ds_read_b128 v[168:171], v247 offset:18432
	ds_read_b128 v[172:175], v247 offset:19456
	ds_read_b128 v[176:179], v247 offset:20480
	ds_read_b128 v[180:183], v247 offset:21504
	ds_read_b128 v[184:187], v247 offset:22528
	ds_read_b128 v[188:191], v247 offset:23552
	global_load_lds_dwordx4 v[204:205], off
	s_add_i32 m0, s59, 0x2000
	s_add_u32 s66, s88, 0xb0000
	v_lshl_add_u64 v[206:207], s[88:89], 0, v[198:199]
	s_addc_u32 s67, s89, 0
	s_add_i32 s59, s27, s15
	global_load_lds_dwordx4 v[206:207], off
	v_lshl_add_u64 v[208:209], s[66:67], 0, v[194:195]
	s_mov_b32 m0, s59
	v_lshl_add_u64 v[210:211], s[90:91], 0, v[196:197]
	global_load_lds_dwordx4 v[208:209], off
	v_lshl_add_u64 v[208:209], s[66:67], 0, v[198:199]
	s_add_i32 m0, s59, 0x2000
	s_nop 0
	global_load_lds_dwordx4 v[208:209], off
	v_lshl_add_u64 v[208:209], s[90:91], 0, v[192:193]
	s_mov_b32 m0, s16
	s_nop 0
	global_load_lds_dwordx4 v[208:209], off
	s_mov_b32 m0, s17
	s_nop 0
	global_load_lds_dwordx4 v[210:211], off
	s_waitcnt vmcnt(8)
	s_waitcnt lgkmcnt(0)
	s_barrier
	s_setprio 1
	v_mfma_f32_16x16x32_bf16 v[60:63], v[120:123], v[160:163], v[60:63]
	v_mfma_f32_16x16x32_bf16 v[56:59], v[128:131], v[160:163], v[56:59]
	v_mfma_f32_16x16x32_bf16 v[44:47], v[120:123], v[168:171], v[44:47]
	v_mfma_f32_16x16x32_bf16 v[40:43], v[128:131], v[168:171], v[40:43]
	v_mfma_f32_16x16x32_bf16 v[28:31], v[120:123], v[176:179], v[28:31]
	v_mfma_f32_16x16x32_bf16 v[24:27], v[128:131], v[176:179], v[24:27]
	v_mfma_f32_16x16x32_bf16 v[12:15], v[120:123], v[184:187], v[12:15]
	v_mfma_f32_16x16x32_bf16 v[8:11], v[128:131], v[184:187], v[8:11]
	v_mfma_f32_16x16x32_bf16 v[60:63], v[124:127], v[164:167], v[60:63]
	v_mfma_f32_16x16x32_bf16 v[56:59], v[132:135], v[164:167], v[56:59]
	v_mfma_f32_16x16x32_bf16 v[44:47], v[124:127], v[172:175], v[44:47]
	v_mfma_f32_16x16x32_bf16 v[40:43], v[132:135], v[172:175], v[40:43]
	v_mfma_f32_16x16x32_bf16 v[28:31], v[124:127], v[180:183], v[28:31]
	v_mfma_f32_16x16x32_bf16 v[24:27], v[132:135], v[180:183], v[24:27]
	v_mfma_f32_16x16x32_bf16 v[12:15], v[124:127], v[188:191], v[12:15]
	v_mfma_f32_16x16x32_bf16 v[8:11], v[132:135], v[188:191], v[8:11]
	v_mfma_f32_16x16x32_bf16 v[52:55], v[144:147], v[160:163], v[52:55]
	v_mfma_f32_16x16x32_bf16 v[48:51], v[152:155], v[160:163], v[48:51]
	v_mfma_f32_16x16x32_bf16 v[36:39], v[144:147], v[168:171], v[36:39]
	v_mfma_f32_16x16x32_bf16 v[32:35], v[152:155], v[168:171], v[32:35]
	v_mfma_f32_16x16x32_bf16 v[20:23], v[144:147], v[176:179], v[20:23]
	v_mfma_f32_16x16x32_bf16 v[16:19], v[152:155], v[176:179], v[16:19]
	v_mfma_f32_16x16x32_bf16 v[4:7], v[144:147], v[184:187], v[4:7]
	v_mfma_f32_16x16x32_bf16 v[0:3], v[152:155], v[184:187], v[0:3]
	v_mfma_f32_16x16x32_bf16 v[52:55], v[148:151], v[164:167], v[52:55]
	v_mfma_f32_16x16x32_bf16 v[48:51], v[156:159], v[164:167], v[48:51]
	v_mfma_f32_16x16x32_bf16 v[36:39], v[148:151], v[172:175], v[36:39]
	v_mfma_f32_16x16x32_bf16 v[32:35], v[156:159], v[172:175], v[32:35]
	s_setprio 3
	s_barrier
	v_mfma_f32_16x16x32_bf16 v[20:23], v[148:151], v[180:183], v[20:23]
	v_mfma_f32_16x16x32_bf16 v[16:19], v[156:159], v[180:183], v[16:19]
	v_mfma_f32_16x16x32_bf16 v[4:7], v[148:151], v[188:191], v[4:7]
	v_mfma_f32_16x16x32_bf16 v[0:3], v[156:159], v[188:191], v[0:3]
	s_setprio 0
	s_add_i32 s59, 0, 0x18000
	s_add_i32 s68, 0, 0x1c000
	v_add_u32_e32 v132, s59, v243
	v_add_u32_e32 v156, s68, v243
	ds_read_b128 v[120:123], v132
	ds_read_b128 v[124:127], v132 offset:1024
	ds_read_b128 v[128:131], v132 offset:2048
	ds_read_b128 v[132:135], v132 offset:3072
	ds_read_b128 v[144:147], v156
	ds_read_b128 v[148:151], v156 offset:1024
	ds_read_b128 v[152:155], v156 offset:2048
	ds_read_b128 v[156:159], v156 offset:3072
	s_add_u32 s66, s90, 0xb0000
	s_addc_u32 s67, s91, 0
	s_mov_b32 m0, s18
	v_lshl_add_u64 v[212:213], s[66:67], 0, v[192:193]
	ds_read_b128 v[160:163], v247 offset:32768
	ds_read_b128 v[164:167], v247 offset:33792
	ds_read_b128 v[168:171], v247 offset:34816
	ds_read_b128 v[172:175], v247 offset:35840
	ds_read_b128 v[176:179], v247 offset:36864
	ds_read_b128 v[180:183], v247 offset:37888
	ds_read_b128 v[184:187], v247 offset:38912
	ds_read_b128 v[188:191], v247 offset:39936
	global_load_lds_dwordx4 v[212:213], off
	v_lshl_add_u64 v[212:213], s[66:67], 0, v[196:197]
	s_mov_b32 m0, s19
	s_nop 0
	global_load_lds_dwordx4 v[212:213], off
	s_waitcnt vmcnt(8)
	s_waitcnt lgkmcnt(0)
	s_barrier
	s_setprio 1
	v_mfma_f32_16x16x32_bf16 v[140:143], v[120:123], v[160:163], v[140:143]
	v_mfma_f32_16x16x32_bf16 v[136:139], v[128:131], v[160:163], v[136:139]
	v_mfma_f32_16x16x32_bf16 v[108:111], v[120:123], v[168:171], v[108:111]
	v_mfma_f32_16x16x32_bf16 v[104:107], v[128:131], v[168:171], v[104:107]
	v_mfma_f32_16x16x32_bf16 v[92:95], v[120:123], v[176:179], v[92:95]
	v_mfma_f32_16x16x32_bf16 v[88:91], v[128:131], v[176:179], v[88:91]
	v_mfma_f32_16x16x32_bf16 v[76:79], v[120:123], v[184:187], v[76:79]
	v_mfma_f32_16x16x32_bf16 v[72:75], v[128:131], v[184:187], v[72:75]
	v_mfma_f32_16x16x32_bf16 v[140:143], v[124:127], v[164:167], v[140:143]
	v_mfma_f32_16x16x32_bf16 v[136:139], v[132:135], v[164:167], v[136:139]
	v_mfma_f32_16x16x32_bf16 v[108:111], v[124:127], v[172:175], v[108:111]
	v_mfma_f32_16x16x32_bf16 v[104:107], v[132:135], v[172:175], v[104:107]
	v_mfma_f32_16x16x32_bf16 v[92:95], v[124:127], v[180:183], v[92:95]
	v_mfma_f32_16x16x32_bf16 v[88:91], v[132:135], v[180:183], v[88:91]
	v_mfma_f32_16x16x32_bf16 v[76:79], v[124:127], v[188:191], v[76:79]
	v_mfma_f32_16x16x32_bf16 v[72:75], v[132:135], v[188:191], v[72:75]
	v_mfma_f32_16x16x32_bf16 v[116:119], v[144:147], v[160:163], v[116:119]
	v_mfma_f32_16x16x32_bf16 v[112:115], v[152:155], v[160:163], v[112:115]
	v_mfma_f32_16x16x32_bf16 v[100:103], v[144:147], v[168:171], v[100:103]
	v_mfma_f32_16x16x32_bf16 v[96:99], v[152:155], v[168:171], v[96:99]
	v_mfma_f32_16x16x32_bf16 v[84:87], v[144:147], v[176:179], v[84:87]
	v_mfma_f32_16x16x32_bf16 v[80:83], v[152:155], v[176:179], v[80:83]
	v_mfma_f32_16x16x32_bf16 v[68:71], v[144:147], v[184:187], v[68:71]
	v_mfma_f32_16x16x32_bf16 v[64:67], v[152:155], v[184:187], v[64:67]
	v_mfma_f32_16x16x32_bf16 v[116:119], v[148:151], v[164:167], v[116:119]
	v_mfma_f32_16x16x32_bf16 v[112:115], v[156:159], v[164:167], v[112:115]
	v_mfma_f32_16x16x32_bf16 v[100:103], v[148:151], v[172:175], v[100:103]
	v_mfma_f32_16x16x32_bf16 v[96:99], v[156:159], v[172:175], v[96:99]
	s_setprio 3
	s_barrier
	v_mfma_f32_16x16x32_bf16 v[84:87], v[148:151], v[180:183], v[84:87]
	v_mfma_f32_16x16x32_bf16 v[80:83], v[156:159], v[180:183], v[80:83]
	v_mfma_f32_16x16x32_bf16 v[68:71], v[148:151], v[188:191], v[68:71]
	v_mfma_f32_16x16x32_bf16 v[64:67], v[156:159], v[188:191], v[64:67]
	s_setprio 0
	s_add_i32 s59, s59, s15
	v_lshl_add_u64 v[204:205], v[204:205], 0, s[80:81]
	s_mov_b32 m0, s59
	ds_read_b128 v[160:163], v247 offset:49152
	ds_read_b128 v[164:167], v247 offset:50176
	ds_read_b128 v[168:171], v247 offset:51200
	ds_read_b128 v[172:175], v247 offset:52224
	ds_read_b128 v[176:179], v247 offset:53248
	ds_read_b128 v[180:183], v247 offset:54272
	ds_read_b128 v[184:187], v247 offset:55296
	ds_read_b128 v[188:191], v247 offset:56320
	global_load_lds_dwordx4 v[204:205], off
	s_add_i32 m0, s59, 0x2000
	s_add_u32 s66, s88, 0xb0080
	v_lshl_add_u64 v[204:205], v[206:207], 0, s[80:81]
	s_addc_u32 s67, s89, 0
	s_add_i32 s59, s68, s15
	global_load_lds_dwordx4 v[204:205], off
	v_lshl_add_u64 v[204:205], s[66:67], 0, v[194:195]
	s_mov_b32 m0, s59
	s_nop 0
	global_load_lds_dwordx4 v[204:205], off
	v_lshl_add_u64 v[204:205], s[66:67], 0, v[198:199]
	s_add_i32 m0, s59, 0x2000
	s_nop 0
	global_load_lds_dwordx4 v[204:205], off
	v_lshl_add_u64 v[204:205], v[208:209], 0, s[80:81]
	s_mov_b32 m0, s21
	s_nop 0
	global_load_lds_dwordx4 v[204:205], off
	v_lshl_add_u64 v[204:205], v[210:211], 0, s[80:81]
	s_mov_b32 m0, s22
	s_nop 0
	global_load_lds_dwordx4 v[204:205], off
	s_waitcnt vmcnt(8)
	s_waitcnt lgkmcnt(0)
	s_barrier
	s_setprio 1
	v_mfma_f32_16x16x32_bf16 v[60:63], v[120:123], v[160:163], v[60:63]
	v_mfma_f32_16x16x32_bf16 v[56:59], v[128:131], v[160:163], v[56:59]
	v_mfma_f32_16x16x32_bf16 v[44:47], v[120:123], v[168:171], v[44:47]
	v_mfma_f32_16x16x32_bf16 v[40:43], v[128:131], v[168:171], v[40:43]
	v_mfma_f32_16x16x32_bf16 v[28:31], v[120:123], v[176:179], v[28:31]
	v_mfma_f32_16x16x32_bf16 v[24:27], v[128:131], v[176:179], v[24:27]
	v_mfma_f32_16x16x32_bf16 v[12:15], v[120:123], v[184:187], v[12:15]
	v_mfma_f32_16x16x32_bf16 v[8:11], v[128:131], v[184:187], v[8:11]
	v_mfma_f32_16x16x32_bf16 v[60:63], v[124:127], v[164:167], v[60:63]
	v_mfma_f32_16x16x32_bf16 v[56:59], v[132:135], v[164:167], v[56:59]
	v_mfma_f32_16x16x32_bf16 v[44:47], v[124:127], v[172:175], v[44:47]
	v_mfma_f32_16x16x32_bf16 v[40:43], v[132:135], v[172:175], v[40:43]
	v_mfma_f32_16x16x32_bf16 v[28:31], v[124:127], v[180:183], v[28:31]
	v_mfma_f32_16x16x32_bf16 v[24:27], v[132:135], v[180:183], v[24:27]
	v_mfma_f32_16x16x32_bf16 v[12:15], v[124:127], v[188:191], v[12:15]
	v_mfma_f32_16x16x32_bf16 v[8:11], v[132:135], v[188:191], v[8:11]
	v_mfma_f32_16x16x32_bf16 v[52:55], v[144:147], v[160:163], v[52:55]
	v_mfma_f32_16x16x32_bf16 v[48:51], v[152:155], v[160:163], v[48:51]
	v_mfma_f32_16x16x32_bf16 v[36:39], v[144:147], v[168:171], v[36:39]
	v_mfma_f32_16x16x32_bf16 v[32:35], v[152:155], v[168:171], v[32:35]
	v_mfma_f32_16x16x32_bf16 v[20:23], v[144:147], v[176:179], v[20:23]
	v_mfma_f32_16x16x32_bf16 v[16:19], v[152:155], v[176:179], v[16:19]
	v_mfma_f32_16x16x32_bf16 v[4:7], v[144:147], v[184:187], v[4:7]
	v_mfma_f32_16x16x32_bf16 v[0:3], v[152:155], v[184:187], v[0:3]
	v_mfma_f32_16x16x32_bf16 v[52:55], v[148:151], v[164:167], v[52:55]
	v_mfma_f32_16x16x32_bf16 v[48:51], v[156:159], v[164:167], v[48:51]
	v_mfma_f32_16x16x32_bf16 v[36:39], v[148:151], v[172:175], v[36:39]
	v_mfma_f32_16x16x32_bf16 v[32:35], v[156:159], v[172:175], v[32:35]
	s_setprio 3
	s_barrier
	v_mfma_f32_16x16x32_bf16 v[20:23], v[148:151], v[180:183], v[20:23]
	v_mfma_f32_16x16x32_bf16 v[16:19], v[156:159], v[180:183], v[16:19]
	v_mfma_f32_16x16x32_bf16 v[4:7], v[148:151], v[188:191], v[4:7]
	v_mfma_f32_16x16x32_bf16 v[0:3], v[156:159], v[188:191], v[0:3]
	s_setprio 0
	s_add_i32 s58, s58, 2
	s_add_u32 s86, s86, 0x100
	s_addc_u32 s87, s87, 0
	s_add_u32 s56, s56, 0x100
	s_addc_u32 s57, s57, 0
	s_cmp_gt_u32 s58, 41
	s_cbranch_scc0 .LBB0_272
	s_and_b64 vcc, exec, s[82:83]
	s_cbranch_vccz .LBB0_275
	s_barrier

.LBB0_429:
	ds_read_b128 v[128:131], v203
	ds_read_b128 v[132:135], v203 offset:1024
	ds_read_b128 v[136:139], v203 offset:2048
	ds_read_b128 v[164:167], v203 offset:3072
	ds_read_b128 v[168:171], v204
	ds_read_b128 v[172:175], v204 offset:1024
	ds_read_b128 v[176:179], v204 offset:2048
	ds_read_b128 v[180:183], v204 offset:3072
	s_add_u32 s6, s88, 0xfffc0080
	s_addc_u32 s7, s89, -1
	s_cmp_eq_u32 s21, 12
	s_cselect_b32 vcc_hi, s15, s7
	s_cselect_b32 vcc_lo, s16, s6
	s_cselect_b32 s7, s17, s20
	s_cselect_b32 s6, s18, s19
	v_lshl_add_u64 v[196:197], s[88:89], 0, v[156:157]
	s_add_i32 m0, s58, 0xc000
	ds_read_b128 v[184:187], v205
	ds_read_b128 v[188:191], v205 offset:1024
	ds_read_b128 v[192:195], v205 offset:2048
	ds_read_b128 v[212:215], v205 offset:3072
	ds_read_b128 v[216:219], v205 offset:4096
	ds_read_b128 v[220:223], v205 offset:5120
	ds_read_b128 v[224:227], v205 offset:6144
	ds_read_b128 v[228:231], v205 offset:7168
	global_load_lds_dwordx4 v[196:197], off
	v_lshl_add_u64 v[196:197], s[88:89], 0, v[158:159]
	s_add_i32 m0, s58, 0xe000
	s_nop 0
	global_load_lds_dwordx4 v[196:197], off
	s_waitcnt vmcnt(8)
	s_waitcnt lgkmcnt(0)
	s_barrier
	s_setprio 1
	v_mfma_f32_16x16x32_bf16 v[124:127], v[128:131], v[184:187], v[124:127]
	v_mfma_f32_16x16x32_bf16 v[116:119], v[136:139], v[184:187], v[116:119]
	v_mfma_f32_16x16x32_bf16 v[108:111], v[128:131], v[192:195], v[108:111]
	v_mfma_f32_16x16x32_bf16 v[100:103], v[136:139], v[192:195], v[100:103]
	v_mfma_f32_16x16x32_bf16 v[92:95], v[128:131], v[216:219], v[92:95]
	v_mfma_f32_16x16x32_bf16 v[84:87], v[136:139], v[216:219], v[84:87]
	v_mfma_f32_16x16x32_bf16 v[76:79], v[128:131], v[224:227], v[76:79]
	v_mfma_f32_16x16x32_bf16 v[68:71], v[136:139], v[224:227], v[68:71]
	v_mfma_f32_16x16x32_bf16 v[124:127], v[132:135], v[188:191], v[124:127]
	v_mfma_f32_16x16x32_bf16 v[116:119], v[164:167], v[188:191], v[116:119]
	v_mfma_f32_16x16x32_bf16 v[108:111], v[132:135], v[212:215], v[108:111]
	v_mfma_f32_16x16x32_bf16 v[100:103], v[164:167], v[212:215], v[100:103]
	v_mfma_f32_16x16x32_bf16 v[92:95], v[132:135], v[220:223], v[92:95]
	v_mfma_f32_16x16x32_bf16 v[84:87], v[164:167], v[220:223], v[84:87]
	v_mfma_f32_16x16x32_bf16 v[76:79], v[132:135], v[228:231], v[76:79]
	v_mfma_f32_16x16x32_bf16 v[68:71], v[164:167], v[228:231], v[68:71]
	v_mfma_f32_16x16x32_bf16 v[120:123], v[168:171], v[184:187], v[120:123]
	v_mfma_f32_16x16x32_bf16 v[112:115], v[176:179], v[184:187], v[112:115]
	v_mfma_f32_16x16x32_bf16 v[104:107], v[168:171], v[192:195], v[104:107]
	v_mfma_f32_16x16x32_bf16 v[96:99], v[176:179], v[192:195], v[96:99]
	v_mfma_f32_16x16x32_bf16 v[88:91], v[168:171], v[216:219], v[88:91]
	v_mfma_f32_16x16x32_bf16 v[80:83], v[176:179], v[216:219], v[80:83]
	v_mfma_f32_16x16x32_bf16 v[72:75], v[168:171], v[224:227], v[72:75]
	v_mfma_f32_16x16x32_bf16 v[64:67], v[176:179], v[224:227], v[64:67]
	v_mfma_f32_16x16x32_bf16 v[120:123], v[172:175], v[188:191], v[120:123]
	v_mfma_f32_16x16x32_bf16 v[112:115], v[180:183], v[188:191], v[112:115]
	v_mfma_f32_16x16x32_bf16 v[104:107], v[172:175], v[212:215], v[104:107]
	v_mfma_f32_16x16x32_bf16 v[96:99], v[180:183], v[212:215], v[96:99]
	s_setprio 3
	s_barrier
	v_mfma_f32_16x16x32_bf16 v[88:91], v[172:175], v[220:223], v[88:91]
	v_mfma_f32_16x16x32_bf16 v[80:83], v[180:183], v[220:223], v[80:83]
	v_mfma_f32_16x16x32_bf16 v[72:75], v[172:175], v[228:231], v[72:75]
	v_mfma_f32_16x16x32_bf16 v[64:67], v[180:183], v[228:231], v[64:67]
	s_setprio 0
	s_add_i32 s22, s76, s57
	v_lshl_add_u64 v[196:197], s[6:7], 0, v[142:143]
	s_mov_b32 m0, s22
	ds_read_b128 v[184:187], v205 offset:16384
	ds_read_b128 v[188:191], v205 offset:17408
	ds_read_b128 v[192:195], v205 offset:18432
	ds_read_b128 v[212:215], v205 offset:19456
	ds_read_b128 v[216:219], v205 offset:20480
	ds_read_b128 v[220:223], v205 offset:21504
	ds_read_b128 v[224:227], v205 offset:22528
	ds_read_b128 v[228:231], v205 offset:23552
	global_load_lds_dwordx4 v[196:197], off
	s_add_i32 m0, s22, 0x2000
	s_add_u32 s22, s6, 0x40000
	v_lshl_add_u64 v[232:233], s[6:7], 0, v[146:147]
	s_addc_u32 s23, s7, 0
	s_add_i32 s24, s77, s57
	global_load_lds_dwordx4 v[232:233], off
	v_lshl_add_u64 v[234:235], s[22:23], 0, v[142:143]
	s_mov_b32 m0, s24
	v_lshl_add_u64 v[236:237], vcc, 0, v[144:145]
	global_load_lds_dwordx4 v[234:235], off
	v_lshl_add_u64 v[234:235], s[22:23], 0, v[146:147]
	s_add_i32 m0, s24, 0x2000
	s_nop 0
	global_load_lds_dwordx4 v[234:235], off
	v_lshl_add_u64 v[234:235], vcc, 0, v[140:141]
	s_mov_b32 m0, s58
	s_nop 0
	global_load_lds_dwordx4 v[234:235], off
	s_mov_b32 m0, s59
	s_nop 0
	global_load_lds_dwordx4 v[236:237], off
	s_waitcnt vmcnt(8)
	s_waitcnt lgkmcnt(0)
	s_barrier
	s_setprio 1
	v_mfma_f32_16x16x32_bf16 v[60:63], v[128:131], v[184:187], v[60:63]
	v_mfma_f32_16x16x32_bf16 v[52:55], v[136:139], v[184:187], v[52:55]
	v_mfma_f32_16x16x32_bf16 v[44:47], v[128:131], v[192:195], v[44:47]
	v_mfma_f32_16x16x32_bf16 v[36:39], v[136:139], v[192:195], v[36:39]
	v_mfma_f32_16x16x32_bf16 v[28:31], v[128:131], v[216:219], v[28:31]
	v_mfma_f32_16x16x32_bf16 v[20:23], v[136:139], v[216:219], v[20:23]
	v_mfma_f32_16x16x32_bf16 v[12:15], v[128:131], v[224:227], v[12:15]
	v_mfma_f32_16x16x32_bf16 v[4:7], v[136:139], v[224:227], v[4:7]
	v_mfma_f32_16x16x32_bf16 v[60:63], v[132:135], v[188:191], v[60:63]
	v_mfma_f32_16x16x32_bf16 v[52:55], v[164:167], v[188:191], v[52:55]
	v_mfma_f32_16x16x32_bf16 v[44:47], v[132:135], v[212:215], v[44:47]
	v_mfma_f32_16x16x32_bf16 v[36:39], v[164:167], v[212:215], v[36:39]
	v_mfma_f32_16x16x32_bf16 v[28:31], v[132:135], v[220:223], v[28:31]
	v_mfma_f32_16x16x32_bf16 v[20:23], v[164:167], v[220:223], v[20:23]
	v_mfma_f32_16x16x32_bf16 v[12:15], v[132:135], v[228:231], v[12:15]
	v_mfma_f32_16x16x32_bf16 v[4:7], v[164:167], v[228:231], v[4:7]
	v_mfma_f32_16x16x32_bf16 v[56:59], v[168:171], v[184:187], v[56:59]
	v_mfma_f32_16x16x32_bf16 v[48:51], v[176:179], v[184:187], v[48:51]
	v_mfma_f32_16x16x32_bf16 v[40:43], v[168:171], v[192:195], v[40:43]
	v_mfma_f32_16x16x32_bf16 v[32:35], v[176:179], v[192:195], v[32:35]
	v_mfma_f32_16x16x32_bf16 v[24:27], v[168:171], v[216:219], v[24:27]
	v_mfma_f32_16x16x32_bf16 v[16:19], v[176:179], v[216:219], v[16:19]
	v_mfma_f32_16x16x32_bf16 v[8:11], v[168:171], v[224:227], v[8:11]
	v_mfma_f32_16x16x32_bf16 v[0:3], v[176:179], v[224:227], v[0:3]
	v_mfma_f32_16x16x32_bf16 v[56:59], v[172:175], v[188:191], v[56:59]
	v_mfma_f32_16x16x32_bf16 v[48:51], v[180:183], v[188:191], v[48:51]
	v_mfma_f32_16x16x32_bf16 v[40:43], v[172:175], v[212:215], v[40:43]
	v_mfma_f32_16x16x32_bf16 v[32:35], v[180:183], v[212:215], v[32:35]
	s_setprio 3
	s_barrier
	v_mfma_f32_16x16x32_bf16 v[24:27], v[172:175], v[220:223], v[24:27]
	v_mfma_f32_16x16x32_bf16 v[16:19], v[180:183], v[220:223], v[16:19]
	v_mfma_f32_16x16x32_bf16 v[8:11], v[172:175], v[228:231], v[8:11]
	v_mfma_f32_16x16x32_bf16 v[0:3], v[180:183], v[228:231], v[0:3]
	s_setprio 0
	s_add_i32 s24, 0, 0x18000
	v_add_u32_e32 v150, s24, v200
	s_add_i32 s25, 0, 0x1c000
	ds_read_b128 v[128:131], v150
	ds_read_b128 v[132:135], v150 offset:1024
	ds_read_b128 v[136:139], v150 offset:2048
	ds_read_b128 v[164:167], v150 offset:3072
	v_add_u32_e32 v150, s25, v200
	ds_read_b128 v[168:171], v150
	ds_read_b128 v[172:175], v150 offset:1024
	ds_read_b128 v[176:179], v150 offset:2048
	ds_read_b128 v[180:183], v150 offset:3072
	s_add_u32 s22, vcc_lo, 0x40000
	s_addc_u32 s23, vcc_hi, 0
	s_mov_b32 m0, s66
	v_lshl_add_u64 v[238:239], s[22:23], 0, v[140:141]
	ds_read_b128 v[184:187], v205 offset:32768
	ds_read_b128 v[188:191], v205 offset:33792
	ds_read_b128 v[192:195], v205 offset:34816
	ds_read_b128 v[212:215], v205 offset:35840
	ds_read_b128 v[216:219], v205 offset:36864
	ds_read_b128 v[220:223], v205 offset:37888
	ds_read_b128 v[224:227], v205 offset:38912
	ds_read_b128 v[228:231], v205 offset:39936
	global_load_lds_dwordx4 v[238:239], off
	v_lshl_add_u64 v[238:239], s[22:23], 0, v[144:145]
	s_mov_b32 m0, s67
	s_nop 0
	global_load_lds_dwordx4 v[238:239], off
	s_waitcnt vmcnt(8)
	s_waitcnt lgkmcnt(0)
	s_barrier
	s_setprio 1
	v_mfma_f32_16x16x32_bf16 v[124:127], v[128:131], v[184:187], v[124:127]
	v_mfma_f32_16x16x32_bf16 v[116:119], v[136:139], v[184:187], v[116:119]
	v_mfma_f32_16x16x32_bf16 v[108:111], v[128:131], v[192:195], v[108:111]
	v_mfma_f32_16x16x32_bf16 v[100:103], v[136:139], v[192:195], v[100:103]
	v_mfma_f32_16x16x32_bf16 v[92:95], v[128:131], v[216:219], v[92:95]
	v_mfma_f32_16x16x32_bf16 v[84:87], v[136:139], v[216:219], v[84:87]
	v_mfma_f32_16x16x32_bf16 v[76:79], v[128:131], v[224:227], v[76:79]
	v_mfma_f32_16x16x32_bf16 v[68:71], v[136:139], v[224:227], v[68:71]
	v_mfma_f32_16x16x32_bf16 v[124:127], v[132:135], v[188:191], v[124:127]
	v_mfma_f32_16x16x32_bf16 v[116:119], v[164:167], v[188:191], v[116:119]
	v_mfma_f32_16x16x32_bf16 v[108:111], v[132:135], v[212:215], v[108:111]
	v_mfma_f32_16x16x32_bf16 v[100:103], v[164:167], v[212:215], v[100:103]
	v_mfma_f32_16x16x32_bf16 v[92:95], v[132:135], v[220:223], v[92:95]
	v_mfma_f32_16x16x32_bf16 v[84:87], v[164:167], v[220:223], v[84:87]
	v_mfma_f32_16x16x32_bf16 v[76:79], v[132:135], v[228:231], v[76:79]
	v_mfma_f32_16x16x32_bf16 v[68:71], v[164:167], v[228:231], v[68:71]
	v_mfma_f32_16x16x32_bf16 v[120:123], v[168:171], v[184:187], v[120:123]
	v_mfma_f32_16x16x32_bf16 v[112:115], v[176:179], v[184:187], v[112:115]
	v_mfma_f32_16x16x32_bf16 v[104:107], v[168:171], v[192:195], v[104:107]
	v_mfma_f32_16x16x32_bf16 v[96:99], v[176:179], v[192:195], v[96:99]
	v_mfma_f32_16x16x32_bf16 v[88:91], v[168:171], v[216:219], v[88:91]
	v_mfma_f32_16x16x32_bf16 v[80:83], v[176:179], v[216:219], v[80:83]
	v_mfma_f32_16x16x32_bf16 v[72:75], v[168:171], v[224:227], v[72:75]
	v_mfma_f32_16x16x32_bf16 v[64:67], v[176:179], v[224:227], v[64:67]
	v_mfma_f32_16x16x32_bf16 v[120:123], v[172:175], v[188:191], v[120:123]
	v_mfma_f32_16x16x32_bf16 v[112:115], v[180:183], v[188:191], v[112:115]
	v_mfma_f32_16x16x32_bf16 v[104:107], v[172:175], v[212:215], v[104:107]
	v_mfma_f32_16x16x32_bf16 v[96:99], v[180:183], v[212:215], v[96:99]
	s_setprio 3
	s_barrier
	v_mfma_f32_16x16x32_bf16 v[88:91], v[172:175], v[220:223], v[88:91]
	v_mfma_f32_16x16x32_bf16 v[80:83], v[180:183], v[220:223], v[80:83]
	v_mfma_f32_16x16x32_bf16 v[72:75], v[172:175], v[228:231], v[72:75]
	v_mfma_f32_16x16x32_bf16 v[64:67], v[180:183], v[228:231], v[64:67]
	s_setprio 0
	s_add_i32 s22, s24, s57
	v_lshl_add_u64 v[196:197], v[196:197], 0, s[80:81]
	s_mov_b32 m0, s22
	ds_read_b128 v[184:187], v205 offset:49152
	ds_read_b128 v[188:191], v205 offset:50176
	ds_read_b128 v[192:195], v205 offset:51200
	ds_read_b128 v[212:215], v205 offset:52224
	ds_read_b128 v[216:219], v205 offset:53248
	ds_read_b128 v[220:223], v205 offset:54272
	ds_read_b128 v[224:227], v205 offset:55296
	ds_read_b128 v[228:231], v205 offset:56320
	global_load_lds_dwordx4 v[196:197], off
	s_add_i32 m0, s22, 0x2000
	s_add_u32 s6, s6, 0x40080
	v_lshl_add_u64 v[196:197], v[232:233], 0, s[80:81]
	s_addc_u32 s7, s7, 0
	s_add_i32 s22, s25, s57
	global_load_lds_dwordx4 v[196:197], off
	v_lshl_add_u64 v[196:197], s[6:7], 0, v[142:143]
	s_mov_b32 m0, s22
	s_nop 0
	global_load_lds_dwordx4 v[196:197], off
	v_lshl_add_u64 v[196:197], s[6:7], 0, v[146:147]
	s_add_i32 m0, s22, 0x2000
	s_nop 0
	global_load_lds_dwordx4 v[196:197], off
	v_lshl_add_u64 v[196:197], v[234:235], 0, s[80:81]
	s_mov_b32 m0, s93
	s_nop 0
	global_load_lds_dwordx4 v[196:197], off
	v_lshl_add_u64 v[196:197], v[236:237], 0, s[80:81]
	s_mov_b32 m0, s69
	s_nop 0
	global_load_lds_dwordx4 v[196:197], off
	s_waitcnt vmcnt(8)
	s_waitcnt lgkmcnt(0)
	s_barrier
	s_setprio 1
	v_mfma_f32_16x16x32_bf16 v[60:63], v[128:131], v[184:187], v[60:63]
	v_mfma_f32_16x16x32_bf16 v[52:55], v[136:139], v[184:187], v[52:55]
	v_mfma_f32_16x16x32_bf16 v[44:47], v[128:131], v[192:195], v[44:47]
	v_mfma_f32_16x16x32_bf16 v[36:39], v[136:139], v[192:195], v[36:39]
	v_mfma_f32_16x16x32_bf16 v[28:31], v[128:131], v[216:219], v[28:31]
	v_mfma_f32_16x16x32_bf16 v[20:23], v[136:139], v[216:219], v[20:23]
	v_mfma_f32_16x16x32_bf16 v[12:15], v[128:131], v[224:227], v[12:15]
	v_mfma_f32_16x16x32_bf16 v[4:7], v[136:139], v[224:227], v[4:7]
	v_mfma_f32_16x16x32_bf16 v[60:63], v[132:135], v[188:191], v[60:63]
	v_mfma_f32_16x16x32_bf16 v[52:55], v[164:167], v[188:191], v[52:55]
	v_mfma_f32_16x16x32_bf16 v[44:47], v[132:135], v[212:215], v[44:47]
	v_mfma_f32_16x16x32_bf16 v[36:39], v[164:167], v[212:215], v[36:39]
	v_mfma_f32_16x16x32_bf16 v[28:31], v[132:135], v[220:223], v[28:31]
	v_mfma_f32_16x16x32_bf16 v[20:23], v[164:167], v[220:223], v[20:23]
	v_mfma_f32_16x16x32_bf16 v[12:15], v[132:135], v[228:231], v[12:15]
	v_mfma_f32_16x16x32_bf16 v[4:7], v[164:167], v[228:231], v[4:7]
	v_mfma_f32_16x16x32_bf16 v[56:59], v[168:171], v[184:187], v[56:59]
	v_mfma_f32_16x16x32_bf16 v[48:51], v[176:179], v[184:187], v[48:51]
	v_mfma_f32_16x16x32_bf16 v[40:43], v[168:171], v[192:195], v[40:43]
	v_mfma_f32_16x16x32_bf16 v[32:35], v[176:179], v[192:195], v[32:35]
	v_mfma_f32_16x16x32_bf16 v[24:27], v[168:171], v[216:219], v[24:27]
	v_mfma_f32_16x16x32_bf16 v[16:19], v[176:179], v[216:219], v[16:19]
	v_mfma_f32_16x16x32_bf16 v[8:11], v[168:171], v[224:227], v[8:11]
	v_mfma_f32_16x16x32_bf16 v[0:3], v[176:179], v[224:227], v[0:3]
	v_mfma_f32_16x16x32_bf16 v[56:59], v[172:175], v[188:191], v[56:59]
	v_mfma_f32_16x16x32_bf16 v[48:51], v[180:183], v[188:191], v[48:51]
	v_mfma_f32_16x16x32_bf16 v[40:43], v[172:175], v[212:215], v[40:43]
	v_mfma_f32_16x16x32_bf16 v[32:35], v[180:183], v[212:215], v[32:35]
	s_setprio 3
	s_barrier
	v_mfma_f32_16x16x32_bf16 v[24:27], v[172:175], v[220:223], v[24:27]
	v_mfma_f32_16x16x32_bf16 v[16:19], v[180:183], v[220:223], v[16:19]
	v_mfma_f32_16x16x32_bf16 v[8:11], v[172:175], v[228:231], v[8:11]
	v_mfma_f32_16x16x32_bf16 v[0:3], v[180:183], v[228:231], v[0:3]
	s_setprio 0
	s_add_i32 s21, s21, 2
	s_add_u32 s88, s88, 0x100
	s_addc_u32 s89, s89, 0
	s_add_u32 s19, s19, 0x100
	s_addc_u32 s20, s20, 0
	s_cmp_gt_u32 s21, 13
	s_cbranch_scc0 .LBB0_429
	s_and_b64 vcc, exec, s[82:83]
	s_cbranch_vccz .LBB0_432
	s_barrier

.LBB0_993:
	ds_read_b128 v[120:123], v245
	ds_read_b128 v[124:127], v245 offset:1024
	ds_read_b128 v[128:131], v245 offset:2048
	ds_read_b128 v[132:135], v245 offset:3072
	ds_read_b128 v[144:147], v246
	ds_read_b128 v[148:151], v246 offset:1024
	ds_read_b128 v[152:155], v246 offset:2048
	ds_read_b128 v[156:159], v246 offset:3072
	s_add_u32 s59, s82, 0xfffc0080
	s_addc_u32 s66, s83, -1
	s_cmp_eq_u32 s58, 12
	s_cselect_b32 s87, s53, s66
	s_cselect_b32 s86, s54, s59
	s_cselect_b32 s85, s51, s57
	s_cselect_b32 s84, s55, s56
	v_lshl_add_u64 v[204:205], s[82:83], 0, v[200:201]
	s_add_i32 m0, s16, 0xc000
	ds_read_b128 v[160:163], v247
	ds_read_b128 v[164:167], v247 offset:1024
	ds_read_b128 v[168:171], v247 offset:2048
	ds_read_b128 v[172:175], v247 offset:3072
	ds_read_b128 v[176:179], v247 offset:4096
	ds_read_b128 v[180:183], v247 offset:5120
	ds_read_b128 v[184:187], v247 offset:6144
	ds_read_b128 v[188:191], v247 offset:7168
	global_load_lds_dwordx4 v[204:205], off
	v_lshl_add_u64 v[204:205], s[82:83], 0, v[202:203]
	s_add_i32 m0, s16, 0xe000
	s_nop 0
	global_load_lds_dwordx4 v[204:205], off
	s_waitcnt vmcnt(8)
	s_waitcnt lgkmcnt(0)
	s_barrier
	s_setprio 1
	v_mfma_f32_16x16x32_bf16 v[140:143], v[120:123], v[160:163], v[140:143]
	v_mfma_f32_16x16x32_bf16 v[136:139], v[128:131], v[160:163], v[136:139]
	v_mfma_f32_16x16x32_bf16 v[108:111], v[120:123], v[168:171], v[108:111]
	v_mfma_f32_16x16x32_bf16 v[104:107], v[128:131], v[168:171], v[104:107]
	v_mfma_f32_16x16x32_bf16 v[92:95], v[120:123], v[176:179], v[92:95]
	v_mfma_f32_16x16x32_bf16 v[88:91], v[128:131], v[176:179], v[88:91]
	v_mfma_f32_16x16x32_bf16 v[76:79], v[120:123], v[184:187], v[76:79]
	v_mfma_f32_16x16x32_bf16 v[72:75], v[128:131], v[184:187], v[72:75]
	v_mfma_f32_16x16x32_bf16 v[140:143], v[124:127], v[164:167], v[140:143]
	v_mfma_f32_16x16x32_bf16 v[136:139], v[132:135], v[164:167], v[136:139]
	v_mfma_f32_16x16x32_bf16 v[108:111], v[124:127], v[172:175], v[108:111]
	v_mfma_f32_16x16x32_bf16 v[104:107], v[132:135], v[172:175], v[104:107]
	v_mfma_f32_16x16x32_bf16 v[92:95], v[124:127], v[180:183], v[92:95]
	v_mfma_f32_16x16x32_bf16 v[88:91], v[132:135], v[180:183], v[88:91]
	v_mfma_f32_16x16x32_bf16 v[76:79], v[124:127], v[188:191], v[76:79]
	v_mfma_f32_16x16x32_bf16 v[72:75], v[132:135], v[188:191], v[72:75]
	v_mfma_f32_16x16x32_bf16 v[116:119], v[144:147], v[160:163], v[116:119]
	v_mfma_f32_16x16x32_bf16 v[112:115], v[152:155], v[160:163], v[112:115]
	v_mfma_f32_16x16x32_bf16 v[100:103], v[144:147], v[168:171], v[100:103]
	v_mfma_f32_16x16x32_bf16 v[96:99], v[152:155], v[168:171], v[96:99]
	v_mfma_f32_16x16x32_bf16 v[84:87], v[144:147], v[176:179], v[84:87]
	v_mfma_f32_16x16x32_bf16 v[80:83], v[152:155], v[176:179], v[80:83]
	v_mfma_f32_16x16x32_bf16 v[68:71], v[144:147], v[184:187], v[68:71]
	v_mfma_f32_16x16x32_bf16 v[64:67], v[152:155], v[184:187], v[64:67]
	v_mfma_f32_16x16x32_bf16 v[116:119], v[148:151], v[164:167], v[116:119]
	v_mfma_f32_16x16x32_bf16 v[112:115], v[156:159], v[164:167], v[112:115]
	v_mfma_f32_16x16x32_bf16 v[100:103], v[148:151], v[172:175], v[100:103]
	v_mfma_f32_16x16x32_bf16 v[96:99], v[156:159], v[172:175], v[96:99]
	s_setprio 3
	s_barrier
	v_mfma_f32_16x16x32_bf16 v[84:87], v[148:151], v[180:183], v[84:87]
	v_mfma_f32_16x16x32_bf16 v[80:83], v[156:159], v[180:183], v[80:83]
	v_mfma_f32_16x16x32_bf16 v[68:71], v[148:151], v[188:191], v[68:71]
	v_mfma_f32_16x16x32_bf16 v[64:67], v[156:159], v[188:191], v[64:67]
	s_setprio 0
	s_add_i32 s59, s26, s15
	v_lshl_add_u64 v[204:205], s[84:85], 0, v[194:195]
	s_mov_b32 m0, s59
	ds_read_b128 v[160:163], v247 offset:16384
	ds_read_b128 v[164:167], v247 offset:17408
	ds_read_b128 v[168:171], v247 offset:18432
	ds_read_b128 v[172:175], v247 offset:19456
	ds_read_b128 v[176:179], v247 offset:20480
	ds_read_b128 v[180:183], v247 offset:21504
	ds_read_b128 v[184:187], v247 offset:22528
	ds_read_b128 v[188:191], v247 offset:23552
	global_load_lds_dwordx4 v[204:205], off
	s_add_i32 m0, s59, 0x2000
	s_add_u32 s66, s84, 0x40000
	v_lshl_add_u64 v[206:207], s[84:85], 0, v[198:199]
	s_addc_u32 s67, s85, 0
	s_add_i32 s59, s27, s15
	global_load_lds_dwordx4 v[206:207], off
	v_lshl_add_u64 v[208:209], s[66:67], 0, v[194:195]
	s_mov_b32 m0, s59
	v_lshl_add_u64 v[210:211], s[86:87], 0, v[196:197]
	global_load_lds_dwordx4 v[208:209], off
	v_lshl_add_u64 v[208:209], s[66:67], 0, v[198:199]
	s_add_i32 m0, s59, 0x2000
	s_nop 0
	global_load_lds_dwordx4 v[208:209], off
	v_lshl_add_u64 v[208:209], s[86:87], 0, v[192:193]
	s_mov_b32 m0, s16
	s_nop 0
	global_load_lds_dwordx4 v[208:209], off
	s_mov_b32 m0, s17
	s_nop 0
	global_load_lds_dwordx4 v[210:211], off
	s_waitcnt vmcnt(8)
	s_waitcnt lgkmcnt(0)
	s_barrier
	s_setprio 1
	v_mfma_f32_16x16x32_bf16 v[60:63], v[120:123], v[160:163], v[60:63]
	v_mfma_f32_16x16x32_bf16 v[56:59], v[128:131], v[160:163], v[56:59]
	v_mfma_f32_16x16x32_bf16 v[44:47], v[120:123], v[168:171], v[44:47]
	v_mfma_f32_16x16x32_bf16 v[40:43], v[128:131], v[168:171], v[40:43]
	v_mfma_f32_16x16x32_bf16 v[28:31], v[120:123], v[176:179], v[28:31]
	v_mfma_f32_16x16x32_bf16 v[24:27], v[128:131], v[176:179], v[24:27]
	v_mfma_f32_16x16x32_bf16 v[12:15], v[120:123], v[184:187], v[12:15]
	v_mfma_f32_16x16x32_bf16 v[8:11], v[128:131], v[184:187], v[8:11]
	v_mfma_f32_16x16x32_bf16 v[60:63], v[124:127], v[164:167], v[60:63]
	v_mfma_f32_16x16x32_bf16 v[56:59], v[132:135], v[164:167], v[56:59]
	v_mfma_f32_16x16x32_bf16 v[44:47], v[124:127], v[172:175], v[44:47]
	v_mfma_f32_16x16x32_bf16 v[40:43], v[132:135], v[172:175], v[40:43]
	v_mfma_f32_16x16x32_bf16 v[28:31], v[124:127], v[180:183], v[28:31]
	v_mfma_f32_16x16x32_bf16 v[24:27], v[132:135], v[180:183], v[24:27]
	v_mfma_f32_16x16x32_bf16 v[12:15], v[124:127], v[188:191], v[12:15]
	v_mfma_f32_16x16x32_bf16 v[8:11], v[132:135], v[188:191], v[8:11]
	v_mfma_f32_16x16x32_bf16 v[52:55], v[144:147], v[160:163], v[52:55]
	v_mfma_f32_16x16x32_bf16 v[48:51], v[152:155], v[160:163], v[48:51]
	v_mfma_f32_16x16x32_bf16 v[36:39], v[144:147], v[168:171], v[36:39]
	v_mfma_f32_16x16x32_bf16 v[32:35], v[152:155], v[168:171], v[32:35]
	v_mfma_f32_16x16x32_bf16 v[20:23], v[144:147], v[176:179], v[20:23]
	v_mfma_f32_16x16x32_bf16 v[16:19], v[152:155], v[176:179], v[16:19]
	v_mfma_f32_16x16x32_bf16 v[4:7], v[144:147], v[184:187], v[4:7]
	v_mfma_f32_16x16x32_bf16 v[0:3], v[152:155], v[184:187], v[0:3]
	v_mfma_f32_16x16x32_bf16 v[52:55], v[148:151], v[164:167], v[52:55]
	v_mfma_f32_16x16x32_bf16 v[48:51], v[156:159], v[164:167], v[48:51]
	v_mfma_f32_16x16x32_bf16 v[36:39], v[148:151], v[172:175], v[36:39]
	v_mfma_f32_16x16x32_bf16 v[32:35], v[156:159], v[172:175], v[32:35]
	s_setprio 3
	s_barrier
	v_mfma_f32_16x16x32_bf16 v[20:23], v[148:151], v[180:183], v[20:23]
	v_mfma_f32_16x16x32_bf16 v[16:19], v[156:159], v[180:183], v[16:19]
	v_mfma_f32_16x16x32_bf16 v[4:7], v[148:151], v[188:191], v[4:7]
	v_mfma_f32_16x16x32_bf16 v[0:3], v[156:159], v[188:191], v[0:3]
	s_setprio 0
	s_add_i32 s59, 0, 0x18000
	s_add_i32 s68, 0, 0x1c000
	v_add_u32_e32 v132, s59, v243
	v_add_u32_e32 v156, s68, v243
	ds_read_b128 v[120:123], v132
	ds_read_b128 v[124:127], v132 offset:1024
	ds_read_b128 v[128:131], v132 offset:2048
	ds_read_b128 v[132:135], v132 offset:3072
	ds_read_b128 v[144:147], v156
	ds_read_b128 v[148:151], v156 offset:1024
	ds_read_b128 v[152:155], v156 offset:2048
	ds_read_b128 v[156:159], v156 offset:3072
	s_add_u32 s66, s86, 0x40000
	s_addc_u32 s67, s87, 0
	s_mov_b32 m0, s18
	v_lshl_add_u64 v[212:213], s[66:67], 0, v[192:193]
	ds_read_b128 v[160:163], v247 offset:32768
	ds_read_b128 v[164:167], v247 offset:33792
	ds_read_b128 v[168:171], v247 offset:34816
	ds_read_b128 v[172:175], v247 offset:35840
	ds_read_b128 v[176:179], v247 offset:36864
	ds_read_b128 v[180:183], v247 offset:37888
	ds_read_b128 v[184:187], v247 offset:38912
	ds_read_b128 v[188:191], v247 offset:39936
	global_load_lds_dwordx4 v[212:213], off
	v_lshl_add_u64 v[212:213], s[66:67], 0, v[196:197]
	s_mov_b32 m0, s19
	s_nop 0
	global_load_lds_dwordx4 v[212:213], off
	s_waitcnt vmcnt(8)
	s_waitcnt lgkmcnt(0)
	s_barrier
	s_setprio 1
	v_mfma_f32_16x16x32_bf16 v[140:143], v[120:123], v[160:163], v[140:143]
	v_mfma_f32_16x16x32_bf16 v[136:139], v[128:131], v[160:163], v[136:139]
	v_mfma_f32_16x16x32_bf16 v[108:111], v[120:123], v[168:171], v[108:111]
	v_mfma_f32_16x16x32_bf16 v[104:107], v[128:131], v[168:171], v[104:107]
	v_mfma_f32_16x16x32_bf16 v[92:95], v[120:123], v[176:179], v[92:95]
	v_mfma_f32_16x16x32_bf16 v[88:91], v[128:131], v[176:179], v[88:91]
	v_mfma_f32_16x16x32_bf16 v[76:79], v[120:123], v[184:187], v[76:79]
	v_mfma_f32_16x16x32_bf16 v[72:75], v[128:131], v[184:187], v[72:75]
	v_mfma_f32_16x16x32_bf16 v[140:143], v[124:127], v[164:167], v[140:143]
	v_mfma_f32_16x16x32_bf16 v[136:139], v[132:135], v[164:167], v[136:139]
	v_mfma_f32_16x16x32_bf16 v[108:111], v[124:127], v[172:175], v[108:111]
	v_mfma_f32_16x16x32_bf16 v[104:107], v[132:135], v[172:175], v[104:107]
	v_mfma_f32_16x16x32_bf16 v[92:95], v[124:127], v[180:183], v[92:95]
	v_mfma_f32_16x16x32_bf16 v[88:91], v[132:135], v[180:183], v[88:91]
	v_mfma_f32_16x16x32_bf16 v[76:79], v[124:127], v[188:191], v[76:79]
	v_mfma_f32_16x16x32_bf16 v[72:75], v[132:135], v[188:191], v[72:75]
	v_mfma_f32_16x16x32_bf16 v[116:119], v[144:147], v[160:163], v[116:119]
	v_mfma_f32_16x16x32_bf16 v[112:115], v[152:155], v[160:163], v[112:115]
	v_mfma_f32_16x16x32_bf16 v[100:103], v[144:147], v[168:171], v[100:103]
	v_mfma_f32_16x16x32_bf16 v[96:99], v[152:155], v[168:171], v[96:99]
	v_mfma_f32_16x16x32_bf16 v[84:87], v[144:147], v[176:179], v[84:87]
	v_mfma_f32_16x16x32_bf16 v[80:83], v[152:155], v[176:179], v[80:83]
	v_mfma_f32_16x16x32_bf16 v[68:71], v[144:147], v[184:187], v[68:71]
	v_mfma_f32_16x16x32_bf16 v[64:67], v[152:155], v[184:187], v[64:67]
	v_mfma_f32_16x16x32_bf16 v[116:119], v[148:151], v[164:167], v[116:119]
	v_mfma_f32_16x16x32_bf16 v[112:115], v[156:159], v[164:167], v[112:115]
	v_mfma_f32_16x16x32_bf16 v[100:103], v[148:151], v[172:175], v[100:103]
	v_mfma_f32_16x16x32_bf16 v[96:99], v[156:159], v[172:175], v[96:99]
	s_setprio 3
	s_barrier
	v_mfma_f32_16x16x32_bf16 v[84:87], v[148:151], v[180:183], v[84:87]
	v_mfma_f32_16x16x32_bf16 v[80:83], v[156:159], v[180:183], v[80:83]
	v_mfma_f32_16x16x32_bf16 v[68:71], v[148:151], v[188:191], v[68:71]
	v_mfma_f32_16x16x32_bf16 v[64:67], v[156:159], v[188:191], v[64:67]
	s_setprio 0
	s_add_i32 s59, s59, s15
	v_lshl_add_u64 v[204:205], v[204:205], 0, s[46:47]
	s_mov_b32 m0, s59
	ds_read_b128 v[160:163], v247 offset:49152
	ds_read_b128 v[164:167], v247 offset:50176
	ds_read_b128 v[168:171], v247 offset:51200
	ds_read_b128 v[172:175], v247 offset:52224
	ds_read_b128 v[176:179], v247 offset:53248
	ds_read_b128 v[180:183], v247 offset:54272
	ds_read_b128 v[184:187], v247 offset:55296
	ds_read_b128 v[188:191], v247 offset:56320
	global_load_lds_dwordx4 v[204:205], off
	s_add_i32 m0, s59, 0x2000
	s_add_u32 s66, s84, 0x40080
	v_lshl_add_u64 v[204:205], v[206:207], 0, s[46:47]
	s_addc_u32 s67, s85, 0
	s_add_i32 s59, s68, s15
	global_load_lds_dwordx4 v[204:205], off
	v_lshl_add_u64 v[204:205], s[66:67], 0, v[194:195]
	s_mov_b32 m0, s59
	s_nop 0
	global_load_lds_dwordx4 v[204:205], off
	v_lshl_add_u64 v[204:205], s[66:67], 0, v[198:199]
	s_add_i32 m0, s59, 0x2000
	s_nop 0
	global_load_lds_dwordx4 v[204:205], off
	v_lshl_add_u64 v[204:205], v[208:209], 0, s[46:47]
	s_mov_b32 m0, s21
	s_nop 0
	global_load_lds_dwordx4 v[204:205], off
	v_lshl_add_u64 v[204:205], v[210:211], 0, s[46:47]
	s_mov_b32 m0, s22
	s_nop 0
	global_load_lds_dwordx4 v[204:205], off
	s_waitcnt vmcnt(8)
	s_waitcnt lgkmcnt(0)
	s_barrier
	s_setprio 1
	v_mfma_f32_16x16x32_bf16 v[60:63], v[120:123], v[160:163], v[60:63]
	v_mfma_f32_16x16x32_bf16 v[56:59], v[128:131], v[160:163], v[56:59]
	v_mfma_f32_16x16x32_bf16 v[44:47], v[120:123], v[168:171], v[44:47]
	v_mfma_f32_16x16x32_bf16 v[40:43], v[128:131], v[168:171], v[40:43]
	v_mfma_f32_16x16x32_bf16 v[28:31], v[120:123], v[176:179], v[28:31]
	v_mfma_f32_16x16x32_bf16 v[24:27], v[128:131], v[176:179], v[24:27]
	v_mfma_f32_16x16x32_bf16 v[12:15], v[120:123], v[184:187], v[12:15]
	v_mfma_f32_16x16x32_bf16 v[8:11], v[128:131], v[184:187], v[8:11]
	v_mfma_f32_16x16x32_bf16 v[60:63], v[124:127], v[164:167], v[60:63]
	v_mfma_f32_16x16x32_bf16 v[56:59], v[132:135], v[164:167], v[56:59]
	v_mfma_f32_16x16x32_bf16 v[44:47], v[124:127], v[172:175], v[44:47]
	v_mfma_f32_16x16x32_bf16 v[40:43], v[132:135], v[172:175], v[40:43]
	v_mfma_f32_16x16x32_bf16 v[28:31], v[124:127], v[180:183], v[28:31]
	v_mfma_f32_16x16x32_bf16 v[24:27], v[132:135], v[180:183], v[24:27]
	v_mfma_f32_16x16x32_bf16 v[12:15], v[124:127], v[188:191], v[12:15]
	v_mfma_f32_16x16x32_bf16 v[8:11], v[132:135], v[188:191], v[8:11]
	v_mfma_f32_16x16x32_bf16 v[52:55], v[144:147], v[160:163], v[52:55]
	v_mfma_f32_16x16x32_bf16 v[48:51], v[152:155], v[160:163], v[48:51]
	v_mfma_f32_16x16x32_bf16 v[36:39], v[144:147], v[168:171], v[36:39]
	v_mfma_f32_16x16x32_bf16 v[32:35], v[152:155], v[168:171], v[32:35]
	v_mfma_f32_16x16x32_bf16 v[20:23], v[144:147], v[176:179], v[20:23]
	v_mfma_f32_16x16x32_bf16 v[16:19], v[152:155], v[176:179], v[16:19]
	v_mfma_f32_16x16x32_bf16 v[4:7], v[144:147], v[184:187], v[4:7]
	v_mfma_f32_16x16x32_bf16 v[0:3], v[152:155], v[184:187], v[0:3]
	v_mfma_f32_16x16x32_bf16 v[52:55], v[148:151], v[164:167], v[52:55]
	v_mfma_f32_16x16x32_bf16 v[48:51], v[156:159], v[164:167], v[48:51]
	v_mfma_f32_16x16x32_bf16 v[36:39], v[148:151], v[172:175], v[36:39]
	v_mfma_f32_16x16x32_bf16 v[32:35], v[156:159], v[172:175], v[32:35]
	s_setprio 3
	s_barrier
	v_mfma_f32_16x16x32_bf16 v[20:23], v[148:151], v[180:183], v[20:23]
	v_mfma_f32_16x16x32_bf16 v[16:19], v[156:159], v[180:183], v[16:19]
	v_mfma_f32_16x16x32_bf16 v[4:7], v[148:151], v[188:191], v[4:7]
	v_mfma_f32_16x16x32_bf16 v[0:3], v[156:159], v[188:191], v[0:3]
	s_setprio 0
	s_add_i32 s58, s58, 2
	s_add_u32 s82, s82, 0x100
	s_addc_u32 s83, s83, 0
	s_add_u32 s56, s56, 0x100
	s_addc_u32 s57, s57, 0
	s_cmp_gt_u32 s58, 13
	s_cbranch_scc0 .LBB0_993
	s_and_b64 vcc, exec, s[48:49]
	s_cbranch_vccz .LBB0_996
	s_barrier

.LBB0_1148:
	ds_read_b128 v[146:149], v174
	ds_read_b128 v[150:153], v174 offset:1024
	ds_read_b128 v[154:157], v174 offset:2048
	ds_read_b128 v[158:161], v174 offset:3072
	ds_read_b128 v[162:165], v175
	ds_read_b128 v[178:181], v175 offset:1024
	ds_read_b128 v[182:185], v175 offset:2048
	ds_read_b128 v[186:189], v175 offset:3072
	s_add_u32 s67, s78, 0xfffc0080
	s_addc_u32 s68, s79, -1
	s_cmp_eq_u32 s66, 12
	s_cselect_b32 s83, s49, s68
	s_cselect_b32 s82, s54, s67
	s_cselect_b32 s81, s47, s59
	s_cselect_b32 s80, s55, s58
	v_lshl_add_u64 v[166:167], s[78:79], 0, v[136:137]
	s_add_i32 m0, s17, 0xc000
	ds_read_b128 v[190:193], v176
	ds_read_b128 v[194:197], v176 offset:1024
	ds_read_b128 v[198:201], v176 offset:2048
	ds_read_b128 v[202:205], v176 offset:3072
	ds_read_b128 v[206:209], v176 offset:4096
	ds_read_b128 v[210:213], v176 offset:5120
	ds_read_b128 v[214:217], v176 offset:6144
	ds_read_b128 v[218:221], v176 offset:7168
	global_load_lds_dwordx4 v[166:167], off
	v_lshl_add_u64 v[166:167], s[78:79], 0, v[140:141]
	s_add_i32 m0, s17, 0xe000
	s_nop 0
	global_load_lds_dwordx4 v[166:167], off
	s_waitcnt vmcnt(8)
	s_waitcnt lgkmcnt(0)
	s_barrier
	s_setprio 1
	v_mfma_f32_16x16x32_bf16 v[124:127], v[146:149], v[190:193], v[124:127]
	v_mfma_f32_16x16x32_bf16 v[116:119], v[154:157], v[190:193], v[116:119]
	v_mfma_f32_16x16x32_bf16 v[108:111], v[146:149], v[198:201], v[108:111]
	v_mfma_f32_16x16x32_bf16 v[100:103], v[154:157], v[198:201], v[100:103]
	v_mfma_f32_16x16x32_bf16 v[92:95], v[146:149], v[206:209], v[92:95]
	v_mfma_f32_16x16x32_bf16 v[84:87], v[154:157], v[206:209], v[84:87]
	v_mfma_f32_16x16x32_bf16 v[76:79], v[146:149], v[214:217], v[76:79]
	v_mfma_f32_16x16x32_bf16 v[68:71], v[154:157], v[214:217], v[68:71]
	v_mfma_f32_16x16x32_bf16 v[124:127], v[150:153], v[194:197], v[124:127]
	v_mfma_f32_16x16x32_bf16 v[116:119], v[158:161], v[194:197], v[116:119]
	v_mfma_f32_16x16x32_bf16 v[108:111], v[150:153], v[202:205], v[108:111]
	v_mfma_f32_16x16x32_bf16 v[100:103], v[158:161], v[202:205], v[100:103]
	v_mfma_f32_16x16x32_bf16 v[92:95], v[150:153], v[210:213], v[92:95]
	v_mfma_f32_16x16x32_bf16 v[84:87], v[158:161], v[210:213], v[84:87]
	v_mfma_f32_16x16x32_bf16 v[76:79], v[150:153], v[218:221], v[76:79]
	v_mfma_f32_16x16x32_bf16 v[68:71], v[158:161], v[218:221], v[68:71]
	v_mfma_f32_16x16x32_bf16 v[120:123], v[162:165], v[190:193], v[120:123]
	v_mfma_f32_16x16x32_bf16 v[112:115], v[182:185], v[190:193], v[112:115]
	v_mfma_f32_16x16x32_bf16 v[104:107], v[162:165], v[198:201], v[104:107]
	v_mfma_f32_16x16x32_bf16 v[96:99], v[182:185], v[198:201], v[96:99]
	v_mfma_f32_16x16x32_bf16 v[88:91], v[162:165], v[206:209], v[88:91]
	v_mfma_f32_16x16x32_bf16 v[80:83], v[182:185], v[206:209], v[80:83]
	v_mfma_f32_16x16x32_bf16 v[72:75], v[162:165], v[214:217], v[72:75]
	v_mfma_f32_16x16x32_bf16 v[64:67], v[182:185], v[214:217], v[64:67]
	v_mfma_f32_16x16x32_bf16 v[120:123], v[178:181], v[194:197], v[120:123]
	v_mfma_f32_16x16x32_bf16 v[112:115], v[186:189], v[194:197], v[112:115]
	v_mfma_f32_16x16x32_bf16 v[104:107], v[178:181], v[202:205], v[104:107]
	v_mfma_f32_16x16x32_bf16 v[96:99], v[186:189], v[202:205], v[96:99]
	s_setprio 3
	s_barrier
	v_mfma_f32_16x16x32_bf16 v[88:91], v[178:181], v[210:213], v[88:91]
	v_mfma_f32_16x16x32_bf16 v[80:83], v[186:189], v[210:213], v[80:83]
	v_mfma_f32_16x16x32_bf16 v[72:75], v[178:181], v[218:221], v[72:75]
	v_mfma_f32_16x16x32_bf16 v[64:67], v[186:189], v[218:221], v[64:67]
	s_setprio 0
	s_add_i32 s67, s25, s16
	v_lshl_add_u64 v[166:167], s[80:81], 0, v[132:133]
	s_mov_b32 m0, s67
	ds_read_b128 v[190:193], v176 offset:16384
	ds_read_b128 v[194:197], v176 offset:17408
	ds_read_b128 v[198:201], v176 offset:18432
	ds_read_b128 v[202:205], v176 offset:19456
	ds_read_b128 v[206:209], v176 offset:20480
	ds_read_b128 v[210:213], v176 offset:21504
	ds_read_b128 v[214:217], v176 offset:22528
	ds_read_b128 v[218:221], v176 offset:23552
	global_load_lds_dwordx4 v[166:167], off
	s_add_i32 m0, s67, 0x2000
	s_add_u32 s68, s80, 0x40000
	v_lshl_add_u64 v[222:223], s[80:81], 0, v[128:129]
	s_addc_u32 s69, s81, 0
	s_add_i32 s67, s26, s16
	global_load_lds_dwordx4 v[222:223], off
	v_lshl_add_u64 v[224:225], s[68:69], 0, v[132:133]
	s_mov_b32 m0, s67
	v_lshl_add_u64 v[226:227], s[82:83], 0, v[130:131]
	global_load_lds_dwordx4 v[224:225], off
	v_lshl_add_u64 v[224:225], s[68:69], 0, v[128:129]
	s_add_i32 m0, s67, 0x2000
	s_nop 0
	global_load_lds_dwordx4 v[224:225], off
	v_lshl_add_u64 v[224:225], s[82:83], 0, v[134:135]
	s_mov_b32 m0, s17
	s_nop 0
	global_load_lds_dwordx4 v[224:225], off
	s_mov_b32 m0, s18
	s_nop 0
	global_load_lds_dwordx4 v[226:227], off
	s_waitcnt vmcnt(8)
	s_waitcnt lgkmcnt(0)
	s_barrier
	s_setprio 1
	v_mfma_f32_16x16x32_bf16 v[60:63], v[146:149], v[190:193], v[60:63]
	v_mfma_f32_16x16x32_bf16 v[52:55], v[154:157], v[190:193], v[52:55]
	v_mfma_f32_16x16x32_bf16 v[44:47], v[146:149], v[198:201], v[44:47]
	v_mfma_f32_16x16x32_bf16 v[36:39], v[154:157], v[198:201], v[36:39]
	v_mfma_f32_16x16x32_bf16 v[28:31], v[146:149], v[206:209], v[28:31]
	v_mfma_f32_16x16x32_bf16 v[20:23], v[154:157], v[206:209], v[20:23]
	v_mfma_f32_16x16x32_bf16 v[12:15], v[146:149], v[214:217], v[12:15]
	v_mfma_f32_16x16x32_bf16 v[4:7], v[154:157], v[214:217], v[4:7]
	v_mfma_f32_16x16x32_bf16 v[60:63], v[150:153], v[194:197], v[60:63]
	v_mfma_f32_16x16x32_bf16 v[52:55], v[158:161], v[194:197], v[52:55]
	v_mfma_f32_16x16x32_bf16 v[44:47], v[150:153], v[202:205], v[44:47]
	v_mfma_f32_16x16x32_bf16 v[36:39], v[158:161], v[202:205], v[36:39]
	v_mfma_f32_16x16x32_bf16 v[28:31], v[150:153], v[210:213], v[28:31]
	v_mfma_f32_16x16x32_bf16 v[20:23], v[158:161], v[210:213], v[20:23]
	v_mfma_f32_16x16x32_bf16 v[12:15], v[150:153], v[218:221], v[12:15]
	v_mfma_f32_16x16x32_bf16 v[4:7], v[158:161], v[218:221], v[4:7]
	v_mfma_f32_16x16x32_bf16 v[56:59], v[162:165], v[190:193], v[56:59]
	v_mfma_f32_16x16x32_bf16 v[48:51], v[182:185], v[190:193], v[48:51]
	v_mfma_f32_16x16x32_bf16 v[40:43], v[162:165], v[198:201], v[40:43]
	v_mfma_f32_16x16x32_bf16 v[32:35], v[182:185], v[198:201], v[32:35]
	v_mfma_f32_16x16x32_bf16 v[24:27], v[162:165], v[206:209], v[24:27]
	v_mfma_f32_16x16x32_bf16 v[16:19], v[182:185], v[206:209], v[16:19]
	v_mfma_f32_16x16x32_bf16 v[8:11], v[162:165], v[214:217], v[8:11]
	v_mfma_f32_16x16x32_bf16 v[0:3], v[182:185], v[214:217], v[0:3]
	v_mfma_f32_16x16x32_bf16 v[56:59], v[178:181], v[194:197], v[56:59]
	v_mfma_f32_16x16x32_bf16 v[48:51], v[186:189], v[194:197], v[48:51]
	v_mfma_f32_16x16x32_bf16 v[40:43], v[178:181], v[202:205], v[40:43]
	v_mfma_f32_16x16x32_bf16 v[32:35], v[186:189], v[202:205], v[32:35]
	s_setprio 3
	s_barrier
	v_mfma_f32_16x16x32_bf16 v[24:27], v[178:181], v[210:213], v[24:27]
	v_mfma_f32_16x16x32_bf16 v[16:19], v[186:189], v[210:213], v[16:19]
	v_mfma_f32_16x16x32_bf16 v[8:11], v[178:181], v[218:221], v[8:11]
	v_mfma_f32_16x16x32_bf16 v[0:3], v[186:189], v[218:221], v[0:3]
	s_setprio 0
	s_add_i32 s67, 0, 0x18000
	s_add_i32 s73, 0, 0x1c000
	v_add_u32_e32 v158, s67, v171
	v_add_u32_e32 v186, s73, v171
	ds_read_b128 v[146:149], v158
	ds_read_b128 v[150:153], v158 offset:1024
	ds_read_b128 v[154:157], v158 offset:2048
	ds_read_b128 v[158:161], v158 offset:3072
	ds_read_b128 v[162:165], v186
	ds_read_b128 v[178:181], v186 offset:1024
	ds_read_b128 v[182:185], v186 offset:2048
	ds_read_b128 v[186:189], v186 offset:3072
	s_add_u32 s68, s82, 0x40000
	s_addc_u32 s69, s83, 0
	s_mov_b32 m0, s19
	v_lshl_add_u64 v[228:229], s[68:69], 0, v[134:135]
	ds_read_b128 v[190:193], v176 offset:32768
	ds_read_b128 v[194:197], v176 offset:33792
	ds_read_b128 v[198:201], v176 offset:34816
	ds_read_b128 v[202:205], v176 offset:35840
	ds_read_b128 v[206:209], v176 offset:36864
	ds_read_b128 v[210:213], v176 offset:37888
	ds_read_b128 v[214:217], v176 offset:38912
	ds_read_b128 v[218:221], v176 offset:39936
	global_load_lds_dwordx4 v[228:229], off
	v_lshl_add_u64 v[228:229], s[68:69], 0, v[130:131]
	s_mov_b32 m0, s20
	s_nop 0
	global_load_lds_dwordx4 v[228:229], off
	s_waitcnt vmcnt(8)
	s_waitcnt lgkmcnt(0)
	s_barrier
	s_setprio 1
	v_mfma_f32_16x16x32_bf16 v[124:127], v[146:149], v[190:193], v[124:127]
	v_mfma_f32_16x16x32_bf16 v[116:119], v[154:157], v[190:193], v[116:119]
	v_mfma_f32_16x16x32_bf16 v[108:111], v[146:149], v[198:201], v[108:111]
	v_mfma_f32_16x16x32_bf16 v[100:103], v[154:157], v[198:201], v[100:103]
	v_mfma_f32_16x16x32_bf16 v[92:95], v[146:149], v[206:209], v[92:95]
	v_mfma_f32_16x16x32_bf16 v[84:87], v[154:157], v[206:209], v[84:87]
	v_mfma_f32_16x16x32_bf16 v[76:79], v[146:149], v[214:217], v[76:79]
	v_mfma_f32_16x16x32_bf16 v[68:71], v[154:157], v[214:217], v[68:71]
	v_mfma_f32_16x16x32_bf16 v[124:127], v[150:153], v[194:197], v[124:127]
	v_mfma_f32_16x16x32_bf16 v[116:119], v[158:161], v[194:197], v[116:119]
	v_mfma_f32_16x16x32_bf16 v[108:111], v[150:153], v[202:205], v[108:111]
	v_mfma_f32_16x16x32_bf16 v[100:103], v[158:161], v[202:205], v[100:103]
	v_mfma_f32_16x16x32_bf16 v[92:95], v[150:153], v[210:213], v[92:95]
	v_mfma_f32_16x16x32_bf16 v[84:87], v[158:161], v[210:213], v[84:87]
	v_mfma_f32_16x16x32_bf16 v[76:79], v[150:153], v[218:221], v[76:79]
	v_mfma_f32_16x16x32_bf16 v[68:71], v[158:161], v[218:221], v[68:71]
	v_mfma_f32_16x16x32_bf16 v[120:123], v[162:165], v[190:193], v[120:123]
	v_mfma_f32_16x16x32_bf16 v[112:115], v[182:185], v[190:193], v[112:115]
	v_mfma_f32_16x16x32_bf16 v[104:107], v[162:165], v[198:201], v[104:107]
	v_mfma_f32_16x16x32_bf16 v[96:99], v[182:185], v[198:201], v[96:99]
	v_mfma_f32_16x16x32_bf16 v[88:91], v[162:165], v[206:209], v[88:91]
	v_mfma_f32_16x16x32_bf16 v[80:83], v[182:185], v[206:209], v[80:83]
	v_mfma_f32_16x16x32_bf16 v[72:75], v[162:165], v[214:217], v[72:75]
	v_mfma_f32_16x16x32_bf16 v[64:67], v[182:185], v[214:217], v[64:67]
	v_mfma_f32_16x16x32_bf16 v[120:123], v[178:181], v[194:197], v[120:123]
	v_mfma_f32_16x16x32_bf16 v[112:115], v[186:189], v[194:197], v[112:115]
	v_mfma_f32_16x16x32_bf16 v[104:107], v[178:181], v[202:205], v[104:107]
	v_mfma_f32_16x16x32_bf16 v[96:99], v[186:189], v[202:205], v[96:99]
	s_setprio 3
	s_barrier
	v_mfma_f32_16x16x32_bf16 v[88:91], v[178:181], v[210:213], v[88:91]
	v_mfma_f32_16x16x32_bf16 v[80:83], v[186:189], v[210:213], v[80:83]
	v_mfma_f32_16x16x32_bf16 v[72:75], v[178:181], v[218:221], v[72:75]
	v_mfma_f32_16x16x32_bf16 v[64:67], v[186:189], v[218:221], v[64:67]
	s_setprio 0
	s_add_i32 s67, s67, s16
	v_lshl_add_u64 v[166:167], v[166:167], 0, s[10:11]
	s_mov_b32 m0, s67
	ds_read_b128 v[190:193], v176 offset:49152
	ds_read_b128 v[194:197], v176 offset:50176
	ds_read_b128 v[198:201], v176 offset:51200
	ds_read_b128 v[202:205], v176 offset:52224
	ds_read_b128 v[206:209], v176 offset:53248
	ds_read_b128 v[210:213], v176 offset:54272
	ds_read_b128 v[214:217], v176 offset:55296
	ds_read_b128 v[218:221], v176 offset:56320
	global_load_lds_dwordx4 v[166:167], off
	s_add_i32 m0, s67, 0x2000
	s_add_u32 s68, s80, 0x40080
	v_lshl_add_u64 v[166:167], v[222:223], 0, s[10:11]
	s_addc_u32 s69, s81, 0
	s_add_i32 s67, s73, s16
	global_load_lds_dwordx4 v[166:167], off
	v_lshl_add_u64 v[166:167], s[68:69], 0, v[132:133]
	s_mov_b32 m0, s67
	s_nop 0
	global_load_lds_dwordx4 v[166:167], off
	v_lshl_add_u64 v[166:167], s[68:69], 0, v[128:129]
	s_add_i32 m0, s67, 0x2000
	s_nop 0
	global_load_lds_dwordx4 v[166:167], off
	v_lshl_add_u64 v[166:167], v[224:225], 0, s[10:11]
	s_mov_b32 m0, s23
	s_nop 0
	global_load_lds_dwordx4 v[166:167], off
	v_lshl_add_u64 v[166:167], v[226:227], 0, s[10:11]
	s_mov_b32 m0, s24
	s_nop 0
	global_load_lds_dwordx4 v[166:167], off
	s_waitcnt vmcnt(8)
	s_waitcnt lgkmcnt(0)
	s_barrier
	s_setprio 1
	v_mfma_f32_16x16x32_bf16 v[60:63], v[146:149], v[190:193], v[60:63]
	v_mfma_f32_16x16x32_bf16 v[52:55], v[154:157], v[190:193], v[52:55]
	v_mfma_f32_16x16x32_bf16 v[44:47], v[146:149], v[198:201], v[44:47]
	v_mfma_f32_16x16x32_bf16 v[36:39], v[154:157], v[198:201], v[36:39]
	v_mfma_f32_16x16x32_bf16 v[28:31], v[146:149], v[206:209], v[28:31]
	v_mfma_f32_16x16x32_bf16 v[20:23], v[154:157], v[206:209], v[20:23]
	v_mfma_f32_16x16x32_bf16 v[12:15], v[146:149], v[214:217], v[12:15]
	v_mfma_f32_16x16x32_bf16 v[4:7], v[154:157], v[214:217], v[4:7]
	v_mfma_f32_16x16x32_bf16 v[60:63], v[150:153], v[194:197], v[60:63]
	v_mfma_f32_16x16x32_bf16 v[52:55], v[158:161], v[194:197], v[52:55]
	v_mfma_f32_16x16x32_bf16 v[44:47], v[150:153], v[202:205], v[44:47]
	v_mfma_f32_16x16x32_bf16 v[36:39], v[158:161], v[202:205], v[36:39]
	v_mfma_f32_16x16x32_bf16 v[28:31], v[150:153], v[210:213], v[28:31]
	v_mfma_f32_16x16x32_bf16 v[20:23], v[158:161], v[210:213], v[20:23]
	v_mfma_f32_16x16x32_bf16 v[12:15], v[150:153], v[218:221], v[12:15]
	v_mfma_f32_16x16x32_bf16 v[4:7], v[158:161], v[218:221], v[4:7]
	v_mfma_f32_16x16x32_bf16 v[56:59], v[162:165], v[190:193], v[56:59]
	v_mfma_f32_16x16x32_bf16 v[48:51], v[182:185], v[190:193], v[48:51]
	v_mfma_f32_16x16x32_bf16 v[40:43], v[162:165], v[198:201], v[40:43]
	v_mfma_f32_16x16x32_bf16 v[32:35], v[182:185], v[198:201], v[32:35]
	v_mfma_f32_16x16x32_bf16 v[24:27], v[162:165], v[206:209], v[24:27]
	v_mfma_f32_16x16x32_bf16 v[16:19], v[182:185], v[206:209], v[16:19]
	v_mfma_f32_16x16x32_bf16 v[8:11], v[162:165], v[214:217], v[8:11]
	v_mfma_f32_16x16x32_bf16 v[0:3], v[182:185], v[214:217], v[0:3]
	v_mfma_f32_16x16x32_bf16 v[56:59], v[178:181], v[194:197], v[56:59]
	v_mfma_f32_16x16x32_bf16 v[48:51], v[186:189], v[194:197], v[48:51]
	v_mfma_f32_16x16x32_bf16 v[40:43], v[178:181], v[202:205], v[40:43]
	v_mfma_f32_16x16x32_bf16 v[32:35], v[186:189], v[202:205], v[32:35]
	s_setprio 3
	s_barrier
	v_mfma_f32_16x16x32_bf16 v[24:27], v[178:181], v[210:213], v[24:27]
	v_mfma_f32_16x16x32_bf16 v[16:19], v[186:189], v[210:213], v[16:19]
	v_mfma_f32_16x16x32_bf16 v[8:11], v[178:181], v[218:221], v[8:11]
	v_mfma_f32_16x16x32_bf16 v[0:3], v[186:189], v[218:221], v[0:3]
	s_setprio 0
	s_add_i32 s66, s66, 2
	s_add_u32 s78, s78, 0x100
	s_addc_u32 s79, s79, 0
	s_add_u32 s58, s58, 0x100
	s_addc_u32 s59, s59, 0
	s_cmp_gt_u32 s66, 13
	s_cbranch_scc0 .LBB0_1148
	s_and_b64 vcc, exec, s[44:45]
	s_cbranch_vccz .LBB0_1151
	s_barrier

.LBB0_1299:
	ds_read_b128 v[120:123], v245
	ds_read_b128 v[124:127], v245 offset:1024
	ds_read_b128 v[128:131], v245 offset:2048
	ds_read_b128 v[132:135], v245 offset:3072
	ds_read_b128 v[144:147], v246
	ds_read_b128 v[148:151], v246 offset:1024
	ds_read_b128 v[152:155], v246 offset:2048
	ds_read_b128 v[156:159], v246 offset:3072
	s_add_u32 s66, s76, 0xfff50080
	s_addc_u32 s67, s77, -1
	s_cmp_eq_u32 s59, 40
	s_cselect_b32 s81, s9, s67
	s_cselect_b32 s80, s8, s66
	s_cselect_b32 s79, s53, s58
	s_cselect_b32 s78, s52, s55
	v_lshl_add_u64 v[204:205], s[76:77], 0, v[200:201]
	s_add_i32 m0, s16, 0xc000
	ds_read_b128 v[160:163], v247
	ds_read_b128 v[164:167], v247 offset:1024
	ds_read_b128 v[168:171], v247 offset:2048
	ds_read_b128 v[172:175], v247 offset:3072
	ds_read_b128 v[176:179], v247 offset:4096
	ds_read_b128 v[180:183], v247 offset:5120
	ds_read_b128 v[184:187], v247 offset:6144
	ds_read_b128 v[188:191], v247 offset:7168
	global_load_lds_dwordx4 v[204:205], off
	v_lshl_add_u64 v[204:205], s[76:77], 0, v[202:203]
	s_add_i32 m0, s16, 0xe000
	s_nop 0
	global_load_lds_dwordx4 v[204:205], off
	s_waitcnt vmcnt(8)
	s_waitcnt lgkmcnt(0)
	s_barrier
	s_setprio 1
	v_mfma_f32_16x16x32_bf16 v[140:143], v[120:123], v[160:163], v[140:143]
	v_mfma_f32_16x16x32_bf16 v[136:139], v[128:131], v[160:163], v[136:139]
	v_mfma_f32_16x16x32_bf16 v[108:111], v[120:123], v[168:171], v[108:111]
	v_mfma_f32_16x16x32_bf16 v[104:107], v[128:131], v[168:171], v[104:107]
	v_mfma_f32_16x16x32_bf16 v[92:95], v[120:123], v[176:179], v[92:95]
	v_mfma_f32_16x16x32_bf16 v[88:91], v[128:131], v[176:179], v[88:91]
	v_mfma_f32_16x16x32_bf16 v[76:79], v[120:123], v[184:187], v[76:79]
	v_mfma_f32_16x16x32_bf16 v[72:75], v[128:131], v[184:187], v[72:75]
	v_mfma_f32_16x16x32_bf16 v[140:143], v[124:127], v[164:167], v[140:143]
	v_mfma_f32_16x16x32_bf16 v[136:139], v[132:135], v[164:167], v[136:139]
	v_mfma_f32_16x16x32_bf16 v[108:111], v[124:127], v[172:175], v[108:111]
	v_mfma_f32_16x16x32_bf16 v[104:107], v[132:135], v[172:175], v[104:107]
	v_mfma_f32_16x16x32_bf16 v[92:95], v[124:127], v[180:183], v[92:95]
	v_mfma_f32_16x16x32_bf16 v[88:91], v[132:135], v[180:183], v[88:91]
	v_mfma_f32_16x16x32_bf16 v[76:79], v[124:127], v[188:191], v[76:79]
	v_mfma_f32_16x16x32_bf16 v[72:75], v[132:135], v[188:191], v[72:75]
	v_mfma_f32_16x16x32_bf16 v[116:119], v[144:147], v[160:163], v[116:119]
	v_mfma_f32_16x16x32_bf16 v[112:115], v[152:155], v[160:163], v[112:115]
	v_mfma_f32_16x16x32_bf16 v[100:103], v[144:147], v[168:171], v[100:103]
	v_mfma_f32_16x16x32_bf16 v[96:99], v[152:155], v[168:171], v[96:99]
	v_mfma_f32_16x16x32_bf16 v[84:87], v[144:147], v[176:179], v[84:87]
	v_mfma_f32_16x16x32_bf16 v[80:83], v[152:155], v[176:179], v[80:83]
	v_mfma_f32_16x16x32_bf16 v[68:71], v[144:147], v[184:187], v[68:71]
	v_mfma_f32_16x16x32_bf16 v[64:67], v[152:155], v[184:187], v[64:67]
	v_mfma_f32_16x16x32_bf16 v[116:119], v[148:151], v[164:167], v[116:119]
	v_mfma_f32_16x16x32_bf16 v[112:115], v[156:159], v[164:167], v[112:115]
	v_mfma_f32_16x16x32_bf16 v[100:103], v[148:151], v[172:175], v[100:103]
	v_mfma_f32_16x16x32_bf16 v[96:99], v[156:159], v[172:175], v[96:99]
	s_setprio 3
	s_barrier
	v_mfma_f32_16x16x32_bf16 v[84:87], v[148:151], v[180:183], v[84:87]
	v_mfma_f32_16x16x32_bf16 v[80:83], v[156:159], v[180:183], v[80:83]
	v_mfma_f32_16x16x32_bf16 v[68:71], v[148:151], v[188:191], v[68:71]
	v_mfma_f32_16x16x32_bf16 v[64:67], v[156:159], v[188:191], v[64:67]
	s_setprio 0
	s_add_i32 s66, s26, s15
	v_lshl_add_u64 v[204:205], s[78:79], 0, v[194:195]
	s_mov_b32 m0, s66
	ds_read_b128 v[160:163], v247 offset:16384
	ds_read_b128 v[164:167], v247 offset:17408
	ds_read_b128 v[168:171], v247 offset:18432
	ds_read_b128 v[172:175], v247 offset:19456
	ds_read_b128 v[176:179], v247 offset:20480
	ds_read_b128 v[180:183], v247 offset:21504
	ds_read_b128 v[184:187], v247 offset:22528
	ds_read_b128 v[188:191], v247 offset:23552
	global_load_lds_dwordx4 v[204:205], off
	s_add_i32 m0, s66, 0x2000
	s_add_u32 s66, s78, 0xb0000
	v_lshl_add_u64 v[206:207], s[78:79], 0, v[198:199]
	s_addc_u32 s67, s79, 0
	s_add_i32 s68, s27, s15
	global_load_lds_dwordx4 v[206:207], off
	v_lshl_add_u64 v[208:209], s[66:67], 0, v[194:195]
	s_mov_b32 m0, s68
	v_lshl_add_u64 v[210:211], s[80:81], 0, v[196:197]
	global_load_lds_dwordx4 v[208:209], off
	v_lshl_add_u64 v[208:209], s[66:67], 0, v[198:199]
	s_add_i32 m0, s68, 0x2000
	s_nop 0
	global_load_lds_dwordx4 v[208:209], off
	v_lshl_add_u64 v[208:209], s[80:81], 0, v[192:193]
	s_mov_b32 m0, s16
	s_nop 0
	global_load_lds_dwordx4 v[208:209], off
	s_mov_b32 m0, s17
	s_nop 0
	global_load_lds_dwordx4 v[210:211], off
	s_waitcnt vmcnt(8)
	s_waitcnt lgkmcnt(0)
	s_barrier
	s_setprio 1
	v_mfma_f32_16x16x32_bf16 v[60:63], v[120:123], v[160:163], v[60:63]
	v_mfma_f32_16x16x32_bf16 v[56:59], v[128:131], v[160:163], v[56:59]
	v_mfma_f32_16x16x32_bf16 v[44:47], v[120:123], v[168:171], v[44:47]
	v_mfma_f32_16x16x32_bf16 v[40:43], v[128:131], v[168:171], v[40:43]
	v_mfma_f32_16x16x32_bf16 v[28:31], v[120:123], v[176:179], v[28:31]
	v_mfma_f32_16x16x32_bf16 v[24:27], v[128:131], v[176:179], v[24:27]
	v_mfma_f32_16x16x32_bf16 v[12:15], v[120:123], v[184:187], v[12:15]
	v_mfma_f32_16x16x32_bf16 v[8:11], v[128:131], v[184:187], v[8:11]
	v_mfma_f32_16x16x32_bf16 v[60:63], v[124:127], v[164:167], v[60:63]
	v_mfma_f32_16x16x32_bf16 v[56:59], v[132:135], v[164:167], v[56:59]
	v_mfma_f32_16x16x32_bf16 v[44:47], v[124:127], v[172:175], v[44:47]
	v_mfma_f32_16x16x32_bf16 v[40:43], v[132:135], v[172:175], v[40:43]
	v_mfma_f32_16x16x32_bf16 v[28:31], v[124:127], v[180:183], v[28:31]
	v_mfma_f32_16x16x32_bf16 v[24:27], v[132:135], v[180:183], v[24:27]
	v_mfma_f32_16x16x32_bf16 v[12:15], v[124:127], v[188:191], v[12:15]
	v_mfma_f32_16x16x32_bf16 v[8:11], v[132:135], v[188:191], v[8:11]
	v_mfma_f32_16x16x32_bf16 v[52:55], v[144:147], v[160:163], v[52:55]
	v_mfma_f32_16x16x32_bf16 v[48:51], v[152:155], v[160:163], v[48:51]
	v_mfma_f32_16x16x32_bf16 v[36:39], v[144:147], v[168:171], v[36:39]
	v_mfma_f32_16x16x32_bf16 v[32:35], v[152:155], v[168:171], v[32:35]
	v_mfma_f32_16x16x32_bf16 v[20:23], v[144:147], v[176:179], v[20:23]
	v_mfma_f32_16x16x32_bf16 v[16:19], v[152:155], v[176:179], v[16:19]
	v_mfma_f32_16x16x32_bf16 v[4:7], v[144:147], v[184:187], v[4:7]
	v_mfma_f32_16x16x32_bf16 v[0:3], v[152:155], v[184:187], v[0:3]
	v_mfma_f32_16x16x32_bf16 v[52:55], v[148:151], v[164:167], v[52:55]
	v_mfma_f32_16x16x32_bf16 v[48:51], v[156:159], v[164:167], v[48:51]
	v_mfma_f32_16x16x32_bf16 v[36:39], v[148:151], v[172:175], v[36:39]
	v_mfma_f32_16x16x32_bf16 v[32:35], v[156:159], v[172:175], v[32:35]
	s_setprio 3
	s_barrier
	v_mfma_f32_16x16x32_bf16 v[20:23], v[148:151], v[180:183], v[20:23]
	v_mfma_f32_16x16x32_bf16 v[16:19], v[156:159], v[180:183], v[16:19]
	v_mfma_f32_16x16x32_bf16 v[4:7], v[148:151], v[188:191], v[4:7]
	v_mfma_f32_16x16x32_bf16 v[0:3], v[156:159], v[188:191], v[0:3]
	s_setprio 0
	s_add_i32 s68, 0, 0x18000
	s_add_i32 s69, 0, 0x1c000
	v_add_u32_e32 v132, s68, v243
	v_add_u32_e32 v156, s69, v243
	ds_read_b128 v[120:123], v132
	ds_read_b128 v[124:127], v132 offset:1024
	ds_read_b128 v[128:131], v132 offset:2048
	ds_read_b128 v[132:135], v132 offset:3072
	ds_read_b128 v[144:147], v156
	ds_read_b128 v[148:151], v156 offset:1024
	ds_read_b128 v[152:155], v156 offset:2048
	ds_read_b128 v[156:159], v156 offset:3072
	s_add_u32 s66, s80, 0xb0000
	s_addc_u32 s67, s81, 0
	s_mov_b32 m0, s18
	v_lshl_add_u64 v[212:213], s[66:67], 0, v[192:193]
	ds_read_b128 v[160:163], v247 offset:32768
	ds_read_b128 v[164:167], v247 offset:33792
	ds_read_b128 v[168:171], v247 offset:34816
	ds_read_b128 v[172:175], v247 offset:35840
	ds_read_b128 v[176:179], v247 offset:36864
	ds_read_b128 v[180:183], v247 offset:37888
	ds_read_b128 v[184:187], v247 offset:38912
	ds_read_b128 v[188:191], v247 offset:39936
	global_load_lds_dwordx4 v[212:213], off
	v_lshl_add_u64 v[212:213], s[66:67], 0, v[196:197]
	s_mov_b32 m0, s19
	s_nop 0
	global_load_lds_dwordx4 v[212:213], off
	s_waitcnt vmcnt(8)
	s_waitcnt lgkmcnt(0)
	s_barrier
	s_setprio 1
	v_mfma_f32_16x16x32_bf16 v[140:143], v[120:123], v[160:163], v[140:143]
	v_mfma_f32_16x16x32_bf16 v[136:139], v[128:131], v[160:163], v[136:139]
	v_mfma_f32_16x16x32_bf16 v[108:111], v[120:123], v[168:171], v[108:111]
	v_mfma_f32_16x16x32_bf16 v[104:107], v[128:131], v[168:171], v[104:107]
	v_mfma_f32_16x16x32_bf16 v[92:95], v[120:123], v[176:179], v[92:95]
	v_mfma_f32_16x16x32_bf16 v[88:91], v[128:131], v[176:179], v[88:91]
	v_mfma_f32_16x16x32_bf16 v[76:79], v[120:123], v[184:187], v[76:79]
	v_mfma_f32_16x16x32_bf16 v[72:75], v[128:131], v[184:187], v[72:75]
	v_mfma_f32_16x16x32_bf16 v[140:143], v[124:127], v[164:167], v[140:143]
	v_mfma_f32_16x16x32_bf16 v[136:139], v[132:135], v[164:167], v[136:139]
	v_mfma_f32_16x16x32_bf16 v[108:111], v[124:127], v[172:175], v[108:111]
	v_mfma_f32_16x16x32_bf16 v[104:107], v[132:135], v[172:175], v[104:107]
	v_mfma_f32_16x16x32_bf16 v[92:95], v[124:127], v[180:183], v[92:95]
	v_mfma_f32_16x16x32_bf16 v[88:91], v[132:135], v[180:183], v[88:91]
	v_mfma_f32_16x16x32_bf16 v[76:79], v[124:127], v[188:191], v[76:79]
	v_mfma_f32_16x16x32_bf16 v[72:75], v[132:135], v[188:191], v[72:75]
	v_mfma_f32_16x16x32_bf16 v[116:119], v[144:147], v[160:163], v[116:119]
	v_mfma_f32_16x16x32_bf16 v[112:115], v[152:155], v[160:163], v[112:115]
	v_mfma_f32_16x16x32_bf16 v[100:103], v[144:147], v[168:171], v[100:103]
	v_mfma_f32_16x16x32_bf16 v[96:99], v[152:155], v[168:171], v[96:99]
	v_mfma_f32_16x16x32_bf16 v[84:87], v[144:147], v[176:179], v[84:87]
	v_mfma_f32_16x16x32_bf16 v[80:83], v[152:155], v[176:179], v[80:83]
	v_mfma_f32_16x16x32_bf16 v[68:71], v[144:147], v[184:187], v[68:71]
	v_mfma_f32_16x16x32_bf16 v[64:67], v[152:155], v[184:187], v[64:67]
	v_mfma_f32_16x16x32_bf16 v[116:119], v[148:151], v[164:167], v[116:119]
	v_mfma_f32_16x16x32_bf16 v[112:115], v[156:159], v[164:167], v[112:115]
	v_mfma_f32_16x16x32_bf16 v[100:103], v[148:151], v[172:175], v[100:103]
	v_mfma_f32_16x16x32_bf16 v[96:99], v[156:159], v[172:175], v[96:99]
	s_setprio 3
	s_barrier
	v_mfma_f32_16x16x32_bf16 v[84:87], v[148:151], v[180:183], v[84:87]
	v_mfma_f32_16x16x32_bf16 v[80:83], v[156:159], v[180:183], v[80:83]
	v_mfma_f32_16x16x32_bf16 v[68:71], v[148:151], v[188:191], v[68:71]
	v_mfma_f32_16x16x32_bf16 v[64:67], v[156:159], v[188:191], v[64:67]
	s_setprio 0
	s_add_i32 s66, s68, s15
	v_lshl_add_u64 v[204:205], v[204:205], 0, s[48:49]
	s_mov_b32 m0, s66
	ds_read_b128 v[160:163], v247 offset:49152
	ds_read_b128 v[164:167], v247 offset:50176
	ds_read_b128 v[168:171], v247 offset:51200
	ds_read_b128 v[172:175], v247 offset:52224
	ds_read_b128 v[176:179], v247 offset:53248
	ds_read_b128 v[180:183], v247 offset:54272
	ds_read_b128 v[184:187], v247 offset:55296
	ds_read_b128 v[188:191], v247 offset:56320
	global_load_lds_dwordx4 v[204:205], off
	s_add_i32 m0, s66, 0x2000
	s_add_u32 s66, s78, 0xb0080
	v_lshl_add_u64 v[204:205], v[206:207], 0, s[48:49]
	s_addc_u32 s67, s79, 0
	s_add_i32 s68, s69, s15
	global_load_lds_dwordx4 v[204:205], off
	v_lshl_add_u64 v[204:205], s[66:67], 0, v[194:195]
	s_mov_b32 m0, s68
	s_nop 0
	global_load_lds_dwordx4 v[204:205], off
	v_lshl_add_u64 v[204:205], s[66:67], 0, v[198:199]
	s_add_i32 m0, s68, 0x2000
	s_nop 0
	global_load_lds_dwordx4 v[204:205], off
	v_lshl_add_u64 v[204:205], v[208:209], 0, s[48:49]
	s_mov_b32 m0, s21
	s_nop 0
	global_load_lds_dwordx4 v[204:205], off
	v_lshl_add_u64 v[204:205], v[210:211], 0, s[48:49]
	s_mov_b32 m0, s22
	s_nop 0
	global_load_lds_dwordx4 v[204:205], off
	s_waitcnt vmcnt(8)
	s_waitcnt lgkmcnt(0)
	s_barrier
	s_setprio 1
	v_mfma_f32_16x16x32_bf16 v[60:63], v[120:123], v[160:163], v[60:63]
	v_mfma_f32_16x16x32_bf16 v[56:59], v[128:131], v[160:163], v[56:59]
	v_mfma_f32_16x16x32_bf16 v[44:47], v[120:123], v[168:171], v[44:47]
	v_mfma_f32_16x16x32_bf16 v[40:43], v[128:131], v[168:171], v[40:43]
	v_mfma_f32_16x16x32_bf16 v[28:31], v[120:123], v[176:179], v[28:31]
	v_mfma_f32_16x16x32_bf16 v[24:27], v[128:131], v[176:179], v[24:27]
	v_mfma_f32_16x16x32_bf16 v[12:15], v[120:123], v[184:187], v[12:15]
	v_mfma_f32_16x16x32_bf16 v[8:11], v[128:131], v[184:187], v[8:11]
	v_mfma_f32_16x16x32_bf16 v[60:63], v[124:127], v[164:167], v[60:63]
	v_mfma_f32_16x16x32_bf16 v[56:59], v[132:135], v[164:167], v[56:59]
	v_mfma_f32_16x16x32_bf16 v[44:47], v[124:127], v[172:175], v[44:47]
	v_mfma_f32_16x16x32_bf16 v[40:43], v[132:135], v[172:175], v[40:43]
	v_mfma_f32_16x16x32_bf16 v[28:31], v[124:127], v[180:183], v[28:31]
	v_mfma_f32_16x16x32_bf16 v[24:27], v[132:135], v[180:183], v[24:27]
	v_mfma_f32_16x16x32_bf16 v[12:15], v[124:127], v[188:191], v[12:15]
	v_mfma_f32_16x16x32_bf16 v[8:11], v[132:135], v[188:191], v[8:11]
	v_mfma_f32_16x16x32_bf16 v[52:55], v[144:147], v[160:163], v[52:55]
	v_mfma_f32_16x16x32_bf16 v[48:51], v[152:155], v[160:163], v[48:51]
	v_mfma_f32_16x16x32_bf16 v[36:39], v[144:147], v[168:171], v[36:39]
	v_mfma_f32_16x16x32_bf16 v[32:35], v[152:155], v[168:171], v[32:35]
	v_mfma_f32_16x16x32_bf16 v[20:23], v[144:147], v[176:179], v[20:23]
	v_mfma_f32_16x16x32_bf16 v[16:19], v[152:155], v[176:179], v[16:19]
	v_mfma_f32_16x16x32_bf16 v[4:7], v[144:147], v[184:187], v[4:7]
	v_mfma_f32_16x16x32_bf16 v[0:3], v[152:155], v[184:187], v[0:3]
	v_mfma_f32_16x16x32_bf16 v[52:55], v[148:151], v[164:167], v[52:55]
	v_mfma_f32_16x16x32_bf16 v[48:51], v[156:159], v[164:167], v[48:51]
	v_mfma_f32_16x16x32_bf16 v[36:39], v[148:151], v[172:175], v[36:39]
	v_mfma_f32_16x16x32_bf16 v[32:35], v[156:159], v[172:175], v[32:35]
	s_setprio 3
	s_barrier
	v_mfma_f32_16x16x32_bf16 v[20:23], v[148:151], v[180:183], v[20:23]
	v_mfma_f32_16x16x32_bf16 v[16:19], v[156:159], v[180:183], v[16:19]
	v_mfma_f32_16x16x32_bf16 v[4:7], v[148:151], v[188:191], v[4:7]
	v_mfma_f32_16x16x32_bf16 v[0:3], v[156:159], v[188:191], v[0:3]
	s_setprio 0
	s_add_i32 s59, s59, 2
	s_add_u32 s76, s76, 0x100
	s_addc_u32 s77, s77, 0
	s_add_u32 s55, s55, 0x100
	s_addc_u32 s58, s58, 0
	s_cmp_gt_u32 s59, 41
	s_cbranch_scc0 .LBB0_1299
	s_and_b64 vcc, exec, s[50:51]
	s_cbranch_vccz .LBB0_1302
	s_barrier

.LBB0_1760:
	ds_read_b128 v[128:131], v181
	ds_read_b128 v[132:135], v181 offset:1024
	ds_read_b128 v[136:139], v181 offset:2048
	ds_read_b128 v[160:163], v181 offset:3072
	ds_read_b128 v[164:167], v182
	ds_read_b128 v[168:171], v182 offset:1024
	ds_read_b128 v[186:189], v182 offset:2048
	ds_read_b128 v[190:193], v182 offset:3072
	s_add_u32 s69, s78, 0xfffc0080
	s_addc_u32 s73, s79, -1
	s_cmp_eq_u32 s68, 12
	s_cselect_b32 s83, s49, s73
	s_cselect_b32 s82, s54, s69
	s_cselect_b32 s81, s47, s67
	s_cselect_b32 s80, s55, s66
	v_lshl_add_u64 v[172:173], s[78:79], 0, v[152:153]
	s_add_i32 m0, s18, 0xc000
	ds_read_b128 v[194:197], v183
	ds_read_b128 v[198:201], v183 offset:1024
	ds_read_b128 v[202:205], v183 offset:2048
	ds_read_b128 v[206:209], v183 offset:3072
	ds_read_b128 v[210:213], v183 offset:4096
	ds_read_b128 v[214:217], v183 offset:5120
	ds_read_b128 v[218:221], v183 offset:6144
	ds_read_b128 v[222:225], v183 offset:7168
	global_load_lds_dwordx4 v[172:173], off
	v_lshl_add_u64 v[172:173], s[78:79], 0, v[154:155]
	s_add_i32 m0, s18, 0xe000
	s_nop 0
	global_load_lds_dwordx4 v[172:173], off
	s_waitcnt vmcnt(8)
	s_waitcnt lgkmcnt(0)
	s_barrier
	s_setprio 1
	v_mfma_f32_16x16x32_bf16 v[124:127], v[128:131], v[194:197], v[124:127]
	v_mfma_f32_16x16x32_bf16 v[120:123], v[136:139], v[194:197], v[120:123]
	v_mfma_f32_16x16x32_bf16 v[108:111], v[128:131], v[202:205], v[108:111]
	v_mfma_f32_16x16x32_bf16 v[104:107], v[136:139], v[202:205], v[104:107]
	v_mfma_f32_16x16x32_bf16 v[92:95], v[128:131], v[210:213], v[92:95]
	v_mfma_f32_16x16x32_bf16 v[88:91], v[136:139], v[210:213], v[88:91]
	v_mfma_f32_16x16x32_bf16 v[76:79], v[128:131], v[218:221], v[76:79]
	v_mfma_f32_16x16x32_bf16 v[72:75], v[136:139], v[218:221], v[72:75]
	v_mfma_f32_16x16x32_bf16 v[124:127], v[132:135], v[198:201], v[124:127]
	v_mfma_f32_16x16x32_bf16 v[120:123], v[160:163], v[198:201], v[120:123]
	v_mfma_f32_16x16x32_bf16 v[108:111], v[132:135], v[206:209], v[108:111]
	v_mfma_f32_16x16x32_bf16 v[104:107], v[160:163], v[206:209], v[104:107]
	v_mfma_f32_16x16x32_bf16 v[92:95], v[132:135], v[214:217], v[92:95]
	v_mfma_f32_16x16x32_bf16 v[88:91], v[160:163], v[214:217], v[88:91]
	v_mfma_f32_16x16x32_bf16 v[76:79], v[132:135], v[222:225], v[76:79]
	v_mfma_f32_16x16x32_bf16 v[72:75], v[160:163], v[222:225], v[72:75]
	v_mfma_f32_16x16x32_bf16 v[116:119], v[164:167], v[194:197], v[116:119]
	v_mfma_f32_16x16x32_bf16 v[112:115], v[186:189], v[194:197], v[112:115]
	v_mfma_f32_16x16x32_bf16 v[100:103], v[164:167], v[202:205], v[100:103]
	v_mfma_f32_16x16x32_bf16 v[96:99], v[186:189], v[202:205], v[96:99]
	v_mfma_f32_16x16x32_bf16 v[84:87], v[164:167], v[210:213], v[84:87]
	v_mfma_f32_16x16x32_bf16 v[80:83], v[186:189], v[210:213], v[80:83]
	v_mfma_f32_16x16x32_bf16 v[68:71], v[164:167], v[218:221], v[68:71]
	v_mfma_f32_16x16x32_bf16 v[64:67], v[186:189], v[218:221], v[64:67]
	v_mfma_f32_16x16x32_bf16 v[116:119], v[168:171], v[198:201], v[116:119]
	v_mfma_f32_16x16x32_bf16 v[112:115], v[190:193], v[198:201], v[112:115]
	v_mfma_f32_16x16x32_bf16 v[100:103], v[168:171], v[206:209], v[100:103]
	v_mfma_f32_16x16x32_bf16 v[96:99], v[190:193], v[206:209], v[96:99]
	s_setprio 3
	s_barrier
	v_mfma_f32_16x16x32_bf16 v[84:87], v[168:171], v[214:217], v[84:87]
	v_mfma_f32_16x16x32_bf16 v[80:83], v[190:193], v[214:217], v[80:83]
	v_mfma_f32_16x16x32_bf16 v[68:71], v[168:171], v[222:225], v[68:71]
	v_mfma_f32_16x16x32_bf16 v[64:67], v[190:193], v[222:225], v[64:67]
	s_setprio 0
	s_add_i32 s69, s25, s17
	v_lshl_add_u64 v[172:173], s[80:81], 0, v[142:143]
	s_mov_b32 m0, s69
	ds_read_b128 v[194:197], v183 offset:16384
	ds_read_b128 v[198:201], v183 offset:17408
	ds_read_b128 v[202:205], v183 offset:18432
	ds_read_b128 v[206:209], v183 offset:19456
	ds_read_b128 v[210:213], v183 offset:20480
	ds_read_b128 v[214:217], v183 offset:21504
	ds_read_b128 v[218:221], v183 offset:22528
	ds_read_b128 v[222:225], v183 offset:23552
	global_load_lds_dwordx4 v[172:173], off
	s_add_i32 m0, s69, 0x2000
	s_add_u32 s84, s80, 0x40000
	v_lshl_add_u64 v[226:227], s[80:81], 0, v[146:147]
	s_addc_u32 s85, s81, 0
	s_add_i32 s69, s26, s17
	global_load_lds_dwordx4 v[226:227], off
	v_lshl_add_u64 v[228:229], s[84:85], 0, v[142:143]
	s_mov_b32 m0, s69
	v_lshl_add_u64 v[230:231], s[82:83], 0, v[144:145]
	global_load_lds_dwordx4 v[228:229], off
	v_lshl_add_u64 v[228:229], s[84:85], 0, v[146:147]
	s_add_i32 m0, s69, 0x2000
	s_nop 0
	global_load_lds_dwordx4 v[228:229], off
	v_lshl_add_u64 v[228:229], s[82:83], 0, v[140:141]
	s_mov_b32 m0, s18
	s_nop 0
	global_load_lds_dwordx4 v[228:229], off
	s_mov_b32 m0, s19
	s_nop 0
	global_load_lds_dwordx4 v[230:231], off
	s_waitcnt vmcnt(8)
	s_waitcnt lgkmcnt(0)
	s_barrier
	s_setprio 1
	v_mfma_f32_16x16x32_bf16 v[60:63], v[128:131], v[194:197], v[60:63]
	v_mfma_f32_16x16x32_bf16 v[56:59], v[136:139], v[194:197], v[56:59]
	v_mfma_f32_16x16x32_bf16 v[44:47], v[128:131], v[202:205], v[44:47]
	v_mfma_f32_16x16x32_bf16 v[40:43], v[136:139], v[202:205], v[40:43]
	v_mfma_f32_16x16x32_bf16 v[28:31], v[128:131], v[210:213], v[28:31]
	v_mfma_f32_16x16x32_bf16 v[24:27], v[136:139], v[210:213], v[24:27]
	v_mfma_f32_16x16x32_bf16 v[12:15], v[128:131], v[218:221], v[12:15]
	v_mfma_f32_16x16x32_bf16 v[8:11], v[136:139], v[218:221], v[8:11]
	v_mfma_f32_16x16x32_bf16 v[60:63], v[132:135], v[198:201], v[60:63]
	v_mfma_f32_16x16x32_bf16 v[56:59], v[160:163], v[198:201], v[56:59]
	v_mfma_f32_16x16x32_bf16 v[44:47], v[132:135], v[206:209], v[44:47]
	v_mfma_f32_16x16x32_bf16 v[40:43], v[160:163], v[206:209], v[40:43]
	v_mfma_f32_16x16x32_bf16 v[28:31], v[132:135], v[214:217], v[28:31]
	v_mfma_f32_16x16x32_bf16 v[24:27], v[160:163], v[214:217], v[24:27]
	v_mfma_f32_16x16x32_bf16 v[12:15], v[132:135], v[222:225], v[12:15]
	v_mfma_f32_16x16x32_bf16 v[8:11], v[160:163], v[222:225], v[8:11]
	v_mfma_f32_16x16x32_bf16 v[52:55], v[164:167], v[194:197], v[52:55]
	v_mfma_f32_16x16x32_bf16 v[48:51], v[186:189], v[194:197], v[48:51]
	v_mfma_f32_16x16x32_bf16 v[36:39], v[164:167], v[202:205], v[36:39]
	v_mfma_f32_16x16x32_bf16 v[32:35], v[186:189], v[202:205], v[32:35]
	v_mfma_f32_16x16x32_bf16 v[20:23], v[164:167], v[210:213], v[20:23]
	v_mfma_f32_16x16x32_bf16 v[16:19], v[186:189], v[210:213], v[16:19]
	v_mfma_f32_16x16x32_bf16 v[4:7], v[164:167], v[218:221], v[4:7]
	v_mfma_f32_16x16x32_bf16 v[0:3], v[186:189], v[218:221], v[0:3]
	v_mfma_f32_16x16x32_bf16 v[52:55], v[168:171], v[198:201], v[52:55]
	v_mfma_f32_16x16x32_bf16 v[48:51], v[190:193], v[198:201], v[48:51]
	v_mfma_f32_16x16x32_bf16 v[36:39], v[168:171], v[206:209], v[36:39]
	v_mfma_f32_16x16x32_bf16 v[32:35], v[190:193], v[206:209], v[32:35]
	s_setprio 3
	s_barrier
	v_mfma_f32_16x16x32_bf16 v[20:23], v[168:171], v[214:217], v[20:23]
	v_mfma_f32_16x16x32_bf16 v[16:19], v[190:193], v[214:217], v[16:19]
	v_mfma_f32_16x16x32_bf16 v[4:7], v[168:171], v[222:225], v[4:7]
	v_mfma_f32_16x16x32_bf16 v[0:3], v[190:193], v[222:225], v[0:3]
	s_setprio 0
	s_add_i32 s69, 0, 0x18000
	v_add_u32_e32 v148, s69, v177
	s_add_i32 s73, 0, 0x1c000
	ds_read_b128 v[128:131], v148
	ds_read_b128 v[132:135], v148 offset:1024
	ds_read_b128 v[136:139], v148 offset:2048
	ds_read_b128 v[160:163], v148 offset:3072
	v_add_u32_e32 v148, s73, v177
	ds_read_b128 v[164:167], v148
	ds_read_b128 v[168:171], v148 offset:1024
	ds_read_b128 v[186:189], v148 offset:2048
	ds_read_b128 v[190:193], v148 offset:3072
	s_add_u32 s82, s82, 0x40000
	s_addc_u32 s83, s83, 0
	s_mov_b32 m0, s20
	v_lshl_add_u64 v[232:233], s[82:83], 0, v[140:141]
	ds_read_b128 v[194:197], v183 offset:32768
	ds_read_b128 v[198:201], v183 offset:33792
	ds_read_b128 v[202:205], v183 offset:34816
	ds_read_b128 v[206:209], v183 offset:35840
	ds_read_b128 v[210:213], v183 offset:36864
	ds_read_b128 v[214:217], v183 offset:37888
	ds_read_b128 v[218:221], v183 offset:38912
	ds_read_b128 v[222:225], v183 offset:39936
	global_load_lds_dwordx4 v[232:233], off
	v_lshl_add_u64 v[232:233], s[82:83], 0, v[144:145]
	s_mov_b32 m0, s21
	s_nop 0
	global_load_lds_dwordx4 v[232:233], off
	s_waitcnt vmcnt(8)
	s_waitcnt lgkmcnt(0)
	s_barrier
	s_setprio 1
	v_mfma_f32_16x16x32_bf16 v[124:127], v[128:131], v[194:197], v[124:127]
	v_mfma_f32_16x16x32_bf16 v[120:123], v[136:139], v[194:197], v[120:123]
	v_mfma_f32_16x16x32_bf16 v[108:111], v[128:131], v[202:205], v[108:111]
	v_mfma_f32_16x16x32_bf16 v[104:107], v[136:139], v[202:205], v[104:107]
	v_mfma_f32_16x16x32_bf16 v[92:95], v[128:131], v[210:213], v[92:95]
	v_mfma_f32_16x16x32_bf16 v[88:91], v[136:139], v[210:213], v[88:91]
	v_mfma_f32_16x16x32_bf16 v[76:79], v[128:131], v[218:221], v[76:79]
	v_mfma_f32_16x16x32_bf16 v[72:75], v[136:139], v[218:221], v[72:75]
	v_mfma_f32_16x16x32_bf16 v[124:127], v[132:135], v[198:201], v[124:127]
	v_mfma_f32_16x16x32_bf16 v[120:123], v[160:163], v[198:201], v[120:123]
	v_mfma_f32_16x16x32_bf16 v[108:111], v[132:135], v[206:209], v[108:111]
	v_mfma_f32_16x16x32_bf16 v[104:107], v[160:163], v[206:209], v[104:107]
	v_mfma_f32_16x16x32_bf16 v[92:95], v[132:135], v[214:217], v[92:95]
	v_mfma_f32_16x16x32_bf16 v[88:91], v[160:163], v[214:217], v[88:91]
	v_mfma_f32_16x16x32_bf16 v[76:79], v[132:135], v[222:225], v[76:79]
	v_mfma_f32_16x16x32_bf16 v[72:75], v[160:163], v[222:225], v[72:75]
	v_mfma_f32_16x16x32_bf16 v[116:119], v[164:167], v[194:197], v[116:119]
	v_mfma_f32_16x16x32_bf16 v[112:115], v[186:189], v[194:197], v[112:115]
	v_mfma_f32_16x16x32_bf16 v[100:103], v[164:167], v[202:205], v[100:103]
	v_mfma_f32_16x16x32_bf16 v[96:99], v[186:189], v[202:205], v[96:99]
	v_mfma_f32_16x16x32_bf16 v[84:87], v[164:167], v[210:213], v[84:87]
	v_mfma_f32_16x16x32_bf16 v[80:83], v[186:189], v[210:213], v[80:83]
	v_mfma_f32_16x16x32_bf16 v[68:71], v[164:167], v[218:221], v[68:71]
	v_mfma_f32_16x16x32_bf16 v[64:67], v[186:189], v[218:221], v[64:67]
	v_mfma_f32_16x16x32_bf16 v[116:119], v[168:171], v[198:201], v[116:119]
	v_mfma_f32_16x16x32_bf16 v[112:115], v[190:193], v[198:201], v[112:115]
	v_mfma_f32_16x16x32_bf16 v[100:103], v[168:171], v[206:209], v[100:103]
	v_mfma_f32_16x16x32_bf16 v[96:99], v[190:193], v[206:209], v[96:99]
	s_setprio 3
	s_barrier
	v_mfma_f32_16x16x32_bf16 v[84:87], v[168:171], v[214:217], v[84:87]
	v_mfma_f32_16x16x32_bf16 v[80:83], v[190:193], v[214:217], v[80:83]
	v_mfma_f32_16x16x32_bf16 v[68:71], v[168:171], v[222:225], v[68:71]
	v_mfma_f32_16x16x32_bf16 v[64:67], v[190:193], v[222:225], v[64:67]
	s_setprio 0
	s_add_i32 s69, s69, s17
	v_lshl_add_u64 v[172:173], v[172:173], 0, s[10:11]
	s_mov_b32 m0, s69
	ds_read_b128 v[194:197], v183 offset:49152
	ds_read_b128 v[198:201], v183 offset:50176
	ds_read_b128 v[202:205], v183 offset:51200
	ds_read_b128 v[206:209], v183 offset:52224
	ds_read_b128 v[210:213], v183 offset:53248
	ds_read_b128 v[214:217], v183 offset:54272
	ds_read_b128 v[218:221], v183 offset:55296
	ds_read_b128 v[222:225], v183 offset:56320
	global_load_lds_dwordx4 v[172:173], off
	s_add_i32 m0, s69, 0x2000
	s_add_u32 s80, s80, 0x40080
	v_lshl_add_u64 v[172:173], v[226:227], 0, s[10:11]
	s_addc_u32 s81, s81, 0
	s_add_i32 s69, s73, s17
	global_load_lds_dwordx4 v[172:173], off
	v_lshl_add_u64 v[172:173], s[80:81], 0, v[142:143]
	s_mov_b32 m0, s69
	s_nop 0
	global_load_lds_dwordx4 v[172:173], off
	v_lshl_add_u64 v[172:173], s[80:81], 0, v[146:147]
	s_add_i32 m0, s69, 0x2000
	s_nop 0
	global_load_lds_dwordx4 v[172:173], off
	v_lshl_add_u64 v[172:173], v[228:229], 0, s[10:11]
	s_mov_b32 m0, s23
	s_nop 0
	global_load_lds_dwordx4 v[172:173], off
	v_lshl_add_u64 v[172:173], v[230:231], 0, s[10:11]
	s_mov_b32 m0, s24
	s_nop 0
	global_load_lds_dwordx4 v[172:173], off
	s_waitcnt vmcnt(8)
	s_waitcnt lgkmcnt(0)
	s_barrier
	s_setprio 1
	v_mfma_f32_16x16x32_bf16 v[60:63], v[128:131], v[194:197], v[60:63]
	v_mfma_f32_16x16x32_bf16 v[56:59], v[136:139], v[194:197], v[56:59]
	v_mfma_f32_16x16x32_bf16 v[44:47], v[128:131], v[202:205], v[44:47]
	v_mfma_f32_16x16x32_bf16 v[40:43], v[136:139], v[202:205], v[40:43]
	v_mfma_f32_16x16x32_bf16 v[28:31], v[128:131], v[210:213], v[28:31]
	v_mfma_f32_16x16x32_bf16 v[24:27], v[136:139], v[210:213], v[24:27]
	v_mfma_f32_16x16x32_bf16 v[12:15], v[128:131], v[218:221], v[12:15]
	v_mfma_f32_16x16x32_bf16 v[8:11], v[136:139], v[218:221], v[8:11]
	v_mfma_f32_16x16x32_bf16 v[60:63], v[132:135], v[198:201], v[60:63]
	v_mfma_f32_16x16x32_bf16 v[56:59], v[160:163], v[198:201], v[56:59]
	v_mfma_f32_16x16x32_bf16 v[44:47], v[132:135], v[206:209], v[44:47]
	v_mfma_f32_16x16x32_bf16 v[40:43], v[160:163], v[206:209], v[40:43]
	v_mfma_f32_16x16x32_bf16 v[28:31], v[132:135], v[214:217], v[28:31]
	v_mfma_f32_16x16x32_bf16 v[24:27], v[160:163], v[214:217], v[24:27]
	v_mfma_f32_16x16x32_bf16 v[12:15], v[132:135], v[222:225], v[12:15]
	v_mfma_f32_16x16x32_bf16 v[8:11], v[160:163], v[222:225], v[8:11]
	v_mfma_f32_16x16x32_bf16 v[52:55], v[164:167], v[194:197], v[52:55]
	v_mfma_f32_16x16x32_bf16 v[48:51], v[186:189], v[194:197], v[48:51]
	v_mfma_f32_16x16x32_bf16 v[36:39], v[164:167], v[202:205], v[36:39]
	v_mfma_f32_16x16x32_bf16 v[32:35], v[186:189], v[202:205], v[32:35]
	v_mfma_f32_16x16x32_bf16 v[20:23], v[164:167], v[210:213], v[20:23]
	v_mfma_f32_16x16x32_bf16 v[16:19], v[186:189], v[210:213], v[16:19]
	v_mfma_f32_16x16x32_bf16 v[4:7], v[164:167], v[218:221], v[4:7]
	v_mfma_f32_16x16x32_bf16 v[0:3], v[186:189], v[218:221], v[0:3]
	v_mfma_f32_16x16x32_bf16 v[52:55], v[168:171], v[198:201], v[52:55]
	v_mfma_f32_16x16x32_bf16 v[48:51], v[190:193], v[198:201], v[48:51]
	v_mfma_f32_16x16x32_bf16 v[36:39], v[168:171], v[206:209], v[36:39]
	v_mfma_f32_16x16x32_bf16 v[32:35], v[190:193], v[206:209], v[32:35]
	s_setprio 3
	s_barrier
	v_mfma_f32_16x16x32_bf16 v[20:23], v[168:171], v[214:217], v[20:23]
	v_mfma_f32_16x16x32_bf16 v[16:19], v[190:193], v[214:217], v[16:19]
	v_mfma_f32_16x16x32_bf16 v[4:7], v[168:171], v[222:225], v[4:7]
	v_mfma_f32_16x16x32_bf16 v[0:3], v[190:193], v[222:225], v[0:3]
	s_setprio 0
	s_add_i32 s68, s68, 2
	s_add_u32 s78, s78, 0x100
	s_addc_u32 s79, s79, 0
	s_add_u32 s66, s66, 0x100
	s_addc_u32 s67, s67, 0
	s_cmp_gt_u32 s68, 13
	s_cbranch_scc0 .LBB0_1760
	s_and_b64 vcc, exec, s[44:45]
	s_cbranch_vccz .LBB0_1763
	s_barrier

.LBB0_2037:
	ds_read_b128 v[120:123], v245
	ds_read_b128 v[124:127], v245 offset:1024
	ds_read_b128 v[128:131], v245 offset:2048
	ds_read_b128 v[132:135], v245 offset:3072
	ds_read_b128 v[144:147], v246
	ds_read_b128 v[148:151], v246 offset:1024
	ds_read_b128 v[152:155], v246 offset:2048
	ds_read_b128 v[156:159], v246 offset:3072
	s_add_u32 s67, s76, 0xfffc0080
	s_addc_u32 s68, s77, -1
	s_cmp_eq_u32 s66, 12
	s_cselect_b32 s81, s53, s68
	s_cselect_b32 s80, s54, s67
	s_cselect_b32 s79, s51, s57
	s_cselect_b32 s78, s55, s56
	v_lshl_add_u64 v[204:205], s[76:77], 0, v[200:201]
	s_add_i32 m0, s16, 0xc000
	ds_read_b128 v[160:163], v247
	ds_read_b128 v[164:167], v247 offset:1024
	ds_read_b128 v[168:171], v247 offset:2048
	ds_read_b128 v[172:175], v247 offset:3072
	ds_read_b128 v[176:179], v247 offset:4096
	ds_read_b128 v[180:183], v247 offset:5120
	ds_read_b128 v[184:187], v247 offset:6144
	ds_read_b128 v[188:191], v247 offset:7168
	global_load_lds_dwordx4 v[204:205], off
	v_lshl_add_u64 v[204:205], s[76:77], 0, v[202:203]
	s_add_i32 m0, s16, 0xe000
	s_nop 0
	global_load_lds_dwordx4 v[204:205], off
	s_waitcnt vmcnt(8)
	s_waitcnt lgkmcnt(0)
	s_barrier
	s_setprio 1
	v_mfma_f32_16x16x32_bf16 v[140:143], v[120:123], v[160:163], v[140:143]
	v_mfma_f32_16x16x32_bf16 v[136:139], v[128:131], v[160:163], v[136:139]
	v_mfma_f32_16x16x32_bf16 v[108:111], v[120:123], v[168:171], v[108:111]
	v_mfma_f32_16x16x32_bf16 v[104:107], v[128:131], v[168:171], v[104:107]
	v_mfma_f32_16x16x32_bf16 v[92:95], v[120:123], v[176:179], v[92:95]
	v_mfma_f32_16x16x32_bf16 v[88:91], v[128:131], v[176:179], v[88:91]
	v_mfma_f32_16x16x32_bf16 v[76:79], v[120:123], v[184:187], v[76:79]
	v_mfma_f32_16x16x32_bf16 v[72:75], v[128:131], v[184:187], v[72:75]
	v_mfma_f32_16x16x32_bf16 v[140:143], v[124:127], v[164:167], v[140:143]
	v_mfma_f32_16x16x32_bf16 v[136:139], v[132:135], v[164:167], v[136:139]
	v_mfma_f32_16x16x32_bf16 v[108:111], v[124:127], v[172:175], v[108:111]
	v_mfma_f32_16x16x32_bf16 v[104:107], v[132:135], v[172:175], v[104:107]
	v_mfma_f32_16x16x32_bf16 v[92:95], v[124:127], v[180:183], v[92:95]
	v_mfma_f32_16x16x32_bf16 v[88:91], v[132:135], v[180:183], v[88:91]
	v_mfma_f32_16x16x32_bf16 v[76:79], v[124:127], v[188:191], v[76:79]
	v_mfma_f32_16x16x32_bf16 v[72:75], v[132:135], v[188:191], v[72:75]
	v_mfma_f32_16x16x32_bf16 v[116:119], v[144:147], v[160:163], v[116:119]
	v_mfma_f32_16x16x32_bf16 v[112:115], v[152:155], v[160:163], v[112:115]
	v_mfma_f32_16x16x32_bf16 v[100:103], v[144:147], v[168:171], v[100:103]
	v_mfma_f32_16x16x32_bf16 v[96:99], v[152:155], v[168:171], v[96:99]
	v_mfma_f32_16x16x32_bf16 v[84:87], v[144:147], v[176:179], v[84:87]
	v_mfma_f32_16x16x32_bf16 v[80:83], v[152:155], v[176:179], v[80:83]
	v_mfma_f32_16x16x32_bf16 v[68:71], v[144:147], v[184:187], v[68:71]
	v_mfma_f32_16x16x32_bf16 v[64:67], v[152:155], v[184:187], v[64:67]
	v_mfma_f32_16x16x32_bf16 v[116:119], v[148:151], v[164:167], v[116:119]
	v_mfma_f32_16x16x32_bf16 v[112:115], v[156:159], v[164:167], v[112:115]
	v_mfma_f32_16x16x32_bf16 v[100:103], v[148:151], v[172:175], v[100:103]
	v_mfma_f32_16x16x32_bf16 v[96:99], v[156:159], v[172:175], v[96:99]
	s_setprio 3
	s_barrier
	v_mfma_f32_16x16x32_bf16 v[84:87], v[148:151], v[180:183], v[84:87]
	v_mfma_f32_16x16x32_bf16 v[80:83], v[156:159], v[180:183], v[80:83]
	v_mfma_f32_16x16x32_bf16 v[68:71], v[148:151], v[188:191], v[68:71]
	v_mfma_f32_16x16x32_bf16 v[64:67], v[156:159], v[188:191], v[64:67]
	s_setprio 0
	s_add_i32 s67, s26, s15
	v_lshl_add_u64 v[204:205], s[78:79], 0, v[194:195]
	s_mov_b32 m0, s67
	ds_read_b128 v[160:163], v247 offset:16384
	ds_read_b128 v[164:167], v247 offset:17408
	ds_read_b128 v[168:171], v247 offset:18432
	ds_read_b128 v[172:175], v247 offset:19456
	ds_read_b128 v[176:179], v247 offset:20480
	ds_read_b128 v[180:183], v247 offset:21504
	ds_read_b128 v[184:187], v247 offset:22528
	ds_read_b128 v[188:191], v247 offset:23552
	global_load_lds_dwordx4 v[204:205], off
	s_add_i32 m0, s67, 0x2000
	s_add_u32 s68, s78, 0x40000
	v_lshl_add_u64 v[206:207], s[78:79], 0, v[198:199]
	s_addc_u32 s69, s79, 0
	s_add_i32 s67, s27, s15
	global_load_lds_dwordx4 v[206:207], off
	v_lshl_add_u64 v[208:209], s[68:69], 0, v[194:195]
	s_mov_b32 m0, s67
	v_lshl_add_u64 v[210:211], s[80:81], 0, v[196:197]
	global_load_lds_dwordx4 v[208:209], off
	v_lshl_add_u64 v[208:209], s[68:69], 0, v[198:199]
	s_add_i32 m0, s67, 0x2000
	s_nop 0
	global_load_lds_dwordx4 v[208:209], off
	v_lshl_add_u64 v[208:209], s[80:81], 0, v[192:193]
	s_mov_b32 m0, s16
	s_nop 0
	global_load_lds_dwordx4 v[208:209], off
	s_mov_b32 m0, s17
	s_nop 0
	global_load_lds_dwordx4 v[210:211], off
	s_waitcnt vmcnt(8)
	s_waitcnt lgkmcnt(0)
	s_barrier
	s_setprio 1
	v_mfma_f32_16x16x32_bf16 v[60:63], v[120:123], v[160:163], v[60:63]
	v_mfma_f32_16x16x32_bf16 v[56:59], v[128:131], v[160:163], v[56:59]
	v_mfma_f32_16x16x32_bf16 v[44:47], v[120:123], v[168:171], v[44:47]
	v_mfma_f32_16x16x32_bf16 v[40:43], v[128:131], v[168:171], v[40:43]
	v_mfma_f32_16x16x32_bf16 v[28:31], v[120:123], v[176:179], v[28:31]
	v_mfma_f32_16x16x32_bf16 v[24:27], v[128:131], v[176:179], v[24:27]
	v_mfma_f32_16x16x32_bf16 v[12:15], v[120:123], v[184:187], v[12:15]
	v_mfma_f32_16x16x32_bf16 v[8:11], v[128:131], v[184:187], v[8:11]
	v_mfma_f32_16x16x32_bf16 v[60:63], v[124:127], v[164:167], v[60:63]
	v_mfma_f32_16x16x32_bf16 v[56:59], v[132:135], v[164:167], v[56:59]
	v_mfma_f32_16x16x32_bf16 v[44:47], v[124:127], v[172:175], v[44:47]
	v_mfma_f32_16x16x32_bf16 v[40:43], v[132:135], v[172:175], v[40:43]
	v_mfma_f32_16x16x32_bf16 v[28:31], v[124:127], v[180:183], v[28:31]
	v_mfma_f32_16x16x32_bf16 v[24:27], v[132:135], v[180:183], v[24:27]
	v_mfma_f32_16x16x32_bf16 v[12:15], v[124:127], v[188:191], v[12:15]
	v_mfma_f32_16x16x32_bf16 v[8:11], v[132:135], v[188:191], v[8:11]
	v_mfma_f32_16x16x32_bf16 v[52:55], v[144:147], v[160:163], v[52:55]
	v_mfma_f32_16x16x32_bf16 v[48:51], v[152:155], v[160:163], v[48:51]
	v_mfma_f32_16x16x32_bf16 v[36:39], v[144:147], v[168:171], v[36:39]
	v_mfma_f32_16x16x32_bf16 v[32:35], v[152:155], v[168:171], v[32:35]
	v_mfma_f32_16x16x32_bf16 v[20:23], v[144:147], v[176:179], v[20:23]
	v_mfma_f32_16x16x32_bf16 v[16:19], v[152:155], v[176:179], v[16:19]
	v_mfma_f32_16x16x32_bf16 v[4:7], v[144:147], v[184:187], v[4:7]
	v_mfma_f32_16x16x32_bf16 v[0:3], v[152:155], v[184:187], v[0:3]
	v_mfma_f32_16x16x32_bf16 v[52:55], v[148:151], v[164:167], v[52:55]
	v_mfma_f32_16x16x32_bf16 v[48:51], v[156:159], v[164:167], v[48:51]
	v_mfma_f32_16x16x32_bf16 v[36:39], v[148:151], v[172:175], v[36:39]
	v_mfma_f32_16x16x32_bf16 v[32:35], v[156:159], v[172:175], v[32:35]
	s_setprio 3
	s_barrier
	v_mfma_f32_16x16x32_bf16 v[20:23], v[148:151], v[180:183], v[20:23]
	v_mfma_f32_16x16x32_bf16 v[16:19], v[156:159], v[180:183], v[16:19]
	v_mfma_f32_16x16x32_bf16 v[4:7], v[148:151], v[188:191], v[4:7]
	v_mfma_f32_16x16x32_bf16 v[0:3], v[156:159], v[188:191], v[0:3]
	s_setprio 0
	s_add_i32 s67, 0, 0x18000
	s_add_i32 s75, 0, 0x1c000
	v_add_u32_e32 v132, s67, v243
	v_add_u32_e32 v156, s75, v243
	ds_read_b128 v[120:123], v132
	ds_read_b128 v[124:127], v132 offset:1024
	ds_read_b128 v[128:131], v132 offset:2048
	ds_read_b128 v[132:135], v132 offset:3072
	ds_read_b128 v[144:147], v156
	ds_read_b128 v[148:151], v156 offset:1024
	ds_read_b128 v[152:155], v156 offset:2048
	ds_read_b128 v[156:159], v156 offset:3072
	s_add_u32 s68, s80, 0x40000
	s_addc_u32 s69, s81, 0
	s_mov_b32 m0, s18
	v_lshl_add_u64 v[212:213], s[68:69], 0, v[192:193]
	ds_read_b128 v[160:163], v247 offset:32768
	ds_read_b128 v[164:167], v247 offset:33792
	ds_read_b128 v[168:171], v247 offset:34816
	ds_read_b128 v[172:175], v247 offset:35840
	ds_read_b128 v[176:179], v247 offset:36864
	ds_read_b128 v[180:183], v247 offset:37888
	ds_read_b128 v[184:187], v247 offset:38912
	ds_read_b128 v[188:191], v247 offset:39936
	global_load_lds_dwordx4 v[212:213], off
	v_lshl_add_u64 v[212:213], s[68:69], 0, v[196:197]
	s_mov_b32 m0, s19
	s_nop 0
	global_load_lds_dwordx4 v[212:213], off
	s_waitcnt vmcnt(8)
	s_waitcnt lgkmcnt(0)
	s_barrier
	s_setprio 1
	v_mfma_f32_16x16x32_bf16 v[140:143], v[120:123], v[160:163], v[140:143]
	v_mfma_f32_16x16x32_bf16 v[136:139], v[128:131], v[160:163], v[136:139]
	v_mfma_f32_16x16x32_bf16 v[108:111], v[120:123], v[168:171], v[108:111]
	v_mfma_f32_16x16x32_bf16 v[104:107], v[128:131], v[168:171], v[104:107]
	v_mfma_f32_16x16x32_bf16 v[92:95], v[120:123], v[176:179], v[92:95]
	v_mfma_f32_16x16x32_bf16 v[88:91], v[128:131], v[176:179], v[88:91]
	v_mfma_f32_16x16x32_bf16 v[76:79], v[120:123], v[184:187], v[76:79]
	v_mfma_f32_16x16x32_bf16 v[72:75], v[128:131], v[184:187], v[72:75]
	v_mfma_f32_16x16x32_bf16 v[140:143], v[124:127], v[164:167], v[140:143]
	v_mfma_f32_16x16x32_bf16 v[136:139], v[132:135], v[164:167], v[136:139]
	v_mfma_f32_16x16x32_bf16 v[108:111], v[124:127], v[172:175], v[108:111]
	v_mfma_f32_16x16x32_bf16 v[104:107], v[132:135], v[172:175], v[104:107]
	v_mfma_f32_16x16x32_bf16 v[92:95], v[124:127], v[180:183], v[92:95]
	v_mfma_f32_16x16x32_bf16 v[88:91], v[132:135], v[180:183], v[88:91]
	v_mfma_f32_16x16x32_bf16 v[76:79], v[124:127], v[188:191], v[76:79]
	v_mfma_f32_16x16x32_bf16 v[72:75], v[132:135], v[188:191], v[72:75]
	v_mfma_f32_16x16x32_bf16 v[116:119], v[144:147], v[160:163], v[116:119]
	v_mfma_f32_16x16x32_bf16 v[112:115], v[152:155], v[160:163], v[112:115]
	v_mfma_f32_16x16x32_bf16 v[100:103], v[144:147], v[168:171], v[100:103]
	v_mfma_f32_16x16x32_bf16 v[96:99], v[152:155], v[168:171], v[96:99]
	v_mfma_f32_16x16x32_bf16 v[84:87], v[144:147], v[176:179], v[84:87]
	v_mfma_f32_16x16x32_bf16 v[80:83], v[152:155], v[176:179], v[80:83]
	v_mfma_f32_16x16x32_bf16 v[68:71], v[144:147], v[184:187], v[68:71]
	v_mfma_f32_16x16x32_bf16 v[64:67], v[152:155], v[184:187], v[64:67]
	v_mfma_f32_16x16x32_bf16 v[116:119], v[148:151], v[164:167], v[116:119]
	v_mfma_f32_16x16x32_bf16 v[112:115], v[156:159], v[164:167], v[112:115]
	v_mfma_f32_16x16x32_bf16 v[100:103], v[148:151], v[172:175], v[100:103]
	v_mfma_f32_16x16x32_bf16 v[96:99], v[156:159], v[172:175], v[96:99]
	s_setprio 3
	s_barrier
	v_mfma_f32_16x16x32_bf16 v[84:87], v[148:151], v[180:183], v[84:87]
	v_mfma_f32_16x16x32_bf16 v[80:83], v[156:159], v[180:183], v[80:83]
	v_mfma_f32_16x16x32_bf16 v[68:71], v[148:151], v[188:191], v[68:71]
	v_mfma_f32_16x16x32_bf16 v[64:67], v[156:159], v[188:191], v[64:67]
	s_setprio 0
	s_add_i32 s67, s67, s15
	v_lshl_add_u64 v[204:205], v[204:205], 0, s[46:47]
	s_mov_b32 m0, s67
	ds_read_b128 v[160:163], v247 offset:49152
	ds_read_b128 v[164:167], v247 offset:50176
	ds_read_b128 v[168:171], v247 offset:51200
	ds_read_b128 v[172:175], v247 offset:52224
	ds_read_b128 v[176:179], v247 offset:53248
	ds_read_b128 v[180:183], v247 offset:54272
	ds_read_b128 v[184:187], v247 offset:55296
	ds_read_b128 v[188:191], v247 offset:56320
	global_load_lds_dwordx4 v[204:205], off
	s_add_i32 m0, s67, 0x2000
	s_add_u32 s68, s78, 0x40080
	v_lshl_add_u64 v[204:205], v[206:207], 0, s[46:47]
	s_addc_u32 s69, s79, 0
	s_add_i32 s67, s75, s15
	global_load_lds_dwordx4 v[204:205], off
	v_lshl_add_u64 v[204:205], s[68:69], 0, v[194:195]
	s_mov_b32 m0, s67
	s_nop 0
	global_load_lds_dwordx4 v[204:205], off
	v_lshl_add_u64 v[204:205], s[68:69], 0, v[198:199]
	s_add_i32 m0, s67, 0x2000
	s_nop 0
	global_load_lds_dwordx4 v[204:205], off
	v_lshl_add_u64 v[204:205], v[208:209], 0, s[46:47]
	s_mov_b32 m0, s21
	s_nop 0
	global_load_lds_dwordx4 v[204:205], off
	v_lshl_add_u64 v[204:205], v[210:211], 0, s[46:47]
	s_mov_b32 m0, s22
	s_nop 0
	global_load_lds_dwordx4 v[204:205], off
	s_waitcnt vmcnt(8)
	s_waitcnt lgkmcnt(0)
	s_barrier
	s_setprio 1
	v_mfma_f32_16x16x32_bf16 v[60:63], v[120:123], v[160:163], v[60:63]
	v_mfma_f32_16x16x32_bf16 v[56:59], v[128:131], v[160:163], v[56:59]
	v_mfma_f32_16x16x32_bf16 v[44:47], v[120:123], v[168:171], v[44:47]
	v_mfma_f32_16x16x32_bf16 v[40:43], v[128:131], v[168:171], v[40:43]
	v_mfma_f32_16x16x32_bf16 v[28:31], v[120:123], v[176:179], v[28:31]
	v_mfma_f32_16x16x32_bf16 v[24:27], v[128:131], v[176:179], v[24:27]
	v_mfma_f32_16x16x32_bf16 v[12:15], v[120:123], v[184:187], v[12:15]
	v_mfma_f32_16x16x32_bf16 v[8:11], v[128:131], v[184:187], v[8:11]
	v_mfma_f32_16x16x32_bf16 v[60:63], v[124:127], v[164:167], v[60:63]
	v_mfma_f32_16x16x32_bf16 v[56:59], v[132:135], v[164:167], v[56:59]
	v_mfma_f32_16x16x32_bf16 v[44:47], v[124:127], v[172:175], v[44:47]
	v_mfma_f32_16x16x32_bf16 v[40:43], v[132:135], v[172:175], v[40:43]
	v_mfma_f32_16x16x32_bf16 v[28:31], v[124:127], v[180:183], v[28:31]
	v_mfma_f32_16x16x32_bf16 v[24:27], v[132:135], v[180:183], v[24:27]
	v_mfma_f32_16x16x32_bf16 v[12:15], v[124:127], v[188:191], v[12:15]
	v_mfma_f32_16x16x32_bf16 v[8:11], v[132:135], v[188:191], v[8:11]
	v_mfma_f32_16x16x32_bf16 v[52:55], v[144:147], v[160:163], v[52:55]
	v_mfma_f32_16x16x32_bf16 v[48:51], v[152:155], v[160:163], v[48:51]
	v_mfma_f32_16x16x32_bf16 v[36:39], v[144:147], v[168:171], v[36:39]
	v_mfma_f32_16x16x32_bf16 v[32:35], v[152:155], v[168:171], v[32:35]
	v_mfma_f32_16x16x32_bf16 v[20:23], v[144:147], v[176:179], v[20:23]
	v_mfma_f32_16x16x32_bf16 v[16:19], v[152:155], v[176:179], v[16:19]
	v_mfma_f32_16x16x32_bf16 v[4:7], v[144:147], v[184:187], v[4:7]
	v_mfma_f32_16x16x32_bf16 v[0:3], v[152:155], v[184:187], v[0:3]
	v_mfma_f32_16x16x32_bf16 v[52:55], v[148:151], v[164:167], v[52:55]
	v_mfma_f32_16x16x32_bf16 v[48:51], v[156:159], v[164:167], v[48:51]
	v_mfma_f32_16x16x32_bf16 v[36:39], v[148:151], v[172:175], v[36:39]
	v_mfma_f32_16x16x32_bf16 v[32:35], v[156:159], v[172:175], v[32:35]
	s_setprio 3
	s_barrier
	v_mfma_f32_16x16x32_bf16 v[20:23], v[148:151], v[180:183], v[20:23]
	v_mfma_f32_16x16x32_bf16 v[16:19], v[156:159], v[180:183], v[16:19]
	v_mfma_f32_16x16x32_bf16 v[4:7], v[148:151], v[188:191], v[4:7]
	v_mfma_f32_16x16x32_bf16 v[0:3], v[156:159], v[188:191], v[0:3]
	s_setprio 0
	s_add_i32 s66, s66, 2
	s_add_u32 s76, s76, 0x100
	s_addc_u32 s77, s77, 0
	s_add_u32 s56, s56, 0x100
	s_addc_u32 s57, s57, 0
	s_cmp_gt_u32 s66, 13
	s_cbranch_scc0 .LBB0_2037
	s_and_b64 vcc, exec, s[48:49]
	s_cbranch_vccz .LBB0_2040
	s_barrier

.LBB0_2192:
	ds_read_b128 v[146:149], v174
	ds_read_b128 v[150:153], v174 offset:1024
	ds_read_b128 v[154:157], v174 offset:2048
	ds_read_b128 v[158:161], v174 offset:3072
	ds_read_b128 v[162:165], v175
	ds_read_b128 v[178:181], v175 offset:1024
	ds_read_b128 v[182:185], v175 offset:2048
	ds_read_b128 v[186:189], v175 offset:3072
	s_add_u32 s70, s58, 0xfffc0080
	s_addc_u32 s71, s59, -1
	s_cmp_eq_u32 s69, 12
	s_cselect_b32 s73, s47, s71
	s_cselect_b32 s72, s53, s70
	s_cselect_b32 s71, s45, s68
	s_cselect_b32 s70, s66, s67
	v_lshl_add_u64 v[166:167], s[58:59], 0, v[136:137]
	s_add_i32 m0, s17, 0xc000
	ds_read_b128 v[190:193], v176
	ds_read_b128 v[194:197], v176 offset:1024
	ds_read_b128 v[198:201], v176 offset:2048
	ds_read_b128 v[202:205], v176 offset:3072
	ds_read_b128 v[206:209], v176 offset:4096
	ds_read_b128 v[210:213], v176 offset:5120
	ds_read_b128 v[214:217], v176 offset:6144
	ds_read_b128 v[218:221], v176 offset:7168
	global_load_lds_dwordx4 v[166:167], off
	v_lshl_add_u64 v[166:167], s[58:59], 0, v[140:141]
	s_add_i32 m0, s17, 0xe000
	s_nop 0
	global_load_lds_dwordx4 v[166:167], off
	s_waitcnt vmcnt(8)
	s_waitcnt lgkmcnt(0)
	s_barrier
	s_setprio 1
	v_mfma_f32_16x16x32_bf16 v[124:127], v[146:149], v[190:193], v[124:127]
	v_mfma_f32_16x16x32_bf16 v[116:119], v[154:157], v[190:193], v[116:119]
	v_mfma_f32_16x16x32_bf16 v[108:111], v[146:149], v[198:201], v[108:111]
	v_mfma_f32_16x16x32_bf16 v[100:103], v[154:157], v[198:201], v[100:103]
	v_mfma_f32_16x16x32_bf16 v[92:95], v[146:149], v[206:209], v[92:95]
	v_mfma_f32_16x16x32_bf16 v[84:87], v[154:157], v[206:209], v[84:87]
	v_mfma_f32_16x16x32_bf16 v[76:79], v[146:149], v[214:217], v[76:79]
	v_mfma_f32_16x16x32_bf16 v[68:71], v[154:157], v[214:217], v[68:71]
	v_mfma_f32_16x16x32_bf16 v[124:127], v[150:153], v[194:197], v[124:127]
	v_mfma_f32_16x16x32_bf16 v[116:119], v[158:161], v[194:197], v[116:119]
	v_mfma_f32_16x16x32_bf16 v[108:111], v[150:153], v[202:205], v[108:111]
	v_mfma_f32_16x16x32_bf16 v[100:103], v[158:161], v[202:205], v[100:103]
	v_mfma_f32_16x16x32_bf16 v[92:95], v[150:153], v[210:213], v[92:95]
	v_mfma_f32_16x16x32_bf16 v[84:87], v[158:161], v[210:213], v[84:87]
	v_mfma_f32_16x16x32_bf16 v[76:79], v[150:153], v[218:221], v[76:79]
	v_mfma_f32_16x16x32_bf16 v[68:71], v[158:161], v[218:221], v[68:71]
	v_mfma_f32_16x16x32_bf16 v[120:123], v[162:165], v[190:193], v[120:123]
	v_mfma_f32_16x16x32_bf16 v[112:115], v[182:185], v[190:193], v[112:115]
	v_mfma_f32_16x16x32_bf16 v[104:107], v[162:165], v[198:201], v[104:107]
	v_mfma_f32_16x16x32_bf16 v[96:99], v[182:185], v[198:201], v[96:99]
	v_mfma_f32_16x16x32_bf16 v[88:91], v[162:165], v[206:209], v[88:91]
	v_mfma_f32_16x16x32_bf16 v[80:83], v[182:185], v[206:209], v[80:83]
	v_mfma_f32_16x16x32_bf16 v[72:75], v[162:165], v[214:217], v[72:75]
	v_mfma_f32_16x16x32_bf16 v[64:67], v[182:185], v[214:217], v[64:67]
	v_mfma_f32_16x16x32_bf16 v[120:123], v[178:181], v[194:197], v[120:123]
	v_mfma_f32_16x16x32_bf16 v[112:115], v[186:189], v[194:197], v[112:115]
	v_mfma_f32_16x16x32_bf16 v[104:107], v[178:181], v[202:205], v[104:107]
	v_mfma_f32_16x16x32_bf16 v[96:99], v[186:189], v[202:205], v[96:99]
	s_setprio 3
	s_barrier
	v_mfma_f32_16x16x32_bf16 v[88:91], v[178:181], v[210:213], v[88:91]
	v_mfma_f32_16x16x32_bf16 v[80:83], v[186:189], v[210:213], v[80:83]
	v_mfma_f32_16x16x32_bf16 v[72:75], v[178:181], v[218:221], v[72:75]
	v_mfma_f32_16x16x32_bf16 v[64:67], v[186:189], v[218:221], v[64:67]
	s_setprio 0
	s_add_i32 s74, s26, s16
	v_lshl_add_u64 v[166:167], s[70:71], 0, v[132:133]
	s_mov_b32 m0, s74
	ds_read_b128 v[190:193], v176 offset:16384
	ds_read_b128 v[194:197], v176 offset:17408
	ds_read_b128 v[198:201], v176 offset:18432
	ds_read_b128 v[202:205], v176 offset:19456
	ds_read_b128 v[206:209], v176 offset:20480
	ds_read_b128 v[210:213], v176 offset:21504
	ds_read_b128 v[214:217], v176 offset:22528
	ds_read_b128 v[218:221], v176 offset:23552
	global_load_lds_dwordx4 v[166:167], off
	s_add_i32 m0, s74, 0x2000
	s_add_u32 s74, s70, 0x40000
	v_lshl_add_u64 v[222:223], s[70:71], 0, v[128:129]
	s_addc_u32 s75, s71, 0
	s_add_i32 s76, s27, s16
	global_load_lds_dwordx4 v[222:223], off
	v_lshl_add_u64 v[224:225], s[74:75], 0, v[132:133]
	s_mov_b32 m0, s76
	v_lshl_add_u64 v[226:227], s[72:73], 0, v[130:131]
	global_load_lds_dwordx4 v[224:225], off
	v_lshl_add_u64 v[224:225], s[74:75], 0, v[128:129]
	s_add_i32 m0, s76, 0x2000
	s_nop 0
	global_load_lds_dwordx4 v[224:225], off
	v_lshl_add_u64 v[224:225], s[72:73], 0, v[134:135]
	s_mov_b32 m0, s17
	s_nop 0
	global_load_lds_dwordx4 v[224:225], off
	s_mov_b32 m0, s18
	s_nop 0
	global_load_lds_dwordx4 v[226:227], off
	s_waitcnt vmcnt(8)
	s_waitcnt lgkmcnt(0)
	s_barrier
	s_setprio 1
	v_mfma_f32_16x16x32_bf16 v[60:63], v[146:149], v[190:193], v[60:63]
	v_mfma_f32_16x16x32_bf16 v[52:55], v[154:157], v[190:193], v[52:55]
	v_mfma_f32_16x16x32_bf16 v[44:47], v[146:149], v[198:201], v[44:47]
	v_mfma_f32_16x16x32_bf16 v[36:39], v[154:157], v[198:201], v[36:39]
	v_mfma_f32_16x16x32_bf16 v[28:31], v[146:149], v[206:209], v[28:31]
	v_mfma_f32_16x16x32_bf16 v[20:23], v[154:157], v[206:209], v[20:23]
	v_mfma_f32_16x16x32_bf16 v[12:15], v[146:149], v[214:217], v[12:15]
	v_mfma_f32_16x16x32_bf16 v[4:7], v[154:157], v[214:217], v[4:7]
	v_mfma_f32_16x16x32_bf16 v[60:63], v[150:153], v[194:197], v[60:63]
	v_mfma_f32_16x16x32_bf16 v[52:55], v[158:161], v[194:197], v[52:55]
	v_mfma_f32_16x16x32_bf16 v[44:47], v[150:153], v[202:205], v[44:47]
	v_mfma_f32_16x16x32_bf16 v[36:39], v[158:161], v[202:205], v[36:39]
	v_mfma_f32_16x16x32_bf16 v[28:31], v[150:153], v[210:213], v[28:31]
	v_mfma_f32_16x16x32_bf16 v[20:23], v[158:161], v[210:213], v[20:23]
	v_mfma_f32_16x16x32_bf16 v[12:15], v[150:153], v[218:221], v[12:15]
	v_mfma_f32_16x16x32_bf16 v[4:7], v[158:161], v[218:221], v[4:7]
	v_mfma_f32_16x16x32_bf16 v[56:59], v[162:165], v[190:193], v[56:59]
	v_mfma_f32_16x16x32_bf16 v[48:51], v[182:185], v[190:193], v[48:51]
	v_mfma_f32_16x16x32_bf16 v[40:43], v[162:165], v[198:201], v[40:43]
	v_mfma_f32_16x16x32_bf16 v[32:35], v[182:185], v[198:201], v[32:35]
	v_mfma_f32_16x16x32_bf16 v[24:27], v[162:165], v[206:209], v[24:27]
	v_mfma_f32_16x16x32_bf16 v[16:19], v[182:185], v[206:209], v[16:19]
	v_mfma_f32_16x16x32_bf16 v[8:11], v[162:165], v[214:217], v[8:11]
	v_mfma_f32_16x16x32_bf16 v[0:3], v[182:185], v[214:217], v[0:3]
	v_mfma_f32_16x16x32_bf16 v[56:59], v[178:181], v[194:197], v[56:59]
	v_mfma_f32_16x16x32_bf16 v[48:51], v[186:189], v[194:197], v[48:51]
	v_mfma_f32_16x16x32_bf16 v[40:43], v[178:181], v[202:205], v[40:43]
	v_mfma_f32_16x16x32_bf16 v[32:35], v[186:189], v[202:205], v[32:35]
	s_setprio 3
	s_barrier
	v_mfma_f32_16x16x32_bf16 v[24:27], v[178:181], v[210:213], v[24:27]
	v_mfma_f32_16x16x32_bf16 v[16:19], v[186:189], v[210:213], v[16:19]
	v_mfma_f32_16x16x32_bf16 v[8:11], v[178:181], v[218:221], v[8:11]
	v_mfma_f32_16x16x32_bf16 v[0:3], v[186:189], v[218:221], v[0:3]
	s_setprio 0
	s_add_i32 s74, 0, 0x18000
	s_add_i32 s75, 0, 0x1c000
	v_add_u32_e32 v158, s74, v171
	v_add_u32_e32 v186, s75, v171
	ds_read_b128 v[146:149], v158
	ds_read_b128 v[150:153], v158 offset:1024
	ds_read_b128 v[154:157], v158 offset:2048
	ds_read_b128 v[158:161], v158 offset:3072
	ds_read_b128 v[162:165], v186
	ds_read_b128 v[178:181], v186 offset:1024
	ds_read_b128 v[182:185], v186 offset:2048
	ds_read_b128 v[186:189], v186 offset:3072
	s_add_u32 s72, s72, 0x40000
	s_addc_u32 s73, s73, 0
	s_mov_b32 m0, s19
	v_lshl_add_u64 v[228:229], s[72:73], 0, v[134:135]
	ds_read_b128 v[190:193], v176 offset:32768
	ds_read_b128 v[194:197], v176 offset:33792
	ds_read_b128 v[198:201], v176 offset:34816
	ds_read_b128 v[202:205], v176 offset:35840
	ds_read_b128 v[206:209], v176 offset:36864
	ds_read_b128 v[210:213], v176 offset:37888
	ds_read_b128 v[214:217], v176 offset:38912
	ds_read_b128 v[218:221], v176 offset:39936
	global_load_lds_dwordx4 v[228:229], off
	v_lshl_add_u64 v[228:229], s[72:73], 0, v[130:131]
	s_mov_b32 m0, s20
	s_nop 0
	global_load_lds_dwordx4 v[228:229], off
	s_waitcnt vmcnt(8)
	s_waitcnt lgkmcnt(0)
	s_barrier
	s_setprio 1
	v_mfma_f32_16x16x32_bf16 v[124:127], v[146:149], v[190:193], v[124:127]
	v_mfma_f32_16x16x32_bf16 v[116:119], v[154:157], v[190:193], v[116:119]
	v_mfma_f32_16x16x32_bf16 v[108:111], v[146:149], v[198:201], v[108:111]
	v_mfma_f32_16x16x32_bf16 v[100:103], v[154:157], v[198:201], v[100:103]
	v_mfma_f32_16x16x32_bf16 v[92:95], v[146:149], v[206:209], v[92:95]
	v_mfma_f32_16x16x32_bf16 v[84:87], v[154:157], v[206:209], v[84:87]
	v_mfma_f32_16x16x32_bf16 v[76:79], v[146:149], v[214:217], v[76:79]
	v_mfma_f32_16x16x32_bf16 v[68:71], v[154:157], v[214:217], v[68:71]
	v_mfma_f32_16x16x32_bf16 v[124:127], v[150:153], v[194:197], v[124:127]
	v_mfma_f32_16x16x32_bf16 v[116:119], v[158:161], v[194:197], v[116:119]
	v_mfma_f32_16x16x32_bf16 v[108:111], v[150:153], v[202:205], v[108:111]
	v_mfma_f32_16x16x32_bf16 v[100:103], v[158:161], v[202:205], v[100:103]
	v_mfma_f32_16x16x32_bf16 v[92:95], v[150:153], v[210:213], v[92:95]
	v_mfma_f32_16x16x32_bf16 v[84:87], v[158:161], v[210:213], v[84:87]
	v_mfma_f32_16x16x32_bf16 v[76:79], v[150:153], v[218:221], v[76:79]
	v_mfma_f32_16x16x32_bf16 v[68:71], v[158:161], v[218:221], v[68:71]
	v_mfma_f32_16x16x32_bf16 v[120:123], v[162:165], v[190:193], v[120:123]
	v_mfma_f32_16x16x32_bf16 v[112:115], v[182:185], v[190:193], v[112:115]
	v_mfma_f32_16x16x32_bf16 v[104:107], v[162:165], v[198:201], v[104:107]
	v_mfma_f32_16x16x32_bf16 v[96:99], v[182:185], v[198:201], v[96:99]
	v_mfma_f32_16x16x32_bf16 v[88:91], v[162:165], v[206:209], v[88:91]
	v_mfma_f32_16x16x32_bf16 v[80:83], v[182:185], v[206:209], v[80:83]
	v_mfma_f32_16x16x32_bf16 v[72:75], v[162:165], v[214:217], v[72:75]
	v_mfma_f32_16x16x32_bf16 v[64:67], v[182:185], v[214:217], v[64:67]
	v_mfma_f32_16x16x32_bf16 v[120:123], v[178:181], v[194:197], v[120:123]
	v_mfma_f32_16x16x32_bf16 v[112:115], v[186:189], v[194:197], v[112:115]
	v_mfma_f32_16x16x32_bf16 v[104:107], v[178:181], v[202:205], v[104:107]
	v_mfma_f32_16x16x32_bf16 v[96:99], v[186:189], v[202:205], v[96:99]
	s_setprio 3
	s_barrier
	v_mfma_f32_16x16x32_bf16 v[88:91], v[178:181], v[210:213], v[88:91]
	v_mfma_f32_16x16x32_bf16 v[80:83], v[186:189], v[210:213], v[80:83]
	v_mfma_f32_16x16x32_bf16 v[72:75], v[178:181], v[218:221], v[72:75]
	v_mfma_f32_16x16x32_bf16 v[64:67], v[186:189], v[218:221], v[64:67]
	s_setprio 0
	s_add_i32 s72, s74, s16
	v_lshl_add_u64 v[166:167], v[166:167], 0, s[10:11]
	s_mov_b32 m0, s72
	ds_read_b128 v[190:193], v176 offset:49152
	ds_read_b128 v[194:197], v176 offset:50176
	ds_read_b128 v[198:201], v176 offset:51200
	ds_read_b128 v[202:205], v176 offset:52224
	ds_read_b128 v[206:209], v176 offset:53248
	ds_read_b128 v[210:213], v176 offset:54272
	ds_read_b128 v[214:217], v176 offset:55296
	ds_read_b128 v[218:221], v176 offset:56320
	global_load_lds_dwordx4 v[166:167], off
	s_add_i32 m0, s72, 0x2000
	s_add_u32 s70, s70, 0x40080
	v_lshl_add_u64 v[166:167], v[222:223], 0, s[10:11]
	s_addc_u32 s71, s71, 0
	s_add_i32 s72, s75, s16
	global_load_lds_dwordx4 v[166:167], off
	v_lshl_add_u64 v[166:167], s[70:71], 0, v[132:133]
	s_mov_b32 m0, s72
	s_nop 0
	global_load_lds_dwordx4 v[166:167], off
	v_lshl_add_u64 v[166:167], s[70:71], 0, v[128:129]
	s_add_i32 m0, s72, 0x2000
	s_nop 0
	global_load_lds_dwordx4 v[166:167], off
	v_lshl_add_u64 v[166:167], v[224:225], 0, s[10:11]
	s_mov_b32 m0, s23
	s_nop 0
	global_load_lds_dwordx4 v[166:167], off
	v_lshl_add_u64 v[166:167], v[226:227], 0, s[10:11]
	s_mov_b32 m0, s24
	s_nop 0
	global_load_lds_dwordx4 v[166:167], off
	s_waitcnt vmcnt(8)
	s_waitcnt lgkmcnt(0)
	s_barrier
	s_setprio 1
	v_mfma_f32_16x16x32_bf16 v[60:63], v[146:149], v[190:193], v[60:63]
	v_mfma_f32_16x16x32_bf16 v[52:55], v[154:157], v[190:193], v[52:55]
	v_mfma_f32_16x16x32_bf16 v[44:47], v[146:149], v[198:201], v[44:47]
	v_mfma_f32_16x16x32_bf16 v[36:39], v[154:157], v[198:201], v[36:39]
	v_mfma_f32_16x16x32_bf16 v[28:31], v[146:149], v[206:209], v[28:31]
	v_mfma_f32_16x16x32_bf16 v[20:23], v[154:157], v[206:209], v[20:23]
	v_mfma_f32_16x16x32_bf16 v[12:15], v[146:149], v[214:217], v[12:15]
	v_mfma_f32_16x16x32_bf16 v[4:7], v[154:157], v[214:217], v[4:7]
	v_mfma_f32_16x16x32_bf16 v[60:63], v[150:153], v[194:197], v[60:63]
	v_mfma_f32_16x16x32_bf16 v[52:55], v[158:161], v[194:197], v[52:55]
	v_mfma_f32_16x16x32_bf16 v[44:47], v[150:153], v[202:205], v[44:47]
	v_mfma_f32_16x16x32_bf16 v[36:39], v[158:161], v[202:205], v[36:39]
	v_mfma_f32_16x16x32_bf16 v[28:31], v[150:153], v[210:213], v[28:31]
	v_mfma_f32_16x16x32_bf16 v[20:23], v[158:161], v[210:213], v[20:23]
	v_mfma_f32_16x16x32_bf16 v[12:15], v[150:153], v[218:221], v[12:15]
	v_mfma_f32_16x16x32_bf16 v[4:7], v[158:161], v[218:221], v[4:7]
	v_mfma_f32_16x16x32_bf16 v[56:59], v[162:165], v[190:193], v[56:59]
	v_mfma_f32_16x16x32_bf16 v[48:51], v[182:185], v[190:193], v[48:51]
	v_mfma_f32_16x16x32_bf16 v[40:43], v[162:165], v[198:201], v[40:43]
	v_mfma_f32_16x16x32_bf16 v[32:35], v[182:185], v[198:201], v[32:35]
	v_mfma_f32_16x16x32_bf16 v[24:27], v[162:165], v[206:209], v[24:27]
	v_mfma_f32_16x16x32_bf16 v[16:19], v[182:185], v[206:209], v[16:19]
	v_mfma_f32_16x16x32_bf16 v[8:11], v[162:165], v[214:217], v[8:11]
	v_mfma_f32_16x16x32_bf16 v[0:3], v[182:185], v[214:217], v[0:3]
	v_mfma_f32_16x16x32_bf16 v[56:59], v[178:181], v[194:197], v[56:59]
	v_mfma_f32_16x16x32_bf16 v[48:51], v[186:189], v[194:197], v[48:51]
	v_mfma_f32_16x16x32_bf16 v[40:43], v[178:181], v[202:205], v[40:43]
	v_mfma_f32_16x16x32_bf16 v[32:35], v[186:189], v[202:205], v[32:35]
	s_setprio 3
	s_barrier
	v_mfma_f32_16x16x32_bf16 v[24:27], v[178:181], v[210:213], v[24:27]
	v_mfma_f32_16x16x32_bf16 v[16:19], v[186:189], v[210:213], v[16:19]
	v_mfma_f32_16x16x32_bf16 v[8:11], v[178:181], v[218:221], v[8:11]
	v_mfma_f32_16x16x32_bf16 v[0:3], v[186:189], v[218:221], v[0:3]
	s_setprio 0
	s_add_i32 s69, s69, 2
	s_add_u32 s58, s58, 0x100
	s_addc_u32 s59, s59, 0
	s_add_u32 s67, s67, 0x100
	s_addc_u32 s68, s68, 0
	s_cmp_gt_u32 s69, 13
	s_cbranch_scc0 .LBB0_2192
	s_and_b64 vcc, exec, s[42:43]
	s_cbranch_vccz .LBB0_2195
	s_barrier

.LBB0_2341:
	ds_read_b128 v[128:131], v197
	ds_read_b128 v[132:135], v197 offset:1024
	ds_read_b128 v[136:139], v197 offset:2048
	ds_read_b128 v[140:143], v197 offset:3072
	ds_read_b128 v[144:147], v198
	ds_read_b128 v[148:151], v198 offset:1024
	ds_read_b128 v[152:155], v198 offset:2048
	ds_read_b128 v[156:159], v198 offset:3072
	s_add_u32 s18, s16, 0xfff50080
	s_addc_u32 s19, s17, -1
	s_cmp_eq_u32 s45, 40
	s_cselect_b32 s21, s5, s19
	s_cselect_b32 s20, s4, s18
	s_cselect_b32 s19, s15, s44
	s_cselect_b32 s18, s14, s43
	v_lshl_add_u64 v[192:193], s[16:17], 0, v[172:173]
	s_add_i32 m0, s25, 0xc000
	ds_read_b128 v[160:163], v199
	ds_read_b128 v[180:183], v199 offset:1024
	ds_read_b128 v[184:187], v199 offset:2048
	ds_read_b128 v[188:191], v199 offset:3072
	ds_read_b128 v[200:203], v199 offset:4096
	ds_read_b128 v[204:207], v199 offset:5120
	ds_read_b128 v[208:211], v199 offset:6144
	ds_read_b128 v[212:215], v199 offset:7168
	global_load_lds_dwordx4 v[192:193], off
	v_lshl_add_u64 v[192:193], s[16:17], 0, v[174:175]
	s_add_i32 m0, s25, 0xe000
	s_nop 0
	global_load_lds_dwordx4 v[192:193], off
	s_waitcnt vmcnt(8)
	s_waitcnt lgkmcnt(0)
	s_barrier
	s_setprio 1
	v_mfma_f32_16x16x32_bf16 v[124:127], v[128:131], v[160:163], v[124:127]
	v_mfma_f32_16x16x32_bf16 v[120:123], v[136:139], v[160:163], v[120:123]
	v_mfma_f32_16x16x32_bf16 v[108:111], v[128:131], v[184:187], v[108:111]
	v_mfma_f32_16x16x32_bf16 v[104:107], v[136:139], v[184:187], v[104:107]
	v_mfma_f32_16x16x32_bf16 v[96:99], v[128:131], v[200:203], v[96:99]
	v_mfma_f32_16x16x32_bf16 v[88:91], v[136:139], v[200:203], v[88:91]
	v_mfma_f32_16x16x32_bf16 v[80:83], v[128:131], v[208:211], v[80:83]
	v_mfma_f32_16x16x32_bf16 v[72:75], v[136:139], v[208:211], v[72:75]
	v_mfma_f32_16x16x32_bf16 v[124:127], v[132:135], v[180:183], v[124:127]
	v_mfma_f32_16x16x32_bf16 v[120:123], v[140:143], v[180:183], v[120:123]
	v_mfma_f32_16x16x32_bf16 v[108:111], v[132:135], v[188:191], v[108:111]
	v_mfma_f32_16x16x32_bf16 v[104:107], v[140:143], v[188:191], v[104:107]
	v_mfma_f32_16x16x32_bf16 v[96:99], v[132:135], v[204:207], v[96:99]
	v_mfma_f32_16x16x32_bf16 v[88:91], v[140:143], v[204:207], v[88:91]
	v_mfma_f32_16x16x32_bf16 v[80:83], v[132:135], v[212:215], v[80:83]
	v_mfma_f32_16x16x32_bf16 v[72:75], v[140:143], v[212:215], v[72:75]
	v_mfma_f32_16x16x32_bf16 v[116:119], v[144:147], v[160:163], v[116:119]
	v_mfma_f32_16x16x32_bf16 v[112:115], v[152:155], v[160:163], v[112:115]
	v_mfma_f32_16x16x32_bf16 v[100:103], v[144:147], v[184:187], v[100:103]
	v_mfma_f32_16x16x32_bf16 v[92:95], v[152:155], v[184:187], v[92:95]
	v_mfma_f32_16x16x32_bf16 v[84:87], v[144:147], v[200:203], v[84:87]
	v_mfma_f32_16x16x32_bf16 v[76:79], v[152:155], v[200:203], v[76:79]
	v_mfma_f32_16x16x32_bf16 v[68:71], v[144:147], v[208:211], v[68:71]
	v_mfma_f32_16x16x32_bf16 v[64:67], v[152:155], v[208:211], v[64:67]
	v_mfma_f32_16x16x32_bf16 v[116:119], v[148:151], v[180:183], v[116:119]
	v_mfma_f32_16x16x32_bf16 v[112:115], v[156:159], v[180:183], v[112:115]
	v_mfma_f32_16x16x32_bf16 v[100:103], v[148:151], v[188:191], v[100:103]
	v_mfma_f32_16x16x32_bf16 v[92:95], v[156:159], v[188:191], v[92:95]
	s_setprio 3
	s_barrier
	v_mfma_f32_16x16x32_bf16 v[84:87], v[148:151], v[204:207], v[84:87]
	v_mfma_f32_16x16x32_bf16 v[76:79], v[156:159], v[204:207], v[76:79]
	v_mfma_f32_16x16x32_bf16 v[68:71], v[148:151], v[212:215], v[68:71]
	v_mfma_f32_16x16x32_bf16 v[64:67], v[156:159], v[212:215], v[64:67]
	s_setprio 0
	s_add_i32 s46, s37, s24
	v_lshl_add_u64 v[192:193], s[18:19], 0, v[166:167]
	s_mov_b32 m0, s46
	ds_read_b128 v[160:163], v199 offset:16384
	ds_read_b128 v[180:183], v199 offset:17408
	ds_read_b128 v[184:187], v199 offset:18432
	ds_read_b128 v[188:191], v199 offset:19456
	ds_read_b128 v[200:203], v199 offset:20480
	ds_read_b128 v[204:207], v199 offset:21504
	ds_read_b128 v[208:211], v199 offset:22528
	ds_read_b128 v[212:215], v199 offset:23552
	global_load_lds_dwordx4 v[192:193], off
	s_add_i32 m0, s46, 0x2000
	s_add_u32 s46, s18, 0xb0000
	v_lshl_add_u64 v[216:217], s[18:19], 0, v[170:171]
	s_addc_u32 s47, s19, 0
	s_add_i32 s48, s38, s24
	global_load_lds_dwordx4 v[216:217], off
	v_lshl_add_u64 v[218:219], s[46:47], 0, v[166:167]
	s_mov_b32 m0, s48
	v_lshl_add_u64 v[220:221], s[20:21], 0, v[168:169]
	global_load_lds_dwordx4 v[218:219], off
	v_lshl_add_u64 v[218:219], s[46:47], 0, v[170:171]
	s_add_i32 m0, s48, 0x2000
	s_nop 0
	global_load_lds_dwordx4 v[218:219], off
	v_lshl_add_u64 v[218:219], s[20:21], 0, v[164:165]
	s_mov_b32 m0, s25
	s_nop 0
	global_load_lds_dwordx4 v[218:219], off
	s_mov_b32 m0, s26
	s_nop 0
	global_load_lds_dwordx4 v[220:221], off
	s_waitcnt vmcnt(8)
	s_waitcnt lgkmcnt(0)
	s_barrier
	s_setprio 1
	v_mfma_f32_16x16x32_bf16 v[60:63], v[128:131], v[160:163], v[60:63]
	v_mfma_f32_16x16x32_bf16 v[56:59], v[136:139], v[160:163], v[56:59]
	v_mfma_f32_16x16x32_bf16 v[48:51], v[128:131], v[184:187], v[48:51]
	v_mfma_f32_16x16x32_bf16 v[40:43], v[136:139], v[184:187], v[40:43]
	v_mfma_f32_16x16x32_bf16 v[32:35], v[128:131], v[200:203], v[32:35]
	v_mfma_f32_16x16x32_bf16 v[24:27], v[136:139], v[200:203], v[24:27]
	v_mfma_f32_16x16x32_bf16 v[16:19], v[128:131], v[208:211], v[16:19]
	v_mfma_f32_16x16x32_bf16 v[8:11], v[136:139], v[208:211], v[8:11]
	v_mfma_f32_16x16x32_bf16 v[60:63], v[132:135], v[180:183], v[60:63]
	v_mfma_f32_16x16x32_bf16 v[56:59], v[140:143], v[180:183], v[56:59]
	v_mfma_f32_16x16x32_bf16 v[48:51], v[132:135], v[188:191], v[48:51]
	v_mfma_f32_16x16x32_bf16 v[40:43], v[140:143], v[188:191], v[40:43]
	v_mfma_f32_16x16x32_bf16 v[32:35], v[132:135], v[204:207], v[32:35]
	v_mfma_f32_16x16x32_bf16 v[24:27], v[140:143], v[204:207], v[24:27]
	v_mfma_f32_16x16x32_bf16 v[16:19], v[132:135], v[212:215], v[16:19]
	v_mfma_f32_16x16x32_bf16 v[8:11], v[140:143], v[212:215], v[8:11]
	v_mfma_f32_16x16x32_bf16 v[52:55], v[144:147], v[160:163], v[52:55]
	v_mfma_f32_16x16x32_bf16 v[44:47], v[152:155], v[160:163], v[44:47]
	v_mfma_f32_16x16x32_bf16 v[36:39], v[144:147], v[184:187], v[36:39]
	v_mfma_f32_16x16x32_bf16 v[28:31], v[152:155], v[184:187], v[28:31]
	v_mfma_f32_16x16x32_bf16 v[20:23], v[144:147], v[200:203], v[20:23]
	v_mfma_f32_16x16x32_bf16 v[12:15], v[152:155], v[200:203], v[12:15]
	v_mfma_f32_16x16x32_bf16 v[4:7], v[144:147], v[208:211], v[4:7]
	v_mfma_f32_16x16x32_bf16 v[0:3], v[152:155], v[208:211], v[0:3]
	v_mfma_f32_16x16x32_bf16 v[52:55], v[148:151], v[180:183], v[52:55]
	v_mfma_f32_16x16x32_bf16 v[44:47], v[156:159], v[180:183], v[44:47]
	v_mfma_f32_16x16x32_bf16 v[36:39], v[148:151], v[188:191], v[36:39]
	v_mfma_f32_16x16x32_bf16 v[28:31], v[156:159], v[188:191], v[28:31]
	s_setprio 3
	s_barrier
	v_mfma_f32_16x16x32_bf16 v[20:23], v[148:151], v[204:207], v[20:23]
	v_mfma_f32_16x16x32_bf16 v[12:15], v[156:159], v[204:207], v[12:15]
	v_mfma_f32_16x16x32_bf16 v[4:7], v[148:151], v[212:215], v[4:7]
	v_mfma_f32_16x16x32_bf16 v[0:3], v[156:159], v[212:215], v[0:3]
	s_setprio 0
	s_add_i32 s46, 0, 0x18000
	s_add_i32 s47, 0, 0x1c000
	v_add_u32_e32 v140, s46, v195
	v_add_u32_e32 v156, s47, v195
	ds_read_b128 v[128:131], v140
	ds_read_b128 v[132:135], v140 offset:1024
	ds_read_b128 v[136:139], v140 offset:2048
	ds_read_b128 v[140:143], v140 offset:3072
	ds_read_b128 v[144:147], v156
	ds_read_b128 v[148:151], v156 offset:1024
	ds_read_b128 v[152:155], v156 offset:2048
	ds_read_b128 v[156:159], v156 offset:3072
	s_add_u32 s20, s20, 0xb0000
	s_addc_u32 s21, s21, 0
	s_mov_b32 m0, s27
	v_lshl_add_u64 v[222:223], s[20:21], 0, v[164:165]
	ds_read_b128 v[160:163], v199 offset:32768
	ds_read_b128 v[180:183], v199 offset:33792
	ds_read_b128 v[184:187], v199 offset:34816
	ds_read_b128 v[188:191], v199 offset:35840
	ds_read_b128 v[200:203], v199 offset:36864
	ds_read_b128 v[204:207], v199 offset:37888
	ds_read_b128 v[208:211], v199 offset:38912
	ds_read_b128 v[212:215], v199 offset:39936
	global_load_lds_dwordx4 v[222:223], off
	v_lshl_add_u64 v[222:223], s[20:21], 0, v[168:169]
	s_mov_b32 m0, s28
	s_nop 0
	global_load_lds_dwordx4 v[222:223], off
	s_waitcnt vmcnt(8)
	s_waitcnt lgkmcnt(0)
	s_barrier
	s_setprio 1
	v_mfma_f32_16x16x32_bf16 v[124:127], v[128:131], v[160:163], v[124:127]
	v_mfma_f32_16x16x32_bf16 v[120:123], v[136:139], v[160:163], v[120:123]
	v_mfma_f32_16x16x32_bf16 v[108:111], v[128:131], v[184:187], v[108:111]
	v_mfma_f32_16x16x32_bf16 v[104:107], v[136:139], v[184:187], v[104:107]
	v_mfma_f32_16x16x32_bf16 v[96:99], v[128:131], v[200:203], v[96:99]
	v_mfma_f32_16x16x32_bf16 v[88:91], v[136:139], v[200:203], v[88:91]
	v_mfma_f32_16x16x32_bf16 v[80:83], v[128:131], v[208:211], v[80:83]
	v_mfma_f32_16x16x32_bf16 v[72:75], v[136:139], v[208:211], v[72:75]
	v_mfma_f32_16x16x32_bf16 v[124:127], v[132:135], v[180:183], v[124:127]
	v_mfma_f32_16x16x32_bf16 v[120:123], v[140:143], v[180:183], v[120:123]
	v_mfma_f32_16x16x32_bf16 v[108:111], v[132:135], v[188:191], v[108:111]
	v_mfma_f32_16x16x32_bf16 v[104:107], v[140:143], v[188:191], v[104:107]
	v_mfma_f32_16x16x32_bf16 v[96:99], v[132:135], v[204:207], v[96:99]
	v_mfma_f32_16x16x32_bf16 v[88:91], v[140:143], v[204:207], v[88:91]
	v_mfma_f32_16x16x32_bf16 v[80:83], v[132:135], v[212:215], v[80:83]
	v_mfma_f32_16x16x32_bf16 v[72:75], v[140:143], v[212:215], v[72:75]
	v_mfma_f32_16x16x32_bf16 v[116:119], v[144:147], v[160:163], v[116:119]
	v_mfma_f32_16x16x32_bf16 v[112:115], v[152:155], v[160:163], v[112:115]
	v_mfma_f32_16x16x32_bf16 v[100:103], v[144:147], v[184:187], v[100:103]
	v_mfma_f32_16x16x32_bf16 v[92:95], v[152:155], v[184:187], v[92:95]
	v_mfma_f32_16x16x32_bf16 v[84:87], v[144:147], v[200:203], v[84:87]
	v_mfma_f32_16x16x32_bf16 v[76:79], v[152:155], v[200:203], v[76:79]
	v_mfma_f32_16x16x32_bf16 v[68:71], v[144:147], v[208:211], v[68:71]
	v_mfma_f32_16x16x32_bf16 v[64:67], v[152:155], v[208:211], v[64:67]
	v_mfma_f32_16x16x32_bf16 v[116:119], v[148:151], v[180:183], v[116:119]
	v_mfma_f32_16x16x32_bf16 v[112:115], v[156:159], v[180:183], v[112:115]
	v_mfma_f32_16x16x32_bf16 v[100:103], v[148:151], v[188:191], v[100:103]
	v_mfma_f32_16x16x32_bf16 v[92:95], v[156:159], v[188:191], v[92:95]
	s_setprio 3
	s_barrier
	v_mfma_f32_16x16x32_bf16 v[84:87], v[148:151], v[204:207], v[84:87]
	v_mfma_f32_16x16x32_bf16 v[76:79], v[156:159], v[204:207], v[76:79]
	v_mfma_f32_16x16x32_bf16 v[68:71], v[148:151], v[212:215], v[68:71]
	v_mfma_f32_16x16x32_bf16 v[64:67], v[156:159], v[212:215], v[64:67]
	s_setprio 0
	s_add_i32 s20, s46, s24
	v_lshl_add_u64 v[192:193], v[192:193], 0, s[8:9]
	s_mov_b32 m0, s20
	ds_read_b128 v[160:163], v199 offset:49152
	ds_read_b128 v[180:183], v199 offset:50176
	ds_read_b128 v[184:187], v199 offset:51200
	ds_read_b128 v[188:191], v199 offset:52224
	ds_read_b128 v[200:203], v199 offset:53248
	ds_read_b128 v[204:207], v199 offset:54272
	ds_read_b128 v[208:211], v199 offset:55296
	ds_read_b128 v[212:215], v199 offset:56320
	global_load_lds_dwordx4 v[192:193], off
	s_add_i32 m0, s20, 0x2000
	s_add_u32 s18, s18, 0xb0080
	v_lshl_add_u64 v[192:193], v[216:217], 0, s[8:9]
	s_addc_u32 s19, s19, 0
	s_add_i32 s20, s47, s24
	global_load_lds_dwordx4 v[192:193], off
	v_lshl_add_u64 v[192:193], s[18:19], 0, v[166:167]
	s_mov_b32 m0, s20
	s_nop 0
	global_load_lds_dwordx4 v[192:193], off
	v_lshl_add_u64 v[192:193], s[18:19], 0, v[170:171]
	s_add_i32 m0, s20, 0x2000
	s_nop 0
	global_load_lds_dwordx4 v[192:193], off
	v_lshl_add_u64 v[192:193], v[218:219], 0, s[8:9]
	s_mov_b32 m0, s33
	s_nop 0
	global_load_lds_dwordx4 v[192:193], off
	v_lshl_add_u64 v[192:193], v[220:221], 0, s[8:9]
	s_mov_b32 m0, s35
	s_nop 0
	global_load_lds_dwordx4 v[192:193], off
	s_waitcnt vmcnt(8)
	s_waitcnt lgkmcnt(0)
	s_barrier
	s_setprio 1
	v_mfma_f32_16x16x32_bf16 v[60:63], v[128:131], v[160:163], v[60:63]
	v_mfma_f32_16x16x32_bf16 v[56:59], v[136:139], v[160:163], v[56:59]
	v_mfma_f32_16x16x32_bf16 v[48:51], v[128:131], v[184:187], v[48:51]
	v_mfma_f32_16x16x32_bf16 v[40:43], v[136:139], v[184:187], v[40:43]
	v_mfma_f32_16x16x32_bf16 v[32:35], v[128:131], v[200:203], v[32:35]
	v_mfma_f32_16x16x32_bf16 v[24:27], v[136:139], v[200:203], v[24:27]
	v_mfma_f32_16x16x32_bf16 v[16:19], v[128:131], v[208:211], v[16:19]
	v_mfma_f32_16x16x32_bf16 v[8:11], v[136:139], v[208:211], v[8:11]
	v_mfma_f32_16x16x32_bf16 v[60:63], v[132:135], v[180:183], v[60:63]
	v_mfma_f32_16x16x32_bf16 v[56:59], v[140:143], v[180:183], v[56:59]
	v_mfma_f32_16x16x32_bf16 v[48:51], v[132:135], v[188:191], v[48:51]
	v_mfma_f32_16x16x32_bf16 v[40:43], v[140:143], v[188:191], v[40:43]
	v_mfma_f32_16x16x32_bf16 v[32:35], v[132:135], v[204:207], v[32:35]
	v_mfma_f32_16x16x32_bf16 v[24:27], v[140:143], v[204:207], v[24:27]
	v_mfma_f32_16x16x32_bf16 v[16:19], v[132:135], v[212:215], v[16:19]
	v_mfma_f32_16x16x32_bf16 v[8:11], v[140:143], v[212:215], v[8:11]
	v_mfma_f32_16x16x32_bf16 v[52:55], v[144:147], v[160:163], v[52:55]
	v_mfma_f32_16x16x32_bf16 v[44:47], v[152:155], v[160:163], v[44:47]
	v_mfma_f32_16x16x32_bf16 v[36:39], v[144:147], v[184:187], v[36:39]
	v_mfma_f32_16x16x32_bf16 v[28:31], v[152:155], v[184:187], v[28:31]
	v_mfma_f32_16x16x32_bf16 v[20:23], v[144:147], v[200:203], v[20:23]
	v_mfma_f32_16x16x32_bf16 v[12:15], v[152:155], v[200:203], v[12:15]
	v_mfma_f32_16x16x32_bf16 v[4:7], v[144:147], v[208:211], v[4:7]
	v_mfma_f32_16x16x32_bf16 v[0:3], v[152:155], v[208:211], v[0:3]
	v_mfma_f32_16x16x32_bf16 v[52:55], v[148:151], v[180:183], v[52:55]
	v_mfma_f32_16x16x32_bf16 v[44:47], v[156:159], v[180:183], v[44:47]
	v_mfma_f32_16x16x32_bf16 v[36:39], v[148:151], v[188:191], v[36:39]
	v_mfma_f32_16x16x32_bf16 v[28:31], v[156:159], v[188:191], v[28:31]
	s_setprio 3
	s_barrier
	v_mfma_f32_16x16x32_bf16 v[20:23], v[148:151], v[204:207], v[20:23]
	v_mfma_f32_16x16x32_bf16 v[12:15], v[156:159], v[204:207], v[12:15]
	v_mfma_f32_16x16x32_bf16 v[4:7], v[148:151], v[212:215], v[4:7]
	v_mfma_f32_16x16x32_bf16 v[0:3], v[156:159], v[212:215], v[0:3]
	s_setprio 0
	s_add_i32 s45, s45, 2
	s_add_u32 s16, s16, 0x100
	s_addc_u32 s17, s17, 0
	s_add_u32 s43, s43, 0x100
	s_addc_u32 s44, s44, 0
	s_cmp_gt_u32 s45, 41
	s_cbranch_scc0 .LBB0_2341
	s_and_b64 vcc, exec, s[10:11]
	s_cbranch_vccz .LBB0_2344
	s_barrier
